# triangular inverse v2: rows' scaled bf16 copies written to LDS as they become final (packed mul + one convert), solver's step-4 operand loads issued mid-solve
# baseline (speedup 1.0000x reference)
; #define PG8_LAS __attribute__((address_space(3)))
; __device__ __forceinline__ bf16_t f2bf(float x) { return (bf16_t)(pk2(x, x) & 0xffffu); }
; __device__ __forceinline__ void solve64(float (&x)[64], const PG8_LAS float* sLt) {
;     ...
;     for (int j = 0; j < 63; ++j) {
;         const float xj = x[j];
; #pragma unroll
;         for (int i4 = (j + 1) / 4; i4 < 16; ++i4) {
;             if (4 * i4 + 0 > j) x[4 * i4 + 0] -= cur[i4][0] * xj;
;             if (4 * i4 + 1 > j) x[4 * i4 + 1] -= cur[i4][1] * xj;
;             if (4 * i4 + 2 > j) x[4 * i4 + 2] -= cur[i4][2] * xj;
;             if (4 * i4 + 3 > j) x[4 * i4 + 3] -= cur[i4][3] * xj;
;             if (j + 1 < 63 && i4 >= (j + 2) / 4) cur[i4] = *(const PG8_LAS f32x4*)(sLt + (j + 1) * 64 + 4 * i4); }
; __device__ __forceinline__ void phase_prep(const Args& a, PG8_LAS unsigned char* lds) {
;     ...
;             __builtin_amdgcn_s_setprio(3);
;             solve64(x, sL);
;             __builtin_amdgcn_s_setprio(0);
; #pragma unroll
;             for (int cc = 0; cc < 2; ++cc) { const int ct = 2 * lw + cc;
;                 pv[cc][0] = *(const bf16x8*)(vTb + (size_t)(16 * ct + r) * 64 + 8 * q); pv[cc][1] = *(const bf16x8*)(vTb + (size_t)(16 * ct + r) * 64 + 32 + 8 * q);
;                 pk[cc][0] = *(const bf16x8*)(kTb + (size_t)(16 * ct + r) * 64 + 8 * q); pk[cc][1] = *(const bf16x8*)(kTb + (size_t)(16 * ct + r) * 64 + 32 + 8 * q); }
;             const float bj = sB[lane], bej = bj * sE[lane];
; #pragma unroll
;             for (int i = 0; i < 64; ++i) { *(PG8_LAS bf16_t*)(Tu + (i * 72 + lane) * 2) = f2bf(x[i] * bj); *(PG8_LAS bf16_t*)(Tw + (i * 72 + lane) * 2) = f2bf(x[i] * bej); }
.LBB0_298:
	s_andn2_b64 vcc, exec, s[26:27]
	s_cbranch_vccnz .LBB0_252
	s_setprio 3
	v_readlane_b32 s14, v252, 32
	s_nop 1
	v_mov_b32_e32 v251, s14
	ds_read2st64_b32 v[128:129], v130 offset0:1 offset1:2
	ds_read_b128 v[64:67], v251 offset:1024
	ds_read_b128 v[68:71], v251 offset:1040
	ds_read_b128 v[72:75], v251 offset:1056
	ds_read_b128 v[76:79], v251 offset:1072
	ds_read_b128 v[80:83], v251 offset:1088
	ds_read_b128 v[84:87], v251 offset:1104
	ds_read_b128 v[88:91], v251 offset:1120
	ds_read_b128 v[92:95], v251 offset:1136
	ds_read_b128 v[230:233], v251 offset:1152
	ds_read_b128 v[234:237], v251 offset:1168
	ds_read_b128 v[238:241], v251 offset:1184
	ds_read_b128 v[242:245], v251 offset:1200
	ds_read_b128 v[246:249], v251 offset:1216
	s_waitcnt lgkmcnt(13)
	v_mul_f32_e32 v129, v128, v129
	v_pk_mul_f32 v[126:127], v[138:139], v[128:129] op_sel:[1,0] op_sel_hi:[1,1]
	s_nop 0
	v_cvt_pk_bf16_f32 v126, v126, v127
	s_nop 0
	ds_write_b16 v205, v126 offset:17408
	ds_write_b16_d16_hi v205, v126 offset:26624
	s_waitcnt lgkmcnt(14)
	v_fma_f32 v1, -v65, v139, v140
	v_fma_f32 v2, -v66, v139, v141
	v_fma_f32 v3, -v67, v139, v142
	ds_read_b128 v[64:67], v251 offset:1232
	s_waitcnt lgkmcnt(14)
	v_fma_f32 v4, -v68, v139, v143
	v_fma_f32 v5, -v69, v139, v144
	v_fma_f32 v6, -v70, v139, v145
	v_fma_f32 v7, -v71, v139, v146
	ds_read_b128 v[68:71], v251 offset:1248
	s_waitcnt lgkmcnt(14)
	v_fma_f32 v8, -v72, v139, v147
	v_fma_f32 v9, -v73, v139, v148
	v_fma_f32 v10, -v74, v139, v149
	v_fma_f32 v11, -v75, v139, v150
	ds_read_b128 v[72:75], v251 offset:1264
	s_waitcnt lgkmcnt(14)
	v_fma_f32 v12, -v76, v139, v151
	v_fma_f32 v13, -v77, v139, v154
	v_fma_f32 v14, -v78, v139, v155
	v_fma_f32 v15, -v79, v139, v156
	ds_read_b128 v[76:79], v251 offset:1280
	s_waitcnt lgkmcnt(14)
	v_fma_f32 v16, -v80, v139, v157
	v_fma_f32 v17, -v81, v139, v158
	v_fma_f32 v18, -v82, v139, v159
	v_fma_f32 v19, -v83, v139, v160
	ds_read_b128 v[80:83], v251 offset:1296
	s_waitcnt lgkmcnt(14)
	v_fma_f32 v20, -v84, v139, v161
	v_fma_f32 v21, -v85, v139, v162
	v_fma_f32 v22, -v86, v139, v163
	v_fma_f32 v23, -v87, v139, v164
	ds_read_b128 v[84:87], v251 offset:1312
	s_waitcnt lgkmcnt(14)
	v_fma_f32 v24, -v88, v139, v165
	v_fma_f32 v25, -v89, v139, v166
	v_fma_f32 v26, -v90, v139, v167
	v_fma_f32 v27, -v91, v139, v168
	ds_read_b128 v[88:91], v251 offset:1328
	s_waitcnt lgkmcnt(14)
	v_fma_f32 v28, -v92, v139, v169
	v_fma_f32 v29, -v93, v139, v170
	v_fma_f32 v30, -v94, v139, v171
	v_fma_f32 v31, -v95, v139, v172
	ds_read_b128 v[92:95], v251 offset:1344
	s_waitcnt lgkmcnt(14)
	v_fma_f32 v32, -v230, v139, v173
	v_fma_f32 v33, -v231, v139, v174
	v_fma_f32 v34, -v232, v139, v175
	v_fma_f32 v35, -v233, v139, v176
	ds_read_b128 v[230:233], v251 offset:1360
	s_waitcnt lgkmcnt(14)
	v_fma_f32 v36, -v234, v139, v177
	v_fma_f32 v37, -v235, v139, v178
	v_fma_f32 v38, -v236, v139, v179
	v_fma_f32 v39, -v237, v139, v180
	ds_read_b128 v[234:237], v251 offset:1376
	s_waitcnt lgkmcnt(14)
	v_fma_f32 v40, -v238, v139, v181
	v_fma_f32 v41, -v239, v139, v182
	v_fma_f32 v42, -v240, v139, v183
	v_fma_f32 v43, -v241, v139, v184
	ds_read_b128 v[238:241], v251 offset:1392
	s_waitcnt lgkmcnt(14)
	v_fma_f32 v44, -v242, v139, v185
	v_fma_f32 v45, -v243, v139, v186
	v_fma_f32 v46, -v244, v139, v187
	v_fma_f32 v47, -v245, v139, v188
	ds_read_b128 v[242:245], v251 offset:1408
	s_waitcnt lgkmcnt(14)
	v_fma_f32 v48, -v246, v139, v189
	v_fma_f32 v49, -v247, v139, v190
	v_fma_f32 v50, -v248, v139, v191
	v_fma_f32 v51, -v249, v139, v192
	ds_read_b128 v[246:249], v251 offset:1424
	s_waitcnt lgkmcnt(12)
	v_fma_f32 v52, -v64, v139, v193
	v_fma_f32 v53, -v65, v139, v194
	v_fma_f32 v54, -v66, v139, v195
	v_fma_f32 v55, -v67, v139, v196
	ds_read_b128 v[64:67], v251 offset:1440
	s_waitcnt lgkmcnt(12)
	v_fma_f32 v56, -v68, v139, v197
	v_fma_f32 v57, -v69, v139, v198
	v_fma_f32 v58, -v70, v139, v199
	v_fma_f32 v59, -v71, v139, v200
	ds_read_b128 v[68:71], v251 offset:1456
	s_waitcnt lgkmcnt(12)
	v_fma_f32 v60, -v72, v139, v201
	v_fma_f32 v61, -v73, v139, v202
	v_fma_f32 v62, -v74, v139, v203
	v_fma_f32 v63, -v75, v139, v204
	ds_read_b128 v[72:75], v251 offset:1472
	v_pk_mul_f32 v[126:127], v[0:1], v[128:129] op_sel:[1,0] op_sel_hi:[1,1]
	s_nop 0
	v_cvt_pk_bf16_f32 v126, v126, v127
	s_nop 0
	ds_write_b16 v205, v126 offset:17552
	ds_write_b16_d16_hi v205, v126 offset:26768
	s_waitcnt lgkmcnt(14)
	v_pk_fma_f32 v[2:3], v[78:79], v[0:1], v[2:3] op_sel:[0,1,0] op_sel_hi:[1,1,1] neg_lo:[1,0,0] neg_hi:[1,0,0]
	ds_read_b128 v[76:79], v251 offset:1488
	s_waitcnt lgkmcnt(14)
	v_pk_fma_f32 v[4:5], v[80:81], v[0:1], v[4:5] op_sel:[0,1,0] op_sel_hi:[1,1,1] neg_lo:[1,0,0] neg_hi:[1,0,0]
	v_pk_fma_f32 v[6:7], v[82:83], v[0:1], v[6:7] op_sel:[0,1,0] op_sel_hi:[1,1,1] neg_lo:[1,0,0] neg_hi:[1,0,0]
	ds_read_b128 v[80:83], v251 offset:1504
	s_waitcnt lgkmcnt(14)
	v_pk_fma_f32 v[8:9], v[84:85], v[0:1], v[8:9] op_sel:[0,1,0] op_sel_hi:[1,1,1] neg_lo:[1,0,0] neg_hi:[1,0,0]
	v_pk_fma_f32 v[10:11], v[86:87], v[0:1], v[10:11] op_sel:[0,1,0] op_sel_hi:[1,1,1] neg_lo:[1,0,0] neg_hi:[1,0,0]
	ds_read_b128 v[84:87], v251 offset:1520
	s_waitcnt lgkmcnt(14)
	v_pk_fma_f32 v[12:13], v[88:89], v[0:1], v[12:13] op_sel:[0,1,0] op_sel_hi:[1,1,1] neg_lo:[1,0,0] neg_hi:[1,0,0]
	v_pk_fma_f32 v[14:15], v[90:91], v[0:1], v[14:15] op_sel:[0,1,0] op_sel_hi:[1,1,1] neg_lo:[1,0,0] neg_hi:[1,0,0]
	ds_read_b128 v[88:91], v251 offset:1536
	s_waitcnt lgkmcnt(14)
	v_pk_fma_f32 v[16:17], v[92:93], v[0:1], v[16:17] op_sel:[0,1,0] op_sel_hi:[1,1,1] neg_lo:[1,0,0] neg_hi:[1,0,0]
	v_pk_fma_f32 v[18:19], v[94:95], v[0:1], v[18:19] op_sel:[0,1,0] op_sel_hi:[1,1,1] neg_lo:[1,0,0] neg_hi:[1,0,0]
	ds_read_b128 v[92:95], v251 offset:1552
	s_waitcnt lgkmcnt(14)
; #define PG8_LAS __attribute__((address_space(3)))
; __device__ __forceinline__ bf16_t f2bf(float x) { return (bf16_t)(pk2(x, x) & 0xffffu); }
; __device__ __forceinline__ void solve64(float (&x)[64], const PG8_LAS float* sLt) {
;     ...
;     for (int j = 0; j < 63; ++j) {
;         const float xj = x[j];
; #pragma unroll
;         for (int i4 = (j + 1) / 4; i4 < 16; ++i4) {
;             if (4 * i4 + 0 > j) x[4 * i4 + 0] -= cur[i4][0] * xj;
;             if (4 * i4 + 1 > j) x[4 * i4 + 1] -= cur[i4][1] * xj;
;             if (4 * i4 + 2 > j) x[4 * i4 + 2] -= cur[i4][2] * xj;
;             if (4 * i4 + 3 > j) x[4 * i4 + 3] -= cur[i4][3] * xj;
;             if (j + 1 < 63 && i4 >= (j + 2) / 4) cur[i4] = *(const PG8_LAS f32x4*)(sLt + (j + 1) * 64 + 4 * i4); }
; __device__ __forceinline__ void phase_prep(const Args& a, PG8_LAS unsigned char* lds) {
;     ...
;             for (int i = 0; i < 64; ++i) { *(PG8_LAS bf16_t*)(Tu + (i * 72 + lane) * 2) = f2bf(x[i] * bj); *(PG8_LAS bf16_t*)(Tw + (i * 72 + lane) * 2) = f2bf(x[i] * bej); }
	v_pk_fma_f32 v[20:21], v[230:231], v[0:1], v[20:21] op_sel:[0,1,0] op_sel_hi:[1,1,1] neg_lo:[1,0,0] neg_hi:[1,0,0]
	v_pk_fma_f32 v[22:23], v[232:233], v[0:1], v[22:23] op_sel:[0,1,0] op_sel_hi:[1,1,1] neg_lo:[1,0,0] neg_hi:[1,0,0]
	ds_read_b128 v[230:233], v251 offset:1568
	s_waitcnt lgkmcnt(14)
	v_pk_fma_f32 v[24:25], v[234:235], v[0:1], v[24:25] op_sel:[0,1,0] op_sel_hi:[1,1,1] neg_lo:[1,0,0] neg_hi:[1,0,0]
	v_pk_fma_f32 v[26:27], v[236:237], v[0:1], v[26:27] op_sel:[0,1,0] op_sel_hi:[1,1,1] neg_lo:[1,0,0] neg_hi:[1,0,0]
	ds_read_b128 v[234:237], v251 offset:1584
	s_waitcnt lgkmcnt(14)
	v_pk_fma_f32 v[28:29], v[238:239], v[0:1], v[28:29] op_sel:[0,1,0] op_sel_hi:[1,1,1] neg_lo:[1,0,0] neg_hi:[1,0,0]
	v_pk_fma_f32 v[30:31], v[240:241], v[0:1], v[30:31] op_sel:[0,1,0] op_sel_hi:[1,1,1] neg_lo:[1,0,0] neg_hi:[1,0,0]
	ds_read_b128 v[238:241], v251 offset:1600
	s_waitcnt lgkmcnt(14)
	v_pk_fma_f32 v[32:33], v[242:243], v[0:1], v[32:33] op_sel:[0,1,0] op_sel_hi:[1,1,1] neg_lo:[1,0,0] neg_hi:[1,0,0]
	v_pk_fma_f32 v[34:35], v[244:245], v[0:1], v[34:35] op_sel:[0,1,0] op_sel_hi:[1,1,1] neg_lo:[1,0,0] neg_hi:[1,0,0]
	ds_read_b128 v[242:245], v251 offset:1616
	s_waitcnt lgkmcnt(14)
	v_pk_fma_f32 v[36:37], v[246:247], v[0:1], v[36:37] op_sel:[0,1,0] op_sel_hi:[1,1,1] neg_lo:[1,0,0] neg_hi:[1,0,0]
	v_pk_fma_f32 v[38:39], v[248:249], v[0:1], v[38:39] op_sel:[0,1,0] op_sel_hi:[1,1,1] neg_lo:[1,0,0] neg_hi:[1,0,0]
	ds_read_b128 v[246:249], v251 offset:1632
	s_waitcnt lgkmcnt(14)
	v_pk_fma_f32 v[40:41], v[64:65], v[0:1], v[40:41] op_sel:[0,1,0] op_sel_hi:[1,1,1] neg_lo:[1,0,0] neg_hi:[1,0,0]
	v_pk_fma_f32 v[42:43], v[66:67], v[0:1], v[42:43] op_sel:[0,1,0] op_sel_hi:[1,1,1] neg_lo:[1,0,0] neg_hi:[1,0,0]
	ds_read_b128 v[64:67], v251 offset:1648
	s_waitcnt lgkmcnt(14)
	v_pk_fma_f32 v[44:45], v[68:69], v[0:1], v[44:45] op_sel:[0,1,0] op_sel_hi:[1,1,1] neg_lo:[1,0,0] neg_hi:[1,0,0]
	v_pk_fma_f32 v[46:47], v[70:71], v[0:1], v[46:47] op_sel:[0,1,0] op_sel_hi:[1,1,1] neg_lo:[1,0,0] neg_hi:[1,0,0]
	ds_read_b128 v[68:71], v251 offset:1664
	s_waitcnt lgkmcnt(14)
	v_pk_fma_f32 v[48:49], v[72:73], v[0:1], v[48:49] op_sel:[0,1,0] op_sel_hi:[1,1,1] neg_lo:[1,0,0] neg_hi:[1,0,0]
	v_pk_fma_f32 v[50:51], v[74:75], v[0:1], v[50:51] op_sel:[0,1,0] op_sel_hi:[1,1,1] neg_lo:[1,0,0] neg_hi:[1,0,0]
	ds_read_b128 v[72:75], v251 offset:1680
	s_waitcnt lgkmcnt(12)
	v_pk_fma_f32 v[52:53], v[76:77], v[0:1], v[52:53] op_sel:[0,1,0] op_sel_hi:[1,1,1] neg_lo:[1,0,0] neg_hi:[1,0,0]
	v_pk_fma_f32 v[54:55], v[78:79], v[0:1], v[54:55] op_sel:[0,1,0] op_sel_hi:[1,1,1] neg_lo:[1,0,0] neg_hi:[1,0,0]
	ds_read_b128 v[76:79], v251 offset:1696
	s_waitcnt lgkmcnt(12)
	v_pk_fma_f32 v[56:57], v[80:81], v[0:1], v[56:57] op_sel:[0,1,0] op_sel_hi:[1,1,1] neg_lo:[1,0,0] neg_hi:[1,0,0]
	v_pk_fma_f32 v[58:59], v[82:83], v[0:1], v[58:59] op_sel:[0,1,0] op_sel_hi:[1,1,1] neg_lo:[1,0,0] neg_hi:[1,0,0]
	ds_read_b128 v[80:83], v251 offset:1712
	s_waitcnt lgkmcnt(12)
	v_pk_fma_f32 v[60:61], v[84:85], v[0:1], v[60:61] op_sel:[0,1,0] op_sel_hi:[1,1,1] neg_lo:[1,0,0] neg_hi:[1,0,0]
	v_pk_fma_f32 v[62:63], v[86:87], v[0:1], v[62:63] op_sel:[0,1,0] op_sel_hi:[1,1,1] neg_lo:[1,0,0] neg_hi:[1,0,0]
	ds_read_b128 v[84:87], v251 offset:1728
	v_pk_mul_f32 v[126:127], v[2:3], v[128:129] op_sel:[0,0] op_sel_hi:[0,1]
	s_nop 0
	v_cvt_pk_bf16_f32 v126, v126, v127
	s_nop 0
	ds_write_b16 v205, v126 offset:17696
	ds_write_b16_d16_hi v205, v126 offset:26912
	s_waitcnt lgkmcnt(14)
	v_fma_f32 v3, -v91, v2, v3
	ds_read_b128 v[88:91], v251 offset:1744
	s_waitcnt lgkmcnt(14)
	v_pk_fma_f32 v[4:5], v[92:93], v[2:3], v[4:5] op_sel:[0,0,0] op_sel_hi:[1,0,1] neg_lo:[1,0,0] neg_hi:[1,0,0]
	v_pk_fma_f32 v[6:7], v[94:95], v[2:3], v[6:7] op_sel:[0,0,0] op_sel_hi:[1,0,1] neg_lo:[1,0,0] neg_hi:[1,0,0]
	ds_read_b128 v[92:95], v251 offset:1760
	s_waitcnt lgkmcnt(14)
	v_pk_fma_f32 v[8:9], v[230:231], v[2:3], v[8:9] op_sel:[0,0,0] op_sel_hi:[1,0,1] neg_lo:[1,0,0] neg_hi:[1,0,0]
	v_pk_fma_f32 v[10:11], v[232:233], v[2:3], v[10:11] op_sel:[0,0,0] op_sel_hi:[1,0,1] neg_lo:[1,0,0] neg_hi:[1,0,0]
	ds_read_b128 v[230:233], v251 offset:1776
	s_waitcnt lgkmcnt(14)
	v_pk_fma_f32 v[12:13], v[234:235], v[2:3], v[12:13] op_sel:[0,0,0] op_sel_hi:[1,0,1] neg_lo:[1,0,0] neg_hi:[1,0,0]
	v_pk_fma_f32 v[14:15], v[236:237], v[2:3], v[14:15] op_sel:[0,0,0] op_sel_hi:[1,0,1] neg_lo:[1,0,0] neg_hi:[1,0,0]
	ds_read_b128 v[234:237], v251 offset:1808
	s_waitcnt lgkmcnt(14)
	v_pk_fma_f32 v[16:17], v[238:239], v[2:3], v[16:17] op_sel:[0,0,0] op_sel_hi:[1,0,1] neg_lo:[1,0,0] neg_hi:[1,0,0]
	v_pk_fma_f32 v[18:19], v[240:241], v[2:3], v[18:19] op_sel:[0,0,0] op_sel_hi:[1,0,1] neg_lo:[1,0,0] neg_hi:[1,0,0]
	ds_read_b128 v[238:241], v251 offset:1824
	s_waitcnt lgkmcnt(14)
	v_pk_fma_f32 v[20:21], v[242:243], v[2:3], v[20:21] op_sel:[0,0,0] op_sel_hi:[1,0,1] neg_lo:[1,0,0] neg_hi:[1,0,0]
	v_pk_fma_f32 v[22:23], v[244:245], v[2:3], v[22:23] op_sel:[0,0,0] op_sel_hi:[1,0,1] neg_lo:[1,0,0] neg_hi:[1,0,0]
	ds_read_b128 v[242:245], v251 offset:1840
	s_waitcnt lgkmcnt(14)
	v_pk_fma_f32 v[24:25], v[246:247], v[2:3], v[24:25] op_sel:[0,0,0] op_sel_hi:[1,0,1] neg_lo:[1,0,0] neg_hi:[1,0,0]
	v_pk_fma_f32 v[26:27], v[248:249], v[2:3], v[26:27] op_sel:[0,0,0] op_sel_hi:[1,0,1] neg_lo:[1,0,0] neg_hi:[1,0,0]
	ds_read_b128 v[246:249], v251 offset:1856
	s_waitcnt lgkmcnt(14)
	v_pk_fma_f32 v[28:29], v[64:65], v[2:3], v[28:29] op_sel:[0,0,0] op_sel_hi:[1,0,1] neg_lo:[1,0,0] neg_hi:[1,0,0]
	v_pk_fma_f32 v[30:31], v[66:67], v[2:3], v[30:31] op_sel:[0,0,0] op_sel_hi:[1,0,1] neg_lo:[1,0,0] neg_hi:[1,0,0]
	ds_read_b128 v[64:67], v251 offset:1872
	s_waitcnt lgkmcnt(14)
; #define PG8_LAS __attribute__((address_space(3)))
; __device__ __forceinline__ bf16_t f2bf(float x) { return (bf16_t)(pk2(x, x) & 0xffffu); }
; __device__ __forceinline__ void solve64(float (&x)[64], const PG8_LAS float* sLt) {
;     ...
;     for (int j = 0; j < 63; ++j) {
;         const float xj = x[j];
; #pragma unroll
;         for (int i4 = (j + 1) / 4; i4 < 16; ++i4) {
;             if (4 * i4 + 0 > j) x[4 * i4 + 0] -= cur[i4][0] * xj;
;             if (4 * i4 + 1 > j) x[4 * i4 + 1] -= cur[i4][1] * xj;
;             if (4 * i4 + 2 > j) x[4 * i4 + 2] -= cur[i4][2] * xj;
;             if (4 * i4 + 3 > j) x[4 * i4 + 3] -= cur[i4][3] * xj;
;             if (j + 1 < 63 && i4 >= (j + 2) / 4) cur[i4] = *(const PG8_LAS f32x4*)(sLt + (j + 1) * 64 + 4 * i4); }
; __device__ __forceinline__ void phase_prep(const Args& a, PG8_LAS unsigned char* lds) {
;     ...
;             for (int i = 0; i < 64; ++i) { *(PG8_LAS bf16_t*)(Tu + (i * 72 + lane) * 2) = f2bf(x[i] * bj); *(PG8_LAS bf16_t*)(Tw + (i * 72 + lane) * 2) = f2bf(x[i] * bej); }
	v_pk_fma_f32 v[32:33], v[68:69], v[2:3], v[32:33] op_sel:[0,0,0] op_sel_hi:[1,0,1] neg_lo:[1,0,0] neg_hi:[1,0,0]
	v_pk_fma_f32 v[34:35], v[70:71], v[2:3], v[34:35] op_sel:[0,0,0] op_sel_hi:[1,0,1] neg_lo:[1,0,0] neg_hi:[1,0,0]
	ds_read_b128 v[68:71], v251 offset:1888
	s_waitcnt lgkmcnt(14)
	v_pk_fma_f32 v[36:37], v[72:73], v[2:3], v[36:37] op_sel:[0,0,0] op_sel_hi:[1,0,1] neg_lo:[1,0,0] neg_hi:[1,0,0]
	v_pk_fma_f32 v[38:39], v[74:75], v[2:3], v[38:39] op_sel:[0,0,0] op_sel_hi:[1,0,1] neg_lo:[1,0,0] neg_hi:[1,0,0]
	ds_read_b128 v[72:75], v251 offset:1904
	s_waitcnt lgkmcnt(14)
	v_pk_fma_f32 v[40:41], v[76:77], v[2:3], v[40:41] op_sel:[0,0,0] op_sel_hi:[1,0,1] neg_lo:[1,0,0] neg_hi:[1,0,0]
	v_pk_fma_f32 v[42:43], v[78:79], v[2:3], v[42:43] op_sel:[0,0,0] op_sel_hi:[1,0,1] neg_lo:[1,0,0] neg_hi:[1,0,0]
	ds_read_b128 v[76:79], v251 offset:1920
	s_waitcnt lgkmcnt(14)
	v_pk_fma_f32 v[44:45], v[80:81], v[2:3], v[44:45] op_sel:[0,0,0] op_sel_hi:[1,0,1] neg_lo:[1,0,0] neg_hi:[1,0,0]
	v_pk_fma_f32 v[46:47], v[82:83], v[2:3], v[46:47] op_sel:[0,0,0] op_sel_hi:[1,0,1] neg_lo:[1,0,0] neg_hi:[1,0,0]
	ds_read_b128 v[80:83], v251 offset:1936
	s_waitcnt lgkmcnt(14)
	v_pk_fma_f32 v[48:49], v[84:85], v[2:3], v[48:49] op_sel:[0,0,0] op_sel_hi:[1,0,1] neg_lo:[1,0,0] neg_hi:[1,0,0]
	v_pk_fma_f32 v[50:51], v[86:87], v[2:3], v[50:51] op_sel:[0,0,0] op_sel_hi:[1,0,1] neg_lo:[1,0,0] neg_hi:[1,0,0]
	ds_read_b128 v[84:87], v251 offset:1952
	s_waitcnt lgkmcnt(12)
	v_pk_fma_f32 v[52:53], v[88:89], v[2:3], v[52:53] op_sel:[0,0,0] op_sel_hi:[1,0,1] neg_lo:[1,0,0] neg_hi:[1,0,0]
	v_pk_fma_f32 v[54:55], v[90:91], v[2:3], v[54:55] op_sel:[0,0,0] op_sel_hi:[1,0,1] neg_lo:[1,0,0] neg_hi:[1,0,0]
	ds_read_b128 v[88:91], v251 offset:1968
	s_waitcnt lgkmcnt(12)
	v_pk_fma_f32 v[56:57], v[92:93], v[2:3], v[56:57] op_sel:[0,0,0] op_sel_hi:[1,0,1] neg_lo:[1,0,0] neg_hi:[1,0,0]
	v_pk_fma_f32 v[58:59], v[94:95], v[2:3], v[58:59] op_sel:[0,0,0] op_sel_hi:[1,0,1] neg_lo:[1,0,0] neg_hi:[1,0,0]
	ds_read_b128 v[92:95], v251 offset:1984
	s_waitcnt lgkmcnt(12)
	v_pk_fma_f32 v[60:61], v[230:231], v[2:3], v[60:61] op_sel:[0,0,0] op_sel_hi:[1,0,1] neg_lo:[1,0,0] neg_hi:[1,0,0]
	v_pk_fma_f32 v[62:63], v[232:233], v[2:3], v[62:63] op_sel:[0,0,0] op_sel_hi:[1,0,1] neg_lo:[1,0,0] neg_hi:[1,0,0]
	ds_read_b128 v[230:233], v251 offset:2000
	v_pk_mul_f32 v[126:127], v[2:3], v[128:129] op_sel:[1,0] op_sel_hi:[1,1]
	s_nop 0
	v_cvt_pk_bf16_f32 v126, v126, v127
	s_nop 0
	ds_write_b16 v205, v126 offset:17840
	ds_write_b16_d16_hi v205, v126 offset:27056
	s_waitcnt lgkmcnt(14)
	v_pk_fma_f32 v[4:5], v[234:235], v[2:3], v[4:5] op_sel:[0,1,0] op_sel_hi:[1,1,1] neg_lo:[1,0,0] neg_hi:[1,0,0]
	v_pk_fma_f32 v[6:7], v[236:237], v[2:3], v[6:7] op_sel:[0,1,0] op_sel_hi:[1,1,1] neg_lo:[1,0,0] neg_hi:[1,0,0]
	ds_read_b128 v[234:237], v251 offset:2016
	s_waitcnt lgkmcnt(14)
	v_pk_fma_f32 v[8:9], v[238:239], v[2:3], v[8:9] op_sel:[0,1,0] op_sel_hi:[1,1,1] neg_lo:[1,0,0] neg_hi:[1,0,0]
	v_pk_fma_f32 v[10:11], v[240:241], v[2:3], v[10:11] op_sel:[0,1,0] op_sel_hi:[1,1,1] neg_lo:[1,0,0] neg_hi:[1,0,0]
	ds_read_b128 v[238:241], v251 offset:2032
	s_waitcnt lgkmcnt(14)
	v_pk_fma_f32 v[12:13], v[242:243], v[2:3], v[12:13] op_sel:[0,1,0] op_sel_hi:[1,1,1] neg_lo:[1,0,0] neg_hi:[1,0,0]
	v_pk_fma_f32 v[14:15], v[244:245], v[2:3], v[14:15] op_sel:[0,1,0] op_sel_hi:[1,1,1] neg_lo:[1,0,0] neg_hi:[1,0,0]
	ds_read_b128 v[242:245], v251 offset:2064
	s_waitcnt lgkmcnt(14)
	v_pk_fma_f32 v[16:17], v[246:247], v[2:3], v[16:17] op_sel:[0,1,0] op_sel_hi:[1,1,1] neg_lo:[1,0,0] neg_hi:[1,0,0]
	v_pk_fma_f32 v[18:19], v[248:249], v[2:3], v[18:19] op_sel:[0,1,0] op_sel_hi:[1,1,1] neg_lo:[1,0,0] neg_hi:[1,0,0]
	ds_read_b128 v[246:249], v251 offset:2080
	s_waitcnt lgkmcnt(14)
	v_pk_fma_f32 v[20:21], v[64:65], v[2:3], v[20:21] op_sel:[0,1,0] op_sel_hi:[1,1,1] neg_lo:[1,0,0] neg_hi:[1,0,0]
	v_pk_fma_f32 v[22:23], v[66:67], v[2:3], v[22:23] op_sel:[0,1,0] op_sel_hi:[1,1,1] neg_lo:[1,0,0] neg_hi:[1,0,0]
	ds_read_b128 v[64:67], v251 offset:2096
	s_waitcnt lgkmcnt(14)
	v_pk_fma_f32 v[24:25], v[68:69], v[2:3], v[24:25] op_sel:[0,1,0] op_sel_hi:[1,1,1] neg_lo:[1,0,0] neg_hi:[1,0,0]
	v_pk_fma_f32 v[26:27], v[70:71], v[2:3], v[26:27] op_sel:[0,1,0] op_sel_hi:[1,1,1] neg_lo:[1,0,0] neg_hi:[1,0,0]
	ds_read_b128 v[68:71], v251 offset:2112
	s_waitcnt lgkmcnt(14)
	v_pk_fma_f32 v[28:29], v[72:73], v[2:3], v[28:29] op_sel:[0,1,0] op_sel_hi:[1,1,1] neg_lo:[1,0,0] neg_hi:[1,0,0]
	v_pk_fma_f32 v[30:31], v[74:75], v[2:3], v[30:31] op_sel:[0,1,0] op_sel_hi:[1,1,1] neg_lo:[1,0,0] neg_hi:[1,0,0]
	ds_read_b128 v[72:75], v251 offset:2128
	s_waitcnt lgkmcnt(14)
	v_pk_fma_f32 v[32:33], v[76:77], v[2:3], v[32:33] op_sel:[0,1,0] op_sel_hi:[1,1,1] neg_lo:[1,0,0] neg_hi:[1,0,0]
	v_pk_fma_f32 v[34:35], v[78:79], v[2:3], v[34:35] op_sel:[0,1,0] op_sel_hi:[1,1,1] neg_lo:[1,0,0] neg_hi:[1,0,0]
	ds_read_b128 v[76:79], v251 offset:2144
	s_waitcnt lgkmcnt(14)
	v_pk_fma_f32 v[36:37], v[80:81], v[2:3], v[36:37] op_sel:[0,1,0] op_sel_hi:[1,1,1] neg_lo:[1,0,0] neg_hi:[1,0,0]
	v_pk_fma_f32 v[38:39], v[82:83], v[2:3], v[38:39] op_sel:[0,1,0] op_sel_hi:[1,1,1] neg_lo:[1,0,0] neg_hi:[1,0,0]
	ds_read_b128 v[80:83], v251 offset:2160
	s_waitcnt lgkmcnt(14)
	v_pk_fma_f32 v[40:41], v[84:85], v[2:3], v[40:41] op_sel:[0,1,0] op_sel_hi:[1,1,1] neg_lo:[1,0,0] neg_hi:[1,0,0]
	v_pk_fma_f32 v[42:43], v[86:87], v[2:3], v[42:43] op_sel:[0,1,0] op_sel_hi:[1,1,1] neg_lo:[1,0,0] neg_hi:[1,0,0]
	ds_read_b128 v[84:87], v251 offset:2176
	s_waitcnt lgkmcnt(14)
	v_pk_fma_f32 v[44:45], v[88:89], v[2:3], v[44:45] op_sel:[0,1,0] op_sel_hi:[1,1,1] neg_lo:[1,0,0] neg_hi:[1,0,0]
	v_pk_fma_f32 v[46:47], v[90:91], v[2:3], v[46:47] op_sel:[0,1,0] op_sel_hi:[1,1,1] neg_lo:[1,0,0] neg_hi:[1,0,0]
	ds_read_b128 v[88:91], v251 offset:2192
	s_waitcnt lgkmcnt(14)
; #define PG8_LAS __attribute__((address_space(3)))
; __device__ __forceinline__ bf16_t f2bf(float x) { return (bf16_t)(pk2(x, x) & 0xffffu); }
; __device__ __forceinline__ void solve64(float (&x)[64], const PG8_LAS float* sLt) {
;     ...
;     for (int j = 0; j < 63; ++j) {
;         const float xj = x[j];
; #pragma unroll
;         for (int i4 = (j + 1) / 4; i4 < 16; ++i4) {
;             if (4 * i4 + 0 > j) x[4 * i4 + 0] -= cur[i4][0] * xj;
;             if (4 * i4 + 1 > j) x[4 * i4 + 1] -= cur[i4][1] * xj;
;             if (4 * i4 + 2 > j) x[4 * i4 + 2] -= cur[i4][2] * xj;
;             if (4 * i4 + 3 > j) x[4 * i4 + 3] -= cur[i4][3] * xj;
;             if (j + 1 < 63 && i4 >= (j + 2) / 4) cur[i4] = *(const PG8_LAS f32x4*)(sLt + (j + 1) * 64 + 4 * i4); }
; __device__ __forceinline__ void phase_prep(const Args& a, PG8_LAS unsigned char* lds) {
;     ...
;             for (int i = 0; i < 64; ++i) { *(PG8_LAS bf16_t*)(Tu + (i * 72 + lane) * 2) = f2bf(x[i] * bj); *(PG8_LAS bf16_t*)(Tw + (i * 72 + lane) * 2) = f2bf(x[i] * bej); }
	v_pk_fma_f32 v[48:49], v[92:93], v[2:3], v[48:49] op_sel:[0,1,0] op_sel_hi:[1,1,1] neg_lo:[1,0,0] neg_hi:[1,0,0]
	v_pk_fma_f32 v[50:51], v[94:95], v[2:3], v[50:51] op_sel:[0,1,0] op_sel_hi:[1,1,1] neg_lo:[1,0,0] neg_hi:[1,0,0]
	ds_read_b128 v[92:95], v251 offset:2208
	s_waitcnt lgkmcnt(14)
	v_pk_fma_f32 v[52:53], v[230:231], v[2:3], v[52:53] op_sel:[0,1,0] op_sel_hi:[1,1,1] neg_lo:[1,0,0] neg_hi:[1,0,0]
	v_pk_fma_f32 v[54:55], v[232:233], v[2:3], v[54:55] op_sel:[0,1,0] op_sel_hi:[1,1,1] neg_lo:[1,0,0] neg_hi:[1,0,0]
	ds_read_b128 v[230:233], v251 offset:2224
	s_waitcnt lgkmcnt(12)
	v_pk_fma_f32 v[56:57], v[234:235], v[2:3], v[56:57] op_sel:[0,1,0] op_sel_hi:[1,1,1] neg_lo:[1,0,0] neg_hi:[1,0,0]
	v_pk_fma_f32 v[58:59], v[236:237], v[2:3], v[58:59] op_sel:[0,1,0] op_sel_hi:[1,1,1] neg_lo:[1,0,0] neg_hi:[1,0,0]
	ds_read_b128 v[234:237], v251 offset:2240
	s_waitcnt lgkmcnt(12)
	v_pk_fma_f32 v[60:61], v[238:239], v[2:3], v[60:61] op_sel:[0,1,0] op_sel_hi:[1,1,1] neg_lo:[1,0,0] neg_hi:[1,0,0]
	v_pk_fma_f32 v[62:63], v[240:241], v[2:3], v[62:63] op_sel:[0,1,0] op_sel_hi:[1,1,1] neg_lo:[1,0,0] neg_hi:[1,0,0]
	ds_read_b128 v[238:241], v251 offset:2256
	v_pk_mul_f32 v[126:127], v[4:5], v[128:129] op_sel:[0,0] op_sel_hi:[0,1]
	s_nop 0
	v_cvt_pk_bf16_f32 v126, v126, v127
	s_nop 0
	ds_write_b16 v205, v126 offset:17984
	ds_write_b16_d16_hi v205, v126 offset:27200
	s_waitcnt lgkmcnt(14)
	v_fma_f32 v5, -v243, v4, v5
	v_pk_fma_f32 v[6:7], v[244:245], v[4:5], v[6:7] op_sel:[0,0,0] op_sel_hi:[1,0,1] neg_lo:[1,0,0] neg_hi:[1,0,0]
	ds_read_b128 v[242:245], v251 offset:2272
	s_waitcnt lgkmcnt(14)
	v_pk_fma_f32 v[8:9], v[246:247], v[4:5], v[8:9] op_sel:[0,0,0] op_sel_hi:[1,0,1] neg_lo:[1,0,0] neg_hi:[1,0,0]
	v_pk_fma_f32 v[10:11], v[248:249], v[4:5], v[10:11] op_sel:[0,0,0] op_sel_hi:[1,0,1] neg_lo:[1,0,0] neg_hi:[1,0,0]
	ds_read_b128 v[246:249], v251 offset:2288
	s_waitcnt lgkmcnt(14)
	v_pk_fma_f32 v[12:13], v[64:65], v[4:5], v[12:13] op_sel:[0,0,0] op_sel_hi:[1,0,1] neg_lo:[1,0,0] neg_hi:[1,0,0]
	v_pk_fma_f32 v[14:15], v[66:67], v[4:5], v[14:15] op_sel:[0,0,0] op_sel_hi:[1,0,1] neg_lo:[1,0,0] neg_hi:[1,0,0]
	ds_read_b128 v[64:67], v251 offset:2320
	s_waitcnt lgkmcnt(14)
	v_pk_fma_f32 v[16:17], v[68:69], v[4:5], v[16:17] op_sel:[0,0,0] op_sel_hi:[1,0,1] neg_lo:[1,0,0] neg_hi:[1,0,0]
	v_pk_fma_f32 v[18:19], v[70:71], v[4:5], v[18:19] op_sel:[0,0,0] op_sel_hi:[1,0,1] neg_lo:[1,0,0] neg_hi:[1,0,0]
	ds_read_b128 v[68:71], v251 offset:2336
	s_waitcnt lgkmcnt(14)
	v_pk_fma_f32 v[20:21], v[72:73], v[4:5], v[20:21] op_sel:[0,0,0] op_sel_hi:[1,0,1] neg_lo:[1,0,0] neg_hi:[1,0,0]
	v_pk_fma_f32 v[22:23], v[74:75], v[4:5], v[22:23] op_sel:[0,0,0] op_sel_hi:[1,0,1] neg_lo:[1,0,0] neg_hi:[1,0,0]
	ds_read_b128 v[72:75], v251 offset:2352
	s_waitcnt lgkmcnt(14)
	v_pk_fma_f32 v[24:25], v[76:77], v[4:5], v[24:25] op_sel:[0,0,0] op_sel_hi:[1,0,1] neg_lo:[1,0,0] neg_hi:[1,0,0]
	v_pk_fma_f32 v[26:27], v[78:79], v[4:5], v[26:27] op_sel:[0,0,0] op_sel_hi:[1,0,1] neg_lo:[1,0,0] neg_hi:[1,0,0]
	ds_read_b128 v[76:79], v251 offset:2368
	s_waitcnt lgkmcnt(14)
	v_pk_fma_f32 v[28:29], v[80:81], v[4:5], v[28:29] op_sel:[0,0,0] op_sel_hi:[1,0,1] neg_lo:[1,0,0] neg_hi:[1,0,0]
	v_pk_fma_f32 v[30:31], v[82:83], v[4:5], v[30:31] op_sel:[0,0,0] op_sel_hi:[1,0,1] neg_lo:[1,0,0] neg_hi:[1,0,0]
	ds_read_b128 v[80:83], v251 offset:2384
	s_waitcnt lgkmcnt(14)
	v_pk_fma_f32 v[32:33], v[84:85], v[4:5], v[32:33] op_sel:[0,0,0] op_sel_hi:[1,0,1] neg_lo:[1,0,0] neg_hi:[1,0,0]
	v_pk_fma_f32 v[34:35], v[86:87], v[4:5], v[34:35] op_sel:[0,0,0] op_sel_hi:[1,0,1] neg_lo:[1,0,0] neg_hi:[1,0,0]
	ds_read_b128 v[84:87], v251 offset:2400
	s_waitcnt lgkmcnt(14)
	v_pk_fma_f32 v[36:37], v[88:89], v[4:5], v[36:37] op_sel:[0,0,0] op_sel_hi:[1,0,1] neg_lo:[1,0,0] neg_hi:[1,0,0]
	v_pk_fma_f32 v[38:39], v[90:91], v[4:5], v[38:39] op_sel:[0,0,0] op_sel_hi:[1,0,1] neg_lo:[1,0,0] neg_hi:[1,0,0]
	ds_read_b128 v[88:91], v251 offset:2416
	s_waitcnt lgkmcnt(14)
	v_pk_fma_f32 v[40:41], v[92:93], v[4:5], v[40:41] op_sel:[0,0,0] op_sel_hi:[1,0,1] neg_lo:[1,0,0] neg_hi:[1,0,0]
	v_pk_fma_f32 v[42:43], v[94:95], v[4:5], v[42:43] op_sel:[0,0,0] op_sel_hi:[1,0,1] neg_lo:[1,0,0] neg_hi:[1,0,0]
	ds_read_b128 v[92:95], v251 offset:2432
	s_waitcnt lgkmcnt(14)
	v_pk_fma_f32 v[44:45], v[230:231], v[4:5], v[44:45] op_sel:[0,0,0] op_sel_hi:[1,0,1] neg_lo:[1,0,0] neg_hi:[1,0,0]
	v_pk_fma_f32 v[46:47], v[232:233], v[4:5], v[46:47] op_sel:[0,0,0] op_sel_hi:[1,0,1] neg_lo:[1,0,0] neg_hi:[1,0,0]
	ds_read_b128 v[230:233], v251 offset:2448
	s_waitcnt lgkmcnt(14)
	v_pk_fma_f32 v[48:49], v[234:235], v[4:5], v[48:49] op_sel:[0,0,0] op_sel_hi:[1,0,1] neg_lo:[1,0,0] neg_hi:[1,0,0]
	v_pk_fma_f32 v[50:51], v[236:237], v[4:5], v[50:51] op_sel:[0,0,0] op_sel_hi:[1,0,1] neg_lo:[1,0,0] neg_hi:[1,0,0]
	ds_read_b128 v[234:237], v251 offset:2464
	s_waitcnt lgkmcnt(14)
	v_pk_fma_f32 v[52:53], v[238:239], v[4:5], v[52:53] op_sel:[0,0,0] op_sel_hi:[1,0,1] neg_lo:[1,0,0] neg_hi:[1,0,0]
	v_pk_fma_f32 v[54:55], v[240:241], v[4:5], v[54:55] op_sel:[0,0,0] op_sel_hi:[1,0,1] neg_lo:[1,0,0] neg_hi:[1,0,0]
	ds_read_b128 v[238:241], v251 offset:2480
	s_waitcnt lgkmcnt(12)
	v_pk_fma_f32 v[56:57], v[242:243], v[4:5], v[56:57] op_sel:[0,0,0] op_sel_hi:[1,0,1] neg_lo:[1,0,0] neg_hi:[1,0,0]
	v_pk_fma_f32 v[58:59], v[244:245], v[4:5], v[58:59] op_sel:[0,0,0] op_sel_hi:[1,0,1] neg_lo:[1,0,0] neg_hi:[1,0,0]
	ds_read_b128 v[242:245], v251 offset:2496
	s_waitcnt lgkmcnt(12)
; #define PG8_LAS __attribute__((address_space(3)))
; __device__ __forceinline__ bf16_t f2bf(float x) { return (bf16_t)(pk2(x, x) & 0xffffu); }
; __device__ __forceinline__ void solve64(float (&x)[64], const PG8_LAS float* sLt) {
;     ...
;     for (int j = 0; j < 63; ++j) {
;         const float xj = x[j];
; #pragma unroll
;         for (int i4 = (j + 1) / 4; i4 < 16; ++i4) {
;             if (4 * i4 + 0 > j) x[4 * i4 + 0] -= cur[i4][0] * xj;
;             if (4 * i4 + 1 > j) x[4 * i4 + 1] -= cur[i4][1] * xj;
;             if (4 * i4 + 2 > j) x[4 * i4 + 2] -= cur[i4][2] * xj;
;             if (4 * i4 + 3 > j) x[4 * i4 + 3] -= cur[i4][3] * xj;
;             if (j + 1 < 63 && i4 >= (j + 2) / 4) cur[i4] = *(const PG8_LAS f32x4*)(sLt + (j + 1) * 64 + 4 * i4); }
; __device__ __forceinline__ void phase_prep(const Args& a, PG8_LAS unsigned char* lds) {
;     ...
;             for (int i = 0; i < 64; ++i) { *(PG8_LAS bf16_t*)(Tu + (i * 72 + lane) * 2) = f2bf(x[i] * bj); *(PG8_LAS bf16_t*)(Tw + (i * 72 + lane) * 2) = f2bf(x[i] * bej); }
	v_pk_fma_f32 v[60:61], v[246:247], v[4:5], v[60:61] op_sel:[0,0,0] op_sel_hi:[1,0,1] neg_lo:[1,0,0] neg_hi:[1,0,0]
	v_pk_fma_f32 v[62:63], v[248:249], v[4:5], v[62:63] op_sel:[0,0,0] op_sel_hi:[1,0,1] neg_lo:[1,0,0] neg_hi:[1,0,0]
	ds_read_b128 v[246:249], v251 offset:2512
	v_pk_mul_f32 v[126:127], v[4:5], v[128:129] op_sel:[1,0] op_sel_hi:[1,1]
	s_nop 0
	v_cvt_pk_bf16_f32 v126, v126, v127
	s_nop 0
	ds_write_b16 v205, v126 offset:18128
	ds_write_b16_d16_hi v205, v126 offset:27344
	s_waitcnt lgkmcnt(14)
	v_pk_fma_f32 v[6:7], v[66:67], v[4:5], v[6:7] op_sel:[0,1,0] op_sel_hi:[1,1,1] neg_lo:[1,0,0] neg_hi:[1,0,0]
	ds_read_b128 v[64:67], v251 offset:2528
	s_waitcnt lgkmcnt(14)
	v_pk_fma_f32 v[8:9], v[68:69], v[4:5], v[8:9] op_sel:[0,1,0] op_sel_hi:[1,1,1] neg_lo:[1,0,0] neg_hi:[1,0,0]
	v_pk_fma_f32 v[10:11], v[70:71], v[4:5], v[10:11] op_sel:[0,1,0] op_sel_hi:[1,1,1] neg_lo:[1,0,0] neg_hi:[1,0,0]
	ds_read_b128 v[68:71], v251 offset:2544
	s_waitcnt lgkmcnt(14)
	v_pk_fma_f32 v[12:13], v[72:73], v[4:5], v[12:13] op_sel:[0,1,0] op_sel_hi:[1,1,1] neg_lo:[1,0,0] neg_hi:[1,0,0]
	v_pk_fma_f32 v[14:15], v[74:75], v[4:5], v[14:15] op_sel:[0,1,0] op_sel_hi:[1,1,1] neg_lo:[1,0,0] neg_hi:[1,0,0]
	ds_read_b128 v[72:75], v251 offset:2576
	s_waitcnt lgkmcnt(14)
	v_pk_fma_f32 v[16:17], v[76:77], v[4:5], v[16:17] op_sel:[0,1,0] op_sel_hi:[1,1,1] neg_lo:[1,0,0] neg_hi:[1,0,0]
	v_pk_fma_f32 v[18:19], v[78:79], v[4:5], v[18:19] op_sel:[0,1,0] op_sel_hi:[1,1,1] neg_lo:[1,0,0] neg_hi:[1,0,0]
	ds_read_b128 v[76:79], v251 offset:2592
	s_waitcnt lgkmcnt(14)
	v_pk_fma_f32 v[20:21], v[80:81], v[4:5], v[20:21] op_sel:[0,1,0] op_sel_hi:[1,1,1] neg_lo:[1,0,0] neg_hi:[1,0,0]
	v_pk_fma_f32 v[22:23], v[82:83], v[4:5], v[22:23] op_sel:[0,1,0] op_sel_hi:[1,1,1] neg_lo:[1,0,0] neg_hi:[1,0,0]
	ds_read_b128 v[80:83], v251 offset:2608
	s_waitcnt lgkmcnt(14)
	v_pk_fma_f32 v[24:25], v[84:85], v[4:5], v[24:25] op_sel:[0,1,0] op_sel_hi:[1,1,1] neg_lo:[1,0,0] neg_hi:[1,0,0]
	v_pk_fma_f32 v[26:27], v[86:87], v[4:5], v[26:27] op_sel:[0,1,0] op_sel_hi:[1,1,1] neg_lo:[1,0,0] neg_hi:[1,0,0]
	ds_read_b128 v[84:87], v251 offset:2624
	s_waitcnt lgkmcnt(14)
	v_pk_fma_f32 v[28:29], v[88:89], v[4:5], v[28:29] op_sel:[0,1,0] op_sel_hi:[1,1,1] neg_lo:[1,0,0] neg_hi:[1,0,0]
	v_pk_fma_f32 v[30:31], v[90:91], v[4:5], v[30:31] op_sel:[0,1,0] op_sel_hi:[1,1,1] neg_lo:[1,0,0] neg_hi:[1,0,0]
	ds_read_b128 v[88:91], v251 offset:2640
	s_waitcnt lgkmcnt(14)
	v_pk_fma_f32 v[32:33], v[92:93], v[4:5], v[32:33] op_sel:[0,1,0] op_sel_hi:[1,1,1] neg_lo:[1,0,0] neg_hi:[1,0,0]
	v_pk_fma_f32 v[34:35], v[94:95], v[4:5], v[34:35] op_sel:[0,1,0] op_sel_hi:[1,1,1] neg_lo:[1,0,0] neg_hi:[1,0,0]
	ds_read_b128 v[92:95], v251 offset:2656
	s_waitcnt lgkmcnt(14)
	v_pk_fma_f32 v[36:37], v[230:231], v[4:5], v[36:37] op_sel:[0,1,0] op_sel_hi:[1,1,1] neg_lo:[1,0,0] neg_hi:[1,0,0]
	v_pk_fma_f32 v[38:39], v[232:233], v[4:5], v[38:39] op_sel:[0,1,0] op_sel_hi:[1,1,1] neg_lo:[1,0,0] neg_hi:[1,0,0]
	ds_read_b128 v[230:233], v251 offset:2672
	s_waitcnt lgkmcnt(14)
	v_pk_fma_f32 v[40:41], v[234:235], v[4:5], v[40:41] op_sel:[0,1,0] op_sel_hi:[1,1,1] neg_lo:[1,0,0] neg_hi:[1,0,0]
	v_pk_fma_f32 v[42:43], v[236:237], v[4:5], v[42:43] op_sel:[0,1,0] op_sel_hi:[1,1,1] neg_lo:[1,0,0] neg_hi:[1,0,0]
	ds_read_b128 v[234:237], v251 offset:2688
	s_waitcnt lgkmcnt(14)
	v_pk_fma_f32 v[44:45], v[238:239], v[4:5], v[44:45] op_sel:[0,1,0] op_sel_hi:[1,1,1] neg_lo:[1,0,0] neg_hi:[1,0,0]
	v_pk_fma_f32 v[46:47], v[240:241], v[4:5], v[46:47] op_sel:[0,1,0] op_sel_hi:[1,1,1] neg_lo:[1,0,0] neg_hi:[1,0,0]
	ds_read_b128 v[238:241], v251 offset:2704
	s_waitcnt lgkmcnt(14)
	v_pk_fma_f32 v[48:49], v[242:243], v[4:5], v[48:49] op_sel:[0,1,0] op_sel_hi:[1,1,1] neg_lo:[1,0,0] neg_hi:[1,0,0]
	v_pk_fma_f32 v[50:51], v[244:245], v[4:5], v[50:51] op_sel:[0,1,0] op_sel_hi:[1,1,1] neg_lo:[1,0,0] neg_hi:[1,0,0]
	ds_read_b128 v[242:245], v251 offset:2720
	s_waitcnt lgkmcnt(14)
	v_pk_fma_f32 v[52:53], v[246:247], v[4:5], v[52:53] op_sel:[0,1,0] op_sel_hi:[1,1,1] neg_lo:[1,0,0] neg_hi:[1,0,0]
	v_pk_fma_f32 v[54:55], v[248:249], v[4:5], v[54:55] op_sel:[0,1,0] op_sel_hi:[1,1,1] neg_lo:[1,0,0] neg_hi:[1,0,0]
	ds_read_b128 v[246:249], v251 offset:2736
	s_waitcnt lgkmcnt(12)
	v_pk_fma_f32 v[56:57], v[64:65], v[4:5], v[56:57] op_sel:[0,1,0] op_sel_hi:[1,1,1] neg_lo:[1,0,0] neg_hi:[1,0,0]
	v_pk_fma_f32 v[58:59], v[66:67], v[4:5], v[58:59] op_sel:[0,1,0] op_sel_hi:[1,1,1] neg_lo:[1,0,0] neg_hi:[1,0,0]
	ds_read_b128 v[64:67], v251 offset:2752
	s_waitcnt lgkmcnt(12)
	v_pk_fma_f32 v[60:61], v[68:69], v[4:5], v[60:61] op_sel:[0,1,0] op_sel_hi:[1,1,1] neg_lo:[1,0,0] neg_hi:[1,0,0]
	v_pk_fma_f32 v[62:63], v[70:71], v[4:5], v[62:63] op_sel:[0,1,0] op_sel_hi:[1,1,1] neg_lo:[1,0,0] neg_hi:[1,0,0]
	ds_read_b128 v[68:71], v251 offset:2768
	v_pk_mul_f32 v[126:127], v[6:7], v[128:129] op_sel:[0,0] op_sel_hi:[0,1]
	s_nop 0
	v_cvt_pk_bf16_f32 v126, v126, v127
	s_nop 0
	ds_write_b16 v205, v126 offset:18272
	ds_write_b16_d16_hi v205, v126 offset:27488
	s_waitcnt lgkmcnt(14)
	v_fma_f32 v7, -v75, v6, v7
	ds_read_b128 v[72:75], v251 offset:2784
	s_waitcnt lgkmcnt(14)
	v_pk_fma_f32 v[8:9], v[76:77], v[6:7], v[8:9] op_sel:[0,0,0] op_sel_hi:[1,0,1] neg_lo:[1,0,0] neg_hi:[1,0,0]
	v_pk_fma_f32 v[10:11], v[78:79], v[6:7], v[10:11] op_sel:[0,0,0] op_sel_hi:[1,0,1] neg_lo:[1,0,0] neg_hi:[1,0,0]
	ds_read_b128 v[76:79], v251 offset:2800
	s_waitcnt lgkmcnt(14)
	v_pk_fma_f32 v[12:13], v[80:81], v[6:7], v[12:13] op_sel:[0,0,0] op_sel_hi:[1,0,1] neg_lo:[1,0,0] neg_hi:[1,0,0]
	v_pk_fma_f32 v[14:15], v[82:83], v[6:7], v[14:15] op_sel:[0,0,0] op_sel_hi:[1,0,1] neg_lo:[1,0,0] neg_hi:[1,0,0]
	ds_read_b128 v[80:83], v251 offset:2848
	s_waitcnt lgkmcnt(14)
; #define PG8_LAS __attribute__((address_space(3)))
; __device__ __forceinline__ bf16_t f2bf(float x) { return (bf16_t)(pk2(x, x) & 0xffffu); }
; __device__ __forceinline__ void solve64(float (&x)[64], const PG8_LAS float* sLt) {
;     ...
;     for (int j = 0; j < 63; ++j) {
;         const float xj = x[j];
; #pragma unroll
;         for (int i4 = (j + 1) / 4; i4 < 16; ++i4) {
;             if (4 * i4 + 0 > j) x[4 * i4 + 0] -= cur[i4][0] * xj;
;             if (4 * i4 + 1 > j) x[4 * i4 + 1] -= cur[i4][1] * xj;
;             if (4 * i4 + 2 > j) x[4 * i4 + 2] -= cur[i4][2] * xj;
;             if (4 * i4 + 3 > j) x[4 * i4 + 3] -= cur[i4][3] * xj;
;             if (j + 1 < 63 && i4 >= (j + 2) / 4) cur[i4] = *(const PG8_LAS f32x4*)(sLt + (j + 1) * 64 + 4 * i4); }
; __device__ __forceinline__ void phase_prep(const Args& a, PG8_LAS unsigned char* lds) {
;     ...
;             for (int i = 0; i < 64; ++i) { *(PG8_LAS bf16_t*)(Tu + (i * 72 + lane) * 2) = f2bf(x[i] * bj); *(PG8_LAS bf16_t*)(Tw + (i * 72 + lane) * 2) = f2bf(x[i] * bej); }
	v_pk_fma_f32 v[16:17], v[84:85], v[6:7], v[16:17] op_sel:[0,0,0] op_sel_hi:[1,0,1] neg_lo:[1,0,0] neg_hi:[1,0,0]
	v_pk_fma_f32 v[18:19], v[86:87], v[6:7], v[18:19] op_sel:[0,0,0] op_sel_hi:[1,0,1] neg_lo:[1,0,0] neg_hi:[1,0,0]
	ds_read_b128 v[84:87], v251 offset:2864
	s_waitcnt lgkmcnt(14)
	v_pk_fma_f32 v[20:21], v[88:89], v[6:7], v[20:21] op_sel:[0,0,0] op_sel_hi:[1,0,1] neg_lo:[1,0,0] neg_hi:[1,0,0]
	v_pk_fma_f32 v[22:23], v[90:91], v[6:7], v[22:23] op_sel:[0,0,0] op_sel_hi:[1,0,1] neg_lo:[1,0,0] neg_hi:[1,0,0]
	ds_read_b128 v[88:91], v251 offset:2880
	s_waitcnt lgkmcnt(14)
	v_pk_fma_f32 v[24:25], v[92:93], v[6:7], v[24:25] op_sel:[0,0,0] op_sel_hi:[1,0,1] neg_lo:[1,0,0] neg_hi:[1,0,0]
	v_pk_fma_f32 v[26:27], v[94:95], v[6:7], v[26:27] op_sel:[0,0,0] op_sel_hi:[1,0,1] neg_lo:[1,0,0] neg_hi:[1,0,0]
	ds_read_b128 v[92:95], v251 offset:2896
	s_waitcnt lgkmcnt(14)
	v_pk_fma_f32 v[28:29], v[230:231], v[6:7], v[28:29] op_sel:[0,0,0] op_sel_hi:[1,0,1] neg_lo:[1,0,0] neg_hi:[1,0,0]
	v_pk_fma_f32 v[30:31], v[232:233], v[6:7], v[30:31] op_sel:[0,0,0] op_sel_hi:[1,0,1] neg_lo:[1,0,0] neg_hi:[1,0,0]
	ds_read_b128 v[230:233], v251 offset:2912
	s_waitcnt lgkmcnt(14)
	v_pk_fma_f32 v[32:33], v[234:235], v[6:7], v[32:33] op_sel:[0,0,0] op_sel_hi:[1,0,1] neg_lo:[1,0,0] neg_hi:[1,0,0]
	v_pk_fma_f32 v[34:35], v[236:237], v[6:7], v[34:35] op_sel:[0,0,0] op_sel_hi:[1,0,1] neg_lo:[1,0,0] neg_hi:[1,0,0]
	ds_read_b128 v[234:237], v251 offset:2928
	s_waitcnt lgkmcnt(14)
	v_pk_fma_f32 v[36:37], v[238:239], v[6:7], v[36:37] op_sel:[0,0,0] op_sel_hi:[1,0,1] neg_lo:[1,0,0] neg_hi:[1,0,0]
	v_pk_fma_f32 v[38:39], v[240:241], v[6:7], v[38:39] op_sel:[0,0,0] op_sel_hi:[1,0,1] neg_lo:[1,0,0] neg_hi:[1,0,0]
	ds_read_b128 v[238:241], v251 offset:2944
	s_waitcnt lgkmcnt(14)
	v_pk_fma_f32 v[40:41], v[242:243], v[6:7], v[40:41] op_sel:[0,0,0] op_sel_hi:[1,0,1] neg_lo:[1,0,0] neg_hi:[1,0,0]
	v_pk_fma_f32 v[42:43], v[244:245], v[6:7], v[42:43] op_sel:[0,0,0] op_sel_hi:[1,0,1] neg_lo:[1,0,0] neg_hi:[1,0,0]
	ds_read_b128 v[242:245], v251 offset:2960
	s_waitcnt lgkmcnt(14)
	v_pk_fma_f32 v[44:45], v[246:247], v[6:7], v[44:45] op_sel:[0,0,0] op_sel_hi:[1,0,1] neg_lo:[1,0,0] neg_hi:[1,0,0]
	v_pk_fma_f32 v[46:47], v[248:249], v[6:7], v[46:47] op_sel:[0,0,0] op_sel_hi:[1,0,1] neg_lo:[1,0,0] neg_hi:[1,0,0]
	ds_read_b128 v[246:249], v251 offset:2976
	s_waitcnt lgkmcnt(14)
	v_pk_fma_f32 v[48:49], v[64:65], v[6:7], v[48:49] op_sel:[0,0,0] op_sel_hi:[1,0,1] neg_lo:[1,0,0] neg_hi:[1,0,0]
	v_pk_fma_f32 v[50:51], v[66:67], v[6:7], v[50:51] op_sel:[0,0,0] op_sel_hi:[1,0,1] neg_lo:[1,0,0] neg_hi:[1,0,0]
	ds_read_b128 v[64:67], v251 offset:2992
	s_waitcnt lgkmcnt(14)
	v_pk_fma_f32 v[52:53], v[68:69], v[6:7], v[52:53] op_sel:[0,0,0] op_sel_hi:[1,0,1] neg_lo:[1,0,0] neg_hi:[1,0,0]
	v_pk_fma_f32 v[54:55], v[70:71], v[6:7], v[54:55] op_sel:[0,0,0] op_sel_hi:[1,0,1] neg_lo:[1,0,0] neg_hi:[1,0,0]
	ds_read_b128 v[68:71], v251 offset:3008
	s_waitcnt lgkmcnt(12)
	v_pk_fma_f32 v[56:57], v[72:73], v[6:7], v[56:57] op_sel:[0,0,0] op_sel_hi:[1,0,1] neg_lo:[1,0,0] neg_hi:[1,0,0]
	v_pk_fma_f32 v[58:59], v[74:75], v[6:7], v[58:59] op_sel:[0,0,0] op_sel_hi:[1,0,1] neg_lo:[1,0,0] neg_hi:[1,0,0]
	ds_read_b128 v[72:75], v251 offset:3024
	s_waitcnt lgkmcnt(12)
	v_pk_fma_f32 v[60:61], v[76:77], v[6:7], v[60:61] op_sel:[0,0,0] op_sel_hi:[1,0,1] neg_lo:[1,0,0] neg_hi:[1,0,0]
	v_pk_fma_f32 v[62:63], v[78:79], v[6:7], v[62:63] op_sel:[0,0,0] op_sel_hi:[1,0,1] neg_lo:[1,0,0] neg_hi:[1,0,0]
	ds_read_b128 v[76:79], v251 offset:3040
	v_pk_mul_f32 v[126:127], v[6:7], v[128:129] op_sel:[1,0] op_sel_hi:[1,1]
	s_nop 0
	v_cvt_pk_bf16_f32 v126, v126, v127
	s_nop 0
	ds_write_b16 v205, v126 offset:18416
	ds_write_b16_d16_hi v205, v126 offset:27632
	s_waitcnt lgkmcnt(14)
	v_pk_fma_f32 v[8:9], v[80:81], v[6:7], v[8:9] op_sel:[0,1,0] op_sel_hi:[1,1,1] neg_lo:[1,0,0] neg_hi:[1,0,0]
	v_pk_fma_f32 v[10:11], v[82:83], v[6:7], v[10:11] op_sel:[0,1,0] op_sel_hi:[1,1,1] neg_lo:[1,0,0] neg_hi:[1,0,0]
	ds_read_b128 v[80:83], v251 offset:3056
	s_waitcnt lgkmcnt(14)
	v_pk_fma_f32 v[12:13], v[84:85], v[6:7], v[12:13] op_sel:[0,1,0] op_sel_hi:[1,1,1] neg_lo:[1,0,0] neg_hi:[1,0,0]
	v_pk_fma_f32 v[14:15], v[86:87], v[6:7], v[14:15] op_sel:[0,1,0] op_sel_hi:[1,1,1] neg_lo:[1,0,0] neg_hi:[1,0,0]
	ds_read_b128 v[84:87], v251 offset:3104
	s_waitcnt lgkmcnt(14)
	v_pk_fma_f32 v[16:17], v[88:89], v[6:7], v[16:17] op_sel:[0,1,0] op_sel_hi:[1,1,1] neg_lo:[1,0,0] neg_hi:[1,0,0]
	v_pk_fma_f32 v[18:19], v[90:91], v[6:7], v[18:19] op_sel:[0,1,0] op_sel_hi:[1,1,1] neg_lo:[1,0,0] neg_hi:[1,0,0]
	ds_read_b128 v[88:91], v251 offset:3120
	s_waitcnt lgkmcnt(14)
	v_pk_fma_f32 v[20:21], v[92:93], v[6:7], v[20:21] op_sel:[0,1,0] op_sel_hi:[1,1,1] neg_lo:[1,0,0] neg_hi:[1,0,0]
	v_pk_fma_f32 v[22:23], v[94:95], v[6:7], v[22:23] op_sel:[0,1,0] op_sel_hi:[1,1,1] neg_lo:[1,0,0] neg_hi:[1,0,0]
	ds_read_b128 v[92:95], v251 offset:3136
	s_waitcnt lgkmcnt(14)
	v_pk_fma_f32 v[24:25], v[230:231], v[6:7], v[24:25] op_sel:[0,1,0] op_sel_hi:[1,1,1] neg_lo:[1,0,0] neg_hi:[1,0,0]
	v_pk_fma_f32 v[26:27], v[232:233], v[6:7], v[26:27] op_sel:[0,1,0] op_sel_hi:[1,1,1] neg_lo:[1,0,0] neg_hi:[1,0,0]
	ds_read_b128 v[230:233], v251 offset:3152
	s_waitcnt lgkmcnt(14)
	v_pk_fma_f32 v[28:29], v[234:235], v[6:7], v[28:29] op_sel:[0,1,0] op_sel_hi:[1,1,1] neg_lo:[1,0,0] neg_hi:[1,0,0]
	v_pk_fma_f32 v[30:31], v[236:237], v[6:7], v[30:31] op_sel:[0,1,0] op_sel_hi:[1,1,1] neg_lo:[1,0,0] neg_hi:[1,0,0]
	ds_read_b128 v[234:237], v251 offset:3168
	s_waitcnt lgkmcnt(14)
; #define PG8_LAS __attribute__((address_space(3)))
; __device__ __forceinline__ bf16_t f2bf(float x) { return (bf16_t)(pk2(x, x) & 0xffffu); }
; __device__ __forceinline__ void solve64(float (&x)[64], const PG8_LAS float* sLt) {
;     ...
;     for (int j = 0; j < 63; ++j) {
;         const float xj = x[j];
; #pragma unroll
;         for (int i4 = (j + 1) / 4; i4 < 16; ++i4) {
;             if (4 * i4 + 0 > j) x[4 * i4 + 0] -= cur[i4][0] * xj;
;             if (4 * i4 + 1 > j) x[4 * i4 + 1] -= cur[i4][1] * xj;
;             if (4 * i4 + 2 > j) x[4 * i4 + 2] -= cur[i4][2] * xj;
;             if (4 * i4 + 3 > j) x[4 * i4 + 3] -= cur[i4][3] * xj;
;             if (j + 1 < 63 && i4 >= (j + 2) / 4) cur[i4] = *(const PG8_LAS f32x4*)(sLt + (j + 1) * 64 + 4 * i4); }
; __device__ __forceinline__ void phase_prep(const Args& a, PG8_LAS unsigned char* lds) {
;     ...
;             for (int i = 0; i < 64; ++i) { *(PG8_LAS bf16_t*)(Tu + (i * 72 + lane) * 2) = f2bf(x[i] * bj); *(PG8_LAS bf16_t*)(Tw + (i * 72 + lane) * 2) = f2bf(x[i] * bej); }
	v_pk_fma_f32 v[32:33], v[238:239], v[6:7], v[32:33] op_sel:[0,1,0] op_sel_hi:[1,1,1] neg_lo:[1,0,0] neg_hi:[1,0,0]
	v_pk_fma_f32 v[34:35], v[240:241], v[6:7], v[34:35] op_sel:[0,1,0] op_sel_hi:[1,1,1] neg_lo:[1,0,0] neg_hi:[1,0,0]
	ds_read_b128 v[238:241], v251 offset:3184
	s_waitcnt lgkmcnt(14)
	v_pk_fma_f32 v[36:37], v[242:243], v[6:7], v[36:37] op_sel:[0,1,0] op_sel_hi:[1,1,1] neg_lo:[1,0,0] neg_hi:[1,0,0]
	v_pk_fma_f32 v[38:39], v[244:245], v[6:7], v[38:39] op_sel:[0,1,0] op_sel_hi:[1,1,1] neg_lo:[1,0,0] neg_hi:[1,0,0]
	ds_read_b128 v[242:245], v251 offset:3200
	s_waitcnt lgkmcnt(14)
	v_pk_fma_f32 v[40:41], v[246:247], v[6:7], v[40:41] op_sel:[0,1,0] op_sel_hi:[1,1,1] neg_lo:[1,0,0] neg_hi:[1,0,0]
	v_pk_fma_f32 v[42:43], v[248:249], v[6:7], v[42:43] op_sel:[0,1,0] op_sel_hi:[1,1,1] neg_lo:[1,0,0] neg_hi:[1,0,0]
	ds_read_b128 v[246:249], v251 offset:3216
	s_waitcnt lgkmcnt(14)
	v_pk_fma_f32 v[44:45], v[64:65], v[6:7], v[44:45] op_sel:[0,1,0] op_sel_hi:[1,1,1] neg_lo:[1,0,0] neg_hi:[1,0,0]
	v_pk_fma_f32 v[46:47], v[66:67], v[6:7], v[46:47] op_sel:[0,1,0] op_sel_hi:[1,1,1] neg_lo:[1,0,0] neg_hi:[1,0,0]
	ds_read_b128 v[64:67], v251 offset:3232
	s_waitcnt lgkmcnt(14)
	v_pk_fma_f32 v[48:49], v[68:69], v[6:7], v[48:49] op_sel:[0,1,0] op_sel_hi:[1,1,1] neg_lo:[1,0,0] neg_hi:[1,0,0]
	v_pk_fma_f32 v[50:51], v[70:71], v[6:7], v[50:51] op_sel:[0,1,0] op_sel_hi:[1,1,1] neg_lo:[1,0,0] neg_hi:[1,0,0]
	ds_read_b128 v[68:71], v251 offset:3248
	s_waitcnt lgkmcnt(14)
	v_pk_fma_f32 v[52:53], v[72:73], v[6:7], v[52:53] op_sel:[0,1,0] op_sel_hi:[1,1,1] neg_lo:[1,0,0] neg_hi:[1,0,0]
	v_pk_fma_f32 v[54:55], v[74:75], v[6:7], v[54:55] op_sel:[0,1,0] op_sel_hi:[1,1,1] neg_lo:[1,0,0] neg_hi:[1,0,0]
	ds_read_b128 v[72:75], v251 offset:3264
	s_waitcnt lgkmcnt(14)
	v_pk_fma_f32 v[56:57], v[76:77], v[6:7], v[56:57] op_sel:[0,1,0] op_sel_hi:[1,1,1] neg_lo:[1,0,0] neg_hi:[1,0,0]
	v_pk_fma_f32 v[58:59], v[78:79], v[6:7], v[58:59] op_sel:[0,1,0] op_sel_hi:[1,1,1] neg_lo:[1,0,0] neg_hi:[1,0,0]
	ds_read_b128 v[76:79], v251 offset:3280
	s_waitcnt lgkmcnt(12)
	v_pk_fma_f32 v[60:61], v[80:81], v[6:7], v[60:61] op_sel:[0,1,0] op_sel_hi:[1,1,1] neg_lo:[1,0,0] neg_hi:[1,0,0]
	v_pk_fma_f32 v[62:63], v[82:83], v[6:7], v[62:63] op_sel:[0,1,0] op_sel_hi:[1,1,1] neg_lo:[1,0,0] neg_hi:[1,0,0]
	ds_read_b128 v[80:83], v251 offset:3296
	v_pk_mul_f32 v[126:127], v[8:9], v[128:129] op_sel:[0,0] op_sel_hi:[0,1]
	s_nop 0
	v_cvt_pk_bf16_f32 v126, v126, v127
	s_nop 0
	ds_write_b16 v205, v126 offset:18560
	ds_write_b16_d16_hi v205, v126 offset:27776
	s_waitcnt lgkmcnt(14)
	v_fma_f32 v9, -v85, v8, v9
	v_pk_fma_f32 v[10:11], v[86:87], v[8:9], v[10:11] op_sel:[0,0,0] op_sel_hi:[1,0,1] neg_lo:[1,0,0] neg_hi:[1,0,0]
	ds_read_b128 v[84:87], v251 offset:3312
	s_waitcnt lgkmcnt(14)
	v_pk_fma_f32 v[12:13], v[88:89], v[8:9], v[12:13] op_sel:[0,0,0] op_sel_hi:[1,0,1] neg_lo:[1,0,0] neg_hi:[1,0,0]
	v_pk_fma_f32 v[14:15], v[90:91], v[8:9], v[14:15] op_sel:[0,0,0] op_sel_hi:[1,0,1] neg_lo:[1,0,0] neg_hi:[1,0,0]
	ds_read_b128 v[88:91], v251 offset:3360
	s_waitcnt lgkmcnt(14)
	v_pk_fma_f32 v[16:17], v[92:93], v[8:9], v[16:17] op_sel:[0,0,0] op_sel_hi:[1,0,1] neg_lo:[1,0,0] neg_hi:[1,0,0]
	v_pk_fma_f32 v[18:19], v[94:95], v[8:9], v[18:19] op_sel:[0,0,0] op_sel_hi:[1,0,1] neg_lo:[1,0,0] neg_hi:[1,0,0]
	ds_read_b128 v[92:95], v251 offset:3376
	s_waitcnt lgkmcnt(14)
	v_pk_fma_f32 v[20:21], v[230:231], v[8:9], v[20:21] op_sel:[0,0,0] op_sel_hi:[1,0,1] neg_lo:[1,0,0] neg_hi:[1,0,0]
	v_pk_fma_f32 v[22:23], v[232:233], v[8:9], v[22:23] op_sel:[0,0,0] op_sel_hi:[1,0,1] neg_lo:[1,0,0] neg_hi:[1,0,0]
	ds_read_b128 v[230:233], v251 offset:3392
	s_waitcnt lgkmcnt(14)
	v_pk_fma_f32 v[24:25], v[234:235], v[8:9], v[24:25] op_sel:[0,0,0] op_sel_hi:[1,0,1] neg_lo:[1,0,0] neg_hi:[1,0,0]
	v_pk_fma_f32 v[26:27], v[236:237], v[8:9], v[26:27] op_sel:[0,0,0] op_sel_hi:[1,0,1] neg_lo:[1,0,0] neg_hi:[1,0,0]
	ds_read_b128 v[234:237], v251 offset:3408
	s_waitcnt lgkmcnt(14)
	v_pk_fma_f32 v[28:29], v[238:239], v[8:9], v[28:29] op_sel:[0,0,0] op_sel_hi:[1,0,1] neg_lo:[1,0,0] neg_hi:[1,0,0]
	v_pk_fma_f32 v[30:31], v[240:241], v[8:9], v[30:31] op_sel:[0,0,0] op_sel_hi:[1,0,1] neg_lo:[1,0,0] neg_hi:[1,0,0]
	ds_read_b128 v[238:241], v251 offset:3424
	s_waitcnt lgkmcnt(14)
	v_pk_fma_f32 v[32:33], v[242:243], v[8:9], v[32:33] op_sel:[0,0,0] op_sel_hi:[1,0,1] neg_lo:[1,0,0] neg_hi:[1,0,0]
	v_pk_fma_f32 v[34:35], v[244:245], v[8:9], v[34:35] op_sel:[0,0,0] op_sel_hi:[1,0,1] neg_lo:[1,0,0] neg_hi:[1,0,0]
	ds_read_b128 v[242:245], v251 offset:3440
	s_waitcnt lgkmcnt(14)
	v_pk_fma_f32 v[36:37], v[246:247], v[8:9], v[36:37] op_sel:[0,0,0] op_sel_hi:[1,0,1] neg_lo:[1,0,0] neg_hi:[1,0,0]
	v_pk_fma_f32 v[38:39], v[248:249], v[8:9], v[38:39] op_sel:[0,0,0] op_sel_hi:[1,0,1] neg_lo:[1,0,0] neg_hi:[1,0,0]
	ds_read_b128 v[246:249], v251 offset:3456
	s_waitcnt lgkmcnt(14)
	v_pk_fma_f32 v[40:41], v[64:65], v[8:9], v[40:41] op_sel:[0,0,0] op_sel_hi:[1,0,1] neg_lo:[1,0,0] neg_hi:[1,0,0]
	v_pk_fma_f32 v[42:43], v[66:67], v[8:9], v[42:43] op_sel:[0,0,0] op_sel_hi:[1,0,1] neg_lo:[1,0,0] neg_hi:[1,0,0]
	ds_read_b128 v[64:67], v251 offset:3472
	s_waitcnt lgkmcnt(14)
	v_pk_fma_f32 v[44:45], v[68:69], v[8:9], v[44:45] op_sel:[0,0,0] op_sel_hi:[1,0,1] neg_lo:[1,0,0] neg_hi:[1,0,0]
	v_pk_fma_f32 v[46:47], v[70:71], v[8:9], v[46:47] op_sel:[0,0,0] op_sel_hi:[1,0,1] neg_lo:[1,0,0] neg_hi:[1,0,0]
	ds_read_b128 v[68:71], v251 offset:3488
	s_waitcnt lgkmcnt(14)
	v_pk_fma_f32 v[48:49], v[72:73], v[8:9], v[48:49] op_sel:[0,0,0] op_sel_hi:[1,0,1] neg_lo:[1,0,0] neg_hi:[1,0,0]
	v_pk_fma_f32 v[50:51], v[74:75], v[8:9], v[50:51] op_sel:[0,0,0] op_sel_hi:[1,0,1] neg_lo:[1,0,0] neg_hi:[1,0,0]
	ds_read_b128 v[72:75], v251 offset:3504
	s_waitcnt lgkmcnt(14)
; #define PG8_LAS __attribute__((address_space(3)))
; __device__ __forceinline__ bf16_t f2bf(float x) { return (bf16_t)(pk2(x, x) & 0xffffu); }
; __device__ __forceinline__ void solve64(float (&x)[64], const PG8_LAS float* sLt) {
;     ...
;     for (int j = 0; j < 63; ++j) {
;         const float xj = x[j];
; #pragma unroll
;         for (int i4 = (j + 1) / 4; i4 < 16; ++i4) {
;             if (4 * i4 + 0 > j) x[4 * i4 + 0] -= cur[i4][0] * xj;
;             if (4 * i4 + 1 > j) x[4 * i4 + 1] -= cur[i4][1] * xj;
;             if (4 * i4 + 2 > j) x[4 * i4 + 2] -= cur[i4][2] * xj;
;             if (4 * i4 + 3 > j) x[4 * i4 + 3] -= cur[i4][3] * xj;
;             if (j + 1 < 63 && i4 >= (j + 2) / 4) cur[i4] = *(const PG8_LAS f32x4*)(sLt + (j + 1) * 64 + 4 * i4); }
; __device__ __forceinline__ void phase_prep(const Args& a, PG8_LAS unsigned char* lds) {
;     ...
;             for (int i = 0; i < 64; ++i) { *(PG8_LAS bf16_t*)(Tu + (i * 72 + lane) * 2) = f2bf(x[i] * bj); *(PG8_LAS bf16_t*)(Tw + (i * 72 + lane) * 2) = f2bf(x[i] * bej); }
	v_pk_fma_f32 v[52:53], v[76:77], v[8:9], v[52:53] op_sel:[0,0,0] op_sel_hi:[1,0,1] neg_lo:[1,0,0] neg_hi:[1,0,0]
	v_pk_fma_f32 v[54:55], v[78:79], v[8:9], v[54:55] op_sel:[0,0,0] op_sel_hi:[1,0,1] neg_lo:[1,0,0] neg_hi:[1,0,0]
	ds_read_b128 v[76:79], v251 offset:3520
	s_waitcnt lgkmcnt(14)
	v_pk_fma_f32 v[56:57], v[80:81], v[8:9], v[56:57] op_sel:[0,0,0] op_sel_hi:[1,0,1] neg_lo:[1,0,0] neg_hi:[1,0,0]
	v_pk_fma_f32 v[58:59], v[82:83], v[8:9], v[58:59] op_sel:[0,0,0] op_sel_hi:[1,0,1] neg_lo:[1,0,0] neg_hi:[1,0,0]
	ds_read_b128 v[80:83], v251 offset:3536
	s_waitcnt lgkmcnt(12)
	v_pk_fma_f32 v[60:61], v[84:85], v[8:9], v[60:61] op_sel:[0,0,0] op_sel_hi:[1,0,1] neg_lo:[1,0,0] neg_hi:[1,0,0]
	v_pk_fma_f32 v[62:63], v[86:87], v[8:9], v[62:63] op_sel:[0,0,0] op_sel_hi:[1,0,1] neg_lo:[1,0,0] neg_hi:[1,0,0]
	ds_read_b128 v[84:87], v251 offset:3552
	v_pk_mul_f32 v[126:127], v[8:9], v[128:129] op_sel:[1,0] op_sel_hi:[1,1]
	s_nop 0
	v_cvt_pk_bf16_f32 v126, v126, v127
	s_nop 0
	ds_write_b16 v205, v126 offset:18704
	ds_write_b16_d16_hi v205, v126 offset:27920
	s_waitcnt lgkmcnt(14)
	v_pk_fma_f32 v[10:11], v[90:91], v[8:9], v[10:11] op_sel:[0,1,0] op_sel_hi:[1,1,1] neg_lo:[1,0,0] neg_hi:[1,0,0]
	ds_read_b128 v[88:91], v251 offset:3568
	s_waitcnt lgkmcnt(14)
	v_pk_fma_f32 v[12:13], v[92:93], v[8:9], v[12:13] op_sel:[0,1,0] op_sel_hi:[1,1,1] neg_lo:[1,0,0] neg_hi:[1,0,0]
	v_pk_fma_f32 v[14:15], v[94:95], v[8:9], v[14:15] op_sel:[0,1,0] op_sel_hi:[1,1,1] neg_lo:[1,0,0] neg_hi:[1,0,0]
	ds_read_b128 v[92:95], v251 offset:3616
	s_waitcnt lgkmcnt(14)
	v_pk_fma_f32 v[16:17], v[230:231], v[8:9], v[16:17] op_sel:[0,1,0] op_sel_hi:[1,1,1] neg_lo:[1,0,0] neg_hi:[1,0,0]
	v_pk_fma_f32 v[18:19], v[232:233], v[8:9], v[18:19] op_sel:[0,1,0] op_sel_hi:[1,1,1] neg_lo:[1,0,0] neg_hi:[1,0,0]
	ds_read_b128 v[230:233], v251 offset:3632
	s_waitcnt lgkmcnt(14)
	v_pk_fma_f32 v[20:21], v[234:235], v[8:9], v[20:21] op_sel:[0,1,0] op_sel_hi:[1,1,1] neg_lo:[1,0,0] neg_hi:[1,0,0]
	v_pk_fma_f32 v[22:23], v[236:237], v[8:9], v[22:23] op_sel:[0,1,0] op_sel_hi:[1,1,1] neg_lo:[1,0,0] neg_hi:[1,0,0]
	ds_read_b128 v[234:237], v251 offset:3648
	s_waitcnt lgkmcnt(14)
	v_pk_fma_f32 v[24:25], v[238:239], v[8:9], v[24:25] op_sel:[0,1,0] op_sel_hi:[1,1,1] neg_lo:[1,0,0] neg_hi:[1,0,0]
	v_pk_fma_f32 v[26:27], v[240:241], v[8:9], v[26:27] op_sel:[0,1,0] op_sel_hi:[1,1,1] neg_lo:[1,0,0] neg_hi:[1,0,0]
	ds_read_b128 v[238:241], v251 offset:3664
	s_waitcnt lgkmcnt(14)
	v_pk_fma_f32 v[28:29], v[242:243], v[8:9], v[28:29] op_sel:[0,1,0] op_sel_hi:[1,1,1] neg_lo:[1,0,0] neg_hi:[1,0,0]
	v_pk_fma_f32 v[30:31], v[244:245], v[8:9], v[30:31] op_sel:[0,1,0] op_sel_hi:[1,1,1] neg_lo:[1,0,0] neg_hi:[1,0,0]
	ds_read_b128 v[242:245], v251 offset:3680
	s_waitcnt lgkmcnt(14)
	v_pk_fma_f32 v[32:33], v[246:247], v[8:9], v[32:33] op_sel:[0,1,0] op_sel_hi:[1,1,1] neg_lo:[1,0,0] neg_hi:[1,0,0]
	v_pk_fma_f32 v[34:35], v[248:249], v[8:9], v[34:35] op_sel:[0,1,0] op_sel_hi:[1,1,1] neg_lo:[1,0,0] neg_hi:[1,0,0]
	ds_read_b128 v[246:249], v251 offset:3696
	s_waitcnt lgkmcnt(14)
	v_pk_fma_f32 v[36:37], v[64:65], v[8:9], v[36:37] op_sel:[0,1,0] op_sel_hi:[1,1,1] neg_lo:[1,0,0] neg_hi:[1,0,0]
	v_pk_fma_f32 v[38:39], v[66:67], v[8:9], v[38:39] op_sel:[0,1,0] op_sel_hi:[1,1,1] neg_lo:[1,0,0] neg_hi:[1,0,0]
	ds_read_b128 v[64:67], v251 offset:3712
	s_waitcnt lgkmcnt(14)
	v_pk_fma_f32 v[40:41], v[68:69], v[8:9], v[40:41] op_sel:[0,1,0] op_sel_hi:[1,1,1] neg_lo:[1,0,0] neg_hi:[1,0,0]
	v_pk_fma_f32 v[42:43], v[70:71], v[8:9], v[42:43] op_sel:[0,1,0] op_sel_hi:[1,1,1] neg_lo:[1,0,0] neg_hi:[1,0,0]
	ds_read_b128 v[68:71], v251 offset:3728
	s_waitcnt lgkmcnt(14)
	v_pk_fma_f32 v[44:45], v[72:73], v[8:9], v[44:45] op_sel:[0,1,0] op_sel_hi:[1,1,1] neg_lo:[1,0,0] neg_hi:[1,0,0]
	v_pk_fma_f32 v[46:47], v[74:75], v[8:9], v[46:47] op_sel:[0,1,0] op_sel_hi:[1,1,1] neg_lo:[1,0,0] neg_hi:[1,0,0]
	ds_read_b128 v[72:75], v251 offset:3744
	s_waitcnt lgkmcnt(14)
	v_pk_fma_f32 v[48:49], v[76:77], v[8:9], v[48:49] op_sel:[0,1,0] op_sel_hi:[1,1,1] neg_lo:[1,0,0] neg_hi:[1,0,0]
	v_pk_fma_f32 v[50:51], v[78:79], v[8:9], v[50:51] op_sel:[0,1,0] op_sel_hi:[1,1,1] neg_lo:[1,0,0] neg_hi:[1,0,0]
	ds_read_b128 v[76:79], v251 offset:3760
	s_waitcnt lgkmcnt(14)
	v_pk_fma_f32 v[52:53], v[80:81], v[8:9], v[52:53] op_sel:[0,1,0] op_sel_hi:[1,1,1] neg_lo:[1,0,0] neg_hi:[1,0,0]
	v_pk_fma_f32 v[54:55], v[82:83], v[8:9], v[54:55] op_sel:[0,1,0] op_sel_hi:[1,1,1] neg_lo:[1,0,0] neg_hi:[1,0,0]
	ds_read_b128 v[80:83], v251 offset:3776
	s_waitcnt lgkmcnt(14)
	v_pk_fma_f32 v[56:57], v[84:85], v[8:9], v[56:57] op_sel:[0,1,0] op_sel_hi:[1,1,1] neg_lo:[1,0,0] neg_hi:[1,0,0]
	v_pk_fma_f32 v[58:59], v[86:87], v[8:9], v[58:59] op_sel:[0,1,0] op_sel_hi:[1,1,1] neg_lo:[1,0,0] neg_hi:[1,0,0]
	ds_read_b128 v[84:87], v251 offset:3792
	s_waitcnt lgkmcnt(12)
	v_pk_fma_f32 v[60:61], v[88:89], v[8:9], v[60:61] op_sel:[0,1,0] op_sel_hi:[1,1,1] neg_lo:[1,0,0] neg_hi:[1,0,0]
	v_pk_fma_f32 v[62:63], v[90:91], v[8:9], v[62:63] op_sel:[0,1,0] op_sel_hi:[1,1,1] neg_lo:[1,0,0] neg_hi:[1,0,0]
	ds_read_b128 v[88:91], v251 offset:3808
	v_pk_mul_f32 v[126:127], v[10:11], v[128:129] op_sel:[0,0] op_sel_hi:[0,1]
	s_nop 0
	v_cvt_pk_bf16_f32 v126, v126, v127
	s_nop 0
	ds_write_b16 v205, v126 offset:18848
	ds_write_b16_d16_hi v205, v126 offset:28064
	s_waitcnt lgkmcnt(14)
	v_fma_f32 v11, -v95, v10, v11
	ds_read_b128 v[92:95], v251 offset:3824
	s_waitcnt lgkmcnt(14)
	v_pk_fma_f32 v[12:13], v[230:231], v[10:11], v[12:13] op_sel:[0,0,0] op_sel_hi:[1,0,1] neg_lo:[1,0,0] neg_hi:[1,0,0]
	v_pk_fma_f32 v[14:15], v[232:233], v[10:11], v[14:15] op_sel:[0,0,0] op_sel_hi:[1,0,1] neg_lo:[1,0,0] neg_hi:[1,0,0]
	ds_read_b128 v[230:233], v251 offset:3888
	s_waitcnt lgkmcnt(14)
; #define PG8_LAS __attribute__((address_space(3)))
; __device__ __forceinline__ bf16_t f2bf(float x) { return (bf16_t)(pk2(x, x) & 0xffffu); }
; __device__ __forceinline__ void solve64(float (&x)[64], const PG8_LAS float* sLt) {
;     f32x4 cur[16];
; #pragma unroll
;     for (int i4 = 0; i4 < 16; ++i4) cur[i4] = *(const PG8_LAS f32x4*)(sLt + 4 * i4);
;     asm volatile("" ::: "memory");
; #pragma unroll
;     for (int j = 0; j < 63; ++j) {
;         const float xj = x[j];
; #pragma unroll
;         for (int i4 = (j + 1) / 4; i4 < 16; ++i4) {
;             if (4 * i4 + 0 > j) x[4 * i4 + 0] -= cur[i4][0] * xj;
;             if (4 * i4 + 1 > j) x[4 * i4 + 1] -= cur[i4][1] * xj;
;             if (4 * i4 + 2 > j) x[4 * i4 + 2] -= cur[i4][2] * xj;
;             if (4 * i4 + 3 > j) x[4 * i4 + 3] -= cur[i4][3] * xj;
;             if (j + 1 < 63 && i4 >= (j + 2) / 4) cur[i4] = *(const PG8_LAS f32x4*)(sLt + (j + 1) * 64 + 4 * i4); }
;         asm volatile("" ::: "memory");
;     }
; }
; __device__ __forceinline__ void phase_prep(const Args& a, PG8_LAS unsigned char* lds) {
;     ...
;             const float bj = sB[lane], bej = bj * sE[lane];
; #pragma unroll
;             for (int i = 0; i < 64; ++i) { *(PG8_LAS bf16_t*)(Tu + (i * 72 + lane) * 2) = f2bf(x[i] * bj); *(PG8_LAS bf16_t*)(Tw + (i * 72 + lane) * 2) = f2bf(x[i] * bej); }
	v_pk_fma_f32 v[16:17], v[234:235], v[10:11], v[16:17] op_sel:[0,0,0] op_sel_hi:[1,0,1] neg_lo:[1,0,0] neg_hi:[1,0,0]
	v_pk_fma_f32 v[18:19], v[236:237], v[10:11], v[18:19] op_sel:[0,0,0] op_sel_hi:[1,0,1] neg_lo:[1,0,0] neg_hi:[1,0,0]
	ds_read_b128 v[234:237], v251 offset:3904
	s_waitcnt lgkmcnt(14)
	v_pk_fma_f32 v[20:21], v[238:239], v[10:11], v[20:21] op_sel:[0,0,0] op_sel_hi:[1,0,1] neg_lo:[1,0,0] neg_hi:[1,0,0]
	v_pk_fma_f32 v[22:23], v[240:241], v[10:11], v[22:23] op_sel:[0,0,0] op_sel_hi:[1,0,1] neg_lo:[1,0,0] neg_hi:[1,0,0]
	ds_read_b128 v[238:241], v251 offset:3920
	s_waitcnt lgkmcnt(14)
	v_pk_fma_f32 v[24:25], v[242:243], v[10:11], v[24:25] op_sel:[0,0,0] op_sel_hi:[1,0,1] neg_lo:[1,0,0] neg_hi:[1,0,0]
	v_pk_fma_f32 v[26:27], v[244:245], v[10:11], v[26:27] op_sel:[0,0,0] op_sel_hi:[1,0,1] neg_lo:[1,0,0] neg_hi:[1,0,0]
	ds_read_b128 v[242:245], v251 offset:3936
	s_waitcnt lgkmcnt(14)
	v_pk_fma_f32 v[28:29], v[246:247], v[10:11], v[28:29] op_sel:[0,0,0] op_sel_hi:[1,0,1] neg_lo:[1,0,0] neg_hi:[1,0,0]
	v_pk_fma_f32 v[30:31], v[248:249], v[10:11], v[30:31] op_sel:[0,0,0] op_sel_hi:[1,0,1] neg_lo:[1,0,0] neg_hi:[1,0,0]
	ds_read_b128 v[246:249], v251 offset:3952
	s_waitcnt lgkmcnt(14)
	v_pk_fma_f32 v[32:33], v[64:65], v[10:11], v[32:33] op_sel:[0,0,0] op_sel_hi:[1,0,1] neg_lo:[1,0,0] neg_hi:[1,0,0]
	v_pk_fma_f32 v[34:35], v[66:67], v[10:11], v[34:35] op_sel:[0,0,0] op_sel_hi:[1,0,1] neg_lo:[1,0,0] neg_hi:[1,0,0]
	ds_read_b128 v[64:67], v251 offset:3968
	s_waitcnt lgkmcnt(14)
	v_pk_fma_f32 v[36:37], v[68:69], v[10:11], v[36:37] op_sel:[0,0,0] op_sel_hi:[1,0,1] neg_lo:[1,0,0] neg_hi:[1,0,0]
	v_pk_fma_f32 v[38:39], v[70:71], v[10:11], v[38:39] op_sel:[0,0,0] op_sel_hi:[1,0,1] neg_lo:[1,0,0] neg_hi:[1,0,0]
	ds_read_b128 v[68:71], v251 offset:3984
	s_waitcnt lgkmcnt(14)
	v_pk_fma_f32 v[40:41], v[72:73], v[10:11], v[40:41] op_sel:[0,0,0] op_sel_hi:[1,0,1] neg_lo:[1,0,0] neg_hi:[1,0,0]
	v_pk_fma_f32 v[42:43], v[74:75], v[10:11], v[42:43] op_sel:[0,0,0] op_sel_hi:[1,0,1] neg_lo:[1,0,0] neg_hi:[1,0,0]
	ds_read_b128 v[72:75], v251 offset:4000
	s_waitcnt lgkmcnt(14)
	v_pk_fma_f32 v[44:45], v[76:77], v[10:11], v[44:45] op_sel:[0,0,0] op_sel_hi:[1,0,1] neg_lo:[1,0,0] neg_hi:[1,0,0]
	v_pk_fma_f32 v[46:47], v[78:79], v[10:11], v[46:47] op_sel:[0,0,0] op_sel_hi:[1,0,1] neg_lo:[1,0,0] neg_hi:[1,0,0]
	ds_read_b128 v[76:79], v251 offset:4016
	s_waitcnt lgkmcnt(14)
	v_pk_fma_f32 v[48:49], v[80:81], v[10:11], v[48:49] op_sel:[0,0,0] op_sel_hi:[1,0,1] neg_lo:[1,0,0] neg_hi:[1,0,0]
	v_pk_fma_f32 v[50:51], v[82:83], v[10:11], v[50:51] op_sel:[0,0,0] op_sel_hi:[1,0,1] neg_lo:[1,0,0] neg_hi:[1,0,0]
	ds_read_b128 v[80:83], v251 offset:4032
	s_waitcnt lgkmcnt(14)
	v_pk_fma_f32 v[52:53], v[84:85], v[10:11], v[52:53] op_sel:[0,0,0] op_sel_hi:[1,0,1] neg_lo:[1,0,0] neg_hi:[1,0,0]
	v_pk_fma_f32 v[54:55], v[86:87], v[10:11], v[54:55] op_sel:[0,0,0] op_sel_hi:[1,0,1] neg_lo:[1,0,0] neg_hi:[1,0,0]
	ds_read_b128 v[84:87], v251 offset:4048
	s_waitcnt lgkmcnt(14)
	v_pk_fma_f32 v[56:57], v[88:89], v[10:11], v[56:57] op_sel:[0,0,0] op_sel_hi:[1,0,1] neg_lo:[1,0,0] neg_hi:[1,0,0]
	v_pk_fma_f32 v[58:59], v[90:91], v[10:11], v[58:59] op_sel:[0,0,0] op_sel_hi:[1,0,1] neg_lo:[1,0,0] neg_hi:[1,0,0]
	ds_read_b128 v[88:91], v251 offset:4064
	s_waitcnt lgkmcnt(12)
	v_pk_fma_f32 v[60:61], v[92:93], v[10:11], v[60:61] op_sel:[0,0,0] op_sel_hi:[1,0,1] neg_lo:[1,0,0] neg_hi:[1,0,0]
	v_pk_fma_f32 v[62:63], v[94:95], v[10:11], v[62:63] op_sel:[0,0,0] op_sel_hi:[1,0,1] neg_lo:[1,0,0] neg_hi:[1,0,0]
	ds_read_b128 v[92:95], v251 offset:4080
	v_pk_mul_f32 v[126:127], v[10:11], v[128:129] op_sel:[1,0] op_sel_hi:[1,1]
	s_nop 0
	v_cvt_pk_bf16_f32 v126, v126, v127
	s_nop 0
	ds_write_b16 v205, v126 offset:18992
	ds_write_b16_d16_hi v205, v126 offset:28208
	s_waitcnt lgkmcnt(14)
	v_pk_fma_f32 v[12:13], v[230:231], v[10:11], v[12:13] op_sel:[0,1,0] op_sel_hi:[1,1,1] neg_lo:[1,0,0] neg_hi:[1,0,0]
	v_pk_fma_f32 v[14:15], v[232:233], v[10:11], v[14:15] op_sel:[0,1,0] op_sel_hi:[1,1,1] neg_lo:[1,0,0] neg_hi:[1,0,0]
	ds_read_b128 v[230:233], v251 offset:4144
	s_waitcnt lgkmcnt(14)
	v_pk_fma_f32 v[16:17], v[234:235], v[10:11], v[16:17] op_sel:[0,1,0] op_sel_hi:[1,1,1] neg_lo:[1,0,0] neg_hi:[1,0,0]
	v_pk_fma_f32 v[18:19], v[236:237], v[10:11], v[18:19] op_sel:[0,1,0] op_sel_hi:[1,1,1] neg_lo:[1,0,0] neg_hi:[1,0,0]
	ds_read_b128 v[234:237], v251 offset:4160
	s_waitcnt lgkmcnt(14)
	v_pk_fma_f32 v[20:21], v[238:239], v[10:11], v[20:21] op_sel:[0,1,0] op_sel_hi:[1,1,1] neg_lo:[1,0,0] neg_hi:[1,0,0]
	v_pk_fma_f32 v[22:23], v[240:241], v[10:11], v[22:23] op_sel:[0,1,0] op_sel_hi:[1,1,1] neg_lo:[1,0,0] neg_hi:[1,0,0]
	ds_read_b128 v[238:241], v251 offset:4176
	s_waitcnt lgkmcnt(14)
	v_pk_fma_f32 v[24:25], v[242:243], v[10:11], v[24:25] op_sel:[0,1,0] op_sel_hi:[1,1,1] neg_lo:[1,0,0] neg_hi:[1,0,0]
	v_pk_fma_f32 v[26:27], v[244:245], v[10:11], v[26:27] op_sel:[0,1,0] op_sel_hi:[1,1,1] neg_lo:[1,0,0] neg_hi:[1,0,0]
	ds_read_b128 v[242:245], v251 offset:4192
	s_waitcnt lgkmcnt(14)
	v_pk_fma_f32 v[28:29], v[246:247], v[10:11], v[28:29] op_sel:[0,1,0] op_sel_hi:[1,1,1] neg_lo:[1,0,0] neg_hi:[1,0,0]
	v_pk_fma_f32 v[30:31], v[248:249], v[10:11], v[30:31] op_sel:[0,1,0] op_sel_hi:[1,1,1] neg_lo:[1,0,0] neg_hi:[1,0,0]
	ds_read_b128 v[246:249], v251 offset:4208
	s_waitcnt lgkmcnt(14)
	v_pk_fma_f32 v[32:33], v[64:65], v[10:11], v[32:33] op_sel:[0,1,0] op_sel_hi:[1,1,1] neg_lo:[1,0,0] neg_hi:[1,0,0]
	v_pk_fma_f32 v[34:35], v[66:67], v[10:11], v[34:35] op_sel:[0,1,0] op_sel_hi:[1,1,1] neg_lo:[1,0,0] neg_hi:[1,0,0]
	ds_read_b128 v[64:67], v251 offset:4224
	s_waitcnt lgkmcnt(14)
; #define PG8_LAS __attribute__((address_space(3)))
; __device__ __forceinline__ bf16_t f2bf(float x) { return (bf16_t)(pk2(x, x) & 0xffffu); }
; __device__ __forceinline__ void solve64(float (&x)[64], const PG8_LAS float* sLt) {
;     f32x4 cur[16];
; #pragma unroll
;     for (int i4 = 0; i4 < 16; ++i4) cur[i4] = *(const PG8_LAS f32x4*)(sLt + 4 * i4);
;     asm volatile("" ::: "memory");
; #pragma unroll
;     for (int j = 0; j < 63; ++j) {
;         const float xj = x[j];
; #pragma unroll
;         for (int i4 = (j + 1) / 4; i4 < 16; ++i4) {
;             if (4 * i4 + 0 > j) x[4 * i4 + 0] -= cur[i4][0] * xj;
;             if (4 * i4 + 1 > j) x[4 * i4 + 1] -= cur[i4][1] * xj;
;             if (4 * i4 + 2 > j) x[4 * i4 + 2] -= cur[i4][2] * xj;
;             if (4 * i4 + 3 > j) x[4 * i4 + 3] -= cur[i4][3] * xj;
;             if (j + 1 < 63 && i4 >= (j + 2) / 4) cur[i4] = *(const PG8_LAS f32x4*)(sLt + (j + 1) * 64 + 4 * i4); }
;         asm volatile("" ::: "memory");
;     }
; }
; __device__ __forceinline__ void phase_prep(const Args& a, PG8_LAS unsigned char* lds) {
;     ...
;             const float bj = sB[lane], bej = bj * sE[lane];
; #pragma unroll
;             for (int i = 0; i < 64; ++i) { *(PG8_LAS bf16_t*)(Tu + (i * 72 + lane) * 2) = f2bf(x[i] * bj); *(PG8_LAS bf16_t*)(Tw + (i * 72 + lane) * 2) = f2bf(x[i] * bej); }
	v_pk_fma_f32 v[36:37], v[68:69], v[10:11], v[36:37] op_sel:[0,1,0] op_sel_hi:[1,1,1] neg_lo:[1,0,0] neg_hi:[1,0,0]
	v_pk_fma_f32 v[38:39], v[70:71], v[10:11], v[38:39] op_sel:[0,1,0] op_sel_hi:[1,1,1] neg_lo:[1,0,0] neg_hi:[1,0,0]
	ds_read_b128 v[68:71], v251 offset:4240
	s_waitcnt lgkmcnt(14)
	v_pk_fma_f32 v[40:41], v[72:73], v[10:11], v[40:41] op_sel:[0,1,0] op_sel_hi:[1,1,1] neg_lo:[1,0,0] neg_hi:[1,0,0]
	v_pk_fma_f32 v[42:43], v[74:75], v[10:11], v[42:43] op_sel:[0,1,0] op_sel_hi:[1,1,1] neg_lo:[1,0,0] neg_hi:[1,0,0]
	ds_read_b128 v[72:75], v251 offset:4256
	s_waitcnt lgkmcnt(14)
	v_pk_fma_f32 v[44:45], v[76:77], v[10:11], v[44:45] op_sel:[0,1,0] op_sel_hi:[1,1,1] neg_lo:[1,0,0] neg_hi:[1,0,0]
	v_pk_fma_f32 v[46:47], v[78:79], v[10:11], v[46:47] op_sel:[0,1,0] op_sel_hi:[1,1,1] neg_lo:[1,0,0] neg_hi:[1,0,0]
	ds_read_b128 v[76:79], v251 offset:4272
	s_waitcnt lgkmcnt(14)
	v_pk_fma_f32 v[48:49], v[80:81], v[10:11], v[48:49] op_sel:[0,1,0] op_sel_hi:[1,1,1] neg_lo:[1,0,0] neg_hi:[1,0,0]
	v_pk_fma_f32 v[50:51], v[82:83], v[10:11], v[50:51] op_sel:[0,1,0] op_sel_hi:[1,1,1] neg_lo:[1,0,0] neg_hi:[1,0,0]
	ds_read_b128 v[80:83], v251 offset:4288
	s_waitcnt lgkmcnt(14)
	v_pk_fma_f32 v[52:53], v[84:85], v[10:11], v[52:53] op_sel:[0,1,0] op_sel_hi:[1,1,1] neg_lo:[1,0,0] neg_hi:[1,0,0]
	v_pk_fma_f32 v[54:55], v[86:87], v[10:11], v[54:55] op_sel:[0,1,0] op_sel_hi:[1,1,1] neg_lo:[1,0,0] neg_hi:[1,0,0]
	ds_read_b128 v[84:87], v251 offset:4304
	s_waitcnt lgkmcnt(14)
	v_pk_fma_f32 v[56:57], v[88:89], v[10:11], v[56:57] op_sel:[0,1,0] op_sel_hi:[1,1,1] neg_lo:[1,0,0] neg_hi:[1,0,0]
	v_pk_fma_f32 v[58:59], v[90:91], v[10:11], v[58:59] op_sel:[0,1,0] op_sel_hi:[1,1,1] neg_lo:[1,0,0] neg_hi:[1,0,0]
	ds_read_b128 v[88:91], v251 offset:4320
	s_waitcnt lgkmcnt(14)
	v_pk_fma_f32 v[60:61], v[92:93], v[10:11], v[60:61] op_sel:[0,1,0] op_sel_hi:[1,1,1] neg_lo:[1,0,0] neg_hi:[1,0,0]
	v_pk_fma_f32 v[62:63], v[94:95], v[10:11], v[62:63] op_sel:[0,1,0] op_sel_hi:[1,1,1] neg_lo:[1,0,0] neg_hi:[1,0,0]
	ds_read_b128 v[92:95], v251 offset:4336
	v_pk_mul_f32 v[126:127], v[12:13], v[128:129] op_sel:[0,0] op_sel_hi:[0,1]
	s_nop 0
	v_cvt_pk_bf16_f32 v126, v126, v127
	s_nop 0
	ds_write_b16 v205, v126 offset:19136
	ds_write_b16_d16_hi v205, v126 offset:28352
	s_waitcnt lgkmcnt(14)
	v_fma_f32 v13, -v231, v12, v13
	v_pk_fma_f32 v[14:15], v[232:233], v[12:13], v[14:15] op_sel:[0,0,0] op_sel_hi:[1,0,1] neg_lo:[1,0,0] neg_hi:[1,0,0]
	ds_read_b128 v[230:233], v251 offset:4400
	s_waitcnt lgkmcnt(14)
	v_pk_fma_f32 v[16:17], v[234:235], v[12:13], v[16:17] op_sel:[0,0,0] op_sel_hi:[1,0,1] neg_lo:[1,0,0] neg_hi:[1,0,0]
	v_pk_fma_f32 v[18:19], v[236:237], v[12:13], v[18:19] op_sel:[0,0,0] op_sel_hi:[1,0,1] neg_lo:[1,0,0] neg_hi:[1,0,0]
	ds_read_b128 v[234:237], v251 offset:4416
	s_waitcnt lgkmcnt(14)
	v_pk_fma_f32 v[20:21], v[238:239], v[12:13], v[20:21] op_sel:[0,0,0] op_sel_hi:[1,0,1] neg_lo:[1,0,0] neg_hi:[1,0,0]
	v_pk_fma_f32 v[22:23], v[240:241], v[12:13], v[22:23] op_sel:[0,0,0] op_sel_hi:[1,0,1] neg_lo:[1,0,0] neg_hi:[1,0,0]
	ds_read_b128 v[238:241], v251 offset:4432
	s_waitcnt lgkmcnt(14)
	v_pk_fma_f32 v[24:25], v[242:243], v[12:13], v[24:25] op_sel:[0,0,0] op_sel_hi:[1,0,1] neg_lo:[1,0,0] neg_hi:[1,0,0]
	v_pk_fma_f32 v[26:27], v[244:245], v[12:13], v[26:27] op_sel:[0,0,0] op_sel_hi:[1,0,1] neg_lo:[1,0,0] neg_hi:[1,0,0]
	ds_read_b128 v[242:245], v251 offset:4448
	s_waitcnt lgkmcnt(14)
	v_pk_fma_f32 v[28:29], v[246:247], v[12:13], v[28:29] op_sel:[0,0,0] op_sel_hi:[1,0,1] neg_lo:[1,0,0] neg_hi:[1,0,0]
	v_pk_fma_f32 v[30:31], v[248:249], v[12:13], v[30:31] op_sel:[0,0,0] op_sel_hi:[1,0,1] neg_lo:[1,0,0] neg_hi:[1,0,0]
	ds_read_b128 v[246:249], v251 offset:4464
	s_waitcnt lgkmcnt(14)
	v_pk_fma_f32 v[32:33], v[64:65], v[12:13], v[32:33] op_sel:[0,0,0] op_sel_hi:[1,0,1] neg_lo:[1,0,0] neg_hi:[1,0,0]
	v_pk_fma_f32 v[34:35], v[66:67], v[12:13], v[34:35] op_sel:[0,0,0] op_sel_hi:[1,0,1] neg_lo:[1,0,0] neg_hi:[1,0,0]
	ds_read_b128 v[64:67], v251 offset:4480
	s_waitcnt lgkmcnt(14)
	v_pk_fma_f32 v[36:37], v[68:69], v[12:13], v[36:37] op_sel:[0,0,0] op_sel_hi:[1,0,1] neg_lo:[1,0,0] neg_hi:[1,0,0]
	v_pk_fma_f32 v[38:39], v[70:71], v[12:13], v[38:39] op_sel:[0,0,0] op_sel_hi:[1,0,1] neg_lo:[1,0,0] neg_hi:[1,0,0]
	ds_read_b128 v[68:71], v251 offset:4496
	s_waitcnt lgkmcnt(14)
	v_pk_fma_f32 v[40:41], v[72:73], v[12:13], v[40:41] op_sel:[0,0,0] op_sel_hi:[1,0,1] neg_lo:[1,0,0] neg_hi:[1,0,0]
	v_pk_fma_f32 v[42:43], v[74:75], v[12:13], v[42:43] op_sel:[0,0,0] op_sel_hi:[1,0,1] neg_lo:[1,0,0] neg_hi:[1,0,0]
	ds_read_b128 v[72:75], v251 offset:4512
	s_waitcnt lgkmcnt(14)
	v_pk_fma_f32 v[44:45], v[76:77], v[12:13], v[44:45] op_sel:[0,0,0] op_sel_hi:[1,0,1] neg_lo:[1,0,0] neg_hi:[1,0,0]
	v_pk_fma_f32 v[46:47], v[78:79], v[12:13], v[46:47] op_sel:[0,0,0] op_sel_hi:[1,0,1] neg_lo:[1,0,0] neg_hi:[1,0,0]
	ds_read_b128 v[76:79], v251 offset:4528
	s_waitcnt lgkmcnt(14)
	v_pk_fma_f32 v[48:49], v[80:81], v[12:13], v[48:49] op_sel:[0,0,0] op_sel_hi:[1,0,1] neg_lo:[1,0,0] neg_hi:[1,0,0]
	v_pk_fma_f32 v[50:51], v[82:83], v[12:13], v[50:51] op_sel:[0,0,0] op_sel_hi:[1,0,1] neg_lo:[1,0,0] neg_hi:[1,0,0]
	ds_read_b128 v[80:83], v251 offset:4544
	s_waitcnt lgkmcnt(14)
	v_pk_fma_f32 v[52:53], v[84:85], v[12:13], v[52:53] op_sel:[0,0,0] op_sel_hi:[1,0,1] neg_lo:[1,0,0] neg_hi:[1,0,0]
	v_pk_fma_f32 v[54:55], v[86:87], v[12:13], v[54:55] op_sel:[0,0,0] op_sel_hi:[1,0,1] neg_lo:[1,0,0] neg_hi:[1,0,0]
	ds_read_b128 v[84:87], v251 offset:4560
	s_waitcnt lgkmcnt(14)
	v_pk_fma_f32 v[56:57], v[88:89], v[12:13], v[56:57] op_sel:[0,0,0] op_sel_hi:[1,0,1] neg_lo:[1,0,0] neg_hi:[1,0,0]
	v_pk_fma_f32 v[58:59], v[90:91], v[12:13], v[58:59] op_sel:[0,0,0] op_sel_hi:[1,0,1] neg_lo:[1,0,0] neg_hi:[1,0,0]
	ds_read_b128 v[88:91], v251 offset:4576
	s_waitcnt lgkmcnt(14)
; #define PG8_LAS __attribute__((address_space(3)))
; __device__ __forceinline__ bf16_t f2bf(float x) { return (bf16_t)(pk2(x, x) & 0xffffu); }
; __device__ __forceinline__ void solve64(float (&x)[64], const PG8_LAS float* sLt) {
;     f32x4 cur[16];
; #pragma unroll
;     for (int i4 = 0; i4 < 16; ++i4) cur[i4] = *(const PG8_LAS f32x4*)(sLt + 4 * i4);
;     asm volatile("" ::: "memory");
; #pragma unroll
;     for (int j = 0; j < 63; ++j) {
;         const float xj = x[j];
; #pragma unroll
;         for (int i4 = (j + 1) / 4; i4 < 16; ++i4) {
;             if (4 * i4 + 0 > j) x[4 * i4 + 0] -= cur[i4][0] * xj;
;             if (4 * i4 + 1 > j) x[4 * i4 + 1] -= cur[i4][1] * xj;
;             if (4 * i4 + 2 > j) x[4 * i4 + 2] -= cur[i4][2] * xj;
;             if (4 * i4 + 3 > j) x[4 * i4 + 3] -= cur[i4][3] * xj;
;             if (j + 1 < 63 && i4 >= (j + 2) / 4) cur[i4] = *(const PG8_LAS f32x4*)(sLt + (j + 1) * 64 + 4 * i4); }
;         asm volatile("" ::: "memory");
;     }
; }
; __device__ __forceinline__ void phase_prep(const Args& a, PG8_LAS unsigned char* lds) {
;     ...
;             const float bj = sB[lane], bej = bj * sE[lane];
; #pragma unroll
;             for (int i = 0; i < 64; ++i) { *(PG8_LAS bf16_t*)(Tu + (i * 72 + lane) * 2) = f2bf(x[i] * bj); *(PG8_LAS bf16_t*)(Tw + (i * 72 + lane) * 2) = f2bf(x[i] * bej); }
	v_pk_fma_f32 v[60:61], v[92:93], v[12:13], v[60:61] op_sel:[0,0,0] op_sel_hi:[1,0,1] neg_lo:[1,0,0] neg_hi:[1,0,0]
	v_pk_fma_f32 v[62:63], v[94:95], v[12:13], v[62:63] op_sel:[0,0,0] op_sel_hi:[1,0,1] neg_lo:[1,0,0] neg_hi:[1,0,0]
	ds_read_b128 v[92:95], v251 offset:4592
	v_pk_mul_f32 v[126:127], v[12:13], v[128:129] op_sel:[1,0] op_sel_hi:[1,1]
	s_nop 0
	v_cvt_pk_bf16_f32 v126, v126, v127
	s_nop 0
	ds_write_b16 v205, v126 offset:19280
	ds_write_b16_d16_hi v205, v126 offset:28496
	s_waitcnt lgkmcnt(14)
	v_pk_fma_f32 v[14:15], v[232:233], v[12:13], v[14:15] op_sel:[0,1,0] op_sel_hi:[1,1,1] neg_lo:[1,0,0] neg_hi:[1,0,0]
	ds_read_b128 v[230:233], v251 offset:4656
	s_waitcnt lgkmcnt(14)
	v_pk_fma_f32 v[16:17], v[234:235], v[12:13], v[16:17] op_sel:[0,1,0] op_sel_hi:[1,1,1] neg_lo:[1,0,0] neg_hi:[1,0,0]
	v_pk_fma_f32 v[18:19], v[236:237], v[12:13], v[18:19] op_sel:[0,1,0] op_sel_hi:[1,1,1] neg_lo:[1,0,0] neg_hi:[1,0,0]
	ds_read_b128 v[234:237], v251 offset:4672
	s_waitcnt lgkmcnt(14)
	v_pk_fma_f32 v[20:21], v[238:239], v[12:13], v[20:21] op_sel:[0,1,0] op_sel_hi:[1,1,1] neg_lo:[1,0,0] neg_hi:[1,0,0]
	v_pk_fma_f32 v[22:23], v[240:241], v[12:13], v[22:23] op_sel:[0,1,0] op_sel_hi:[1,1,1] neg_lo:[1,0,0] neg_hi:[1,0,0]
	ds_read_b128 v[238:241], v251 offset:4688
	s_waitcnt lgkmcnt(14)
	v_pk_fma_f32 v[24:25], v[242:243], v[12:13], v[24:25] op_sel:[0,1,0] op_sel_hi:[1,1,1] neg_lo:[1,0,0] neg_hi:[1,0,0]
	v_pk_fma_f32 v[26:27], v[244:245], v[12:13], v[26:27] op_sel:[0,1,0] op_sel_hi:[1,1,1] neg_lo:[1,0,0] neg_hi:[1,0,0]
	ds_read_b128 v[242:245], v251 offset:4704
	s_waitcnt lgkmcnt(14)
	v_pk_fma_f32 v[28:29], v[246:247], v[12:13], v[28:29] op_sel:[0,1,0] op_sel_hi:[1,1,1] neg_lo:[1,0,0] neg_hi:[1,0,0]
	v_pk_fma_f32 v[30:31], v[248:249], v[12:13], v[30:31] op_sel:[0,1,0] op_sel_hi:[1,1,1] neg_lo:[1,0,0] neg_hi:[1,0,0]
	ds_read_b128 v[246:249], v251 offset:4720
	s_waitcnt lgkmcnt(14)
	v_pk_fma_f32 v[32:33], v[64:65], v[12:13], v[32:33] op_sel:[0,1,0] op_sel_hi:[1,1,1] neg_lo:[1,0,0] neg_hi:[1,0,0]
	v_pk_fma_f32 v[34:35], v[66:67], v[12:13], v[34:35] op_sel:[0,1,0] op_sel_hi:[1,1,1] neg_lo:[1,0,0] neg_hi:[1,0,0]
	ds_read_b128 v[64:67], v251 offset:4736
	s_waitcnt lgkmcnt(14)
	v_pk_fma_f32 v[36:37], v[68:69], v[12:13], v[36:37] op_sel:[0,1,0] op_sel_hi:[1,1,1] neg_lo:[1,0,0] neg_hi:[1,0,0]
	v_pk_fma_f32 v[38:39], v[70:71], v[12:13], v[38:39] op_sel:[0,1,0] op_sel_hi:[1,1,1] neg_lo:[1,0,0] neg_hi:[1,0,0]
	ds_read_b128 v[68:71], v251 offset:4752
	s_waitcnt lgkmcnt(14)
	v_pk_fma_f32 v[40:41], v[72:73], v[12:13], v[40:41] op_sel:[0,1,0] op_sel_hi:[1,1,1] neg_lo:[1,0,0] neg_hi:[1,0,0]
	v_pk_fma_f32 v[42:43], v[74:75], v[12:13], v[42:43] op_sel:[0,1,0] op_sel_hi:[1,1,1] neg_lo:[1,0,0] neg_hi:[1,0,0]
	ds_read_b128 v[72:75], v251 offset:4768
	s_waitcnt lgkmcnt(14)
	v_pk_fma_f32 v[44:45], v[76:77], v[12:13], v[44:45] op_sel:[0,1,0] op_sel_hi:[1,1,1] neg_lo:[1,0,0] neg_hi:[1,0,0]
	v_pk_fma_f32 v[46:47], v[78:79], v[12:13], v[46:47] op_sel:[0,1,0] op_sel_hi:[1,1,1] neg_lo:[1,0,0] neg_hi:[1,0,0]
	ds_read_b128 v[76:79], v251 offset:4784
	s_waitcnt lgkmcnt(14)
	v_pk_fma_f32 v[48:49], v[80:81], v[12:13], v[48:49] op_sel:[0,1,0] op_sel_hi:[1,1,1] neg_lo:[1,0,0] neg_hi:[1,0,0]
	v_pk_fma_f32 v[50:51], v[82:83], v[12:13], v[50:51] op_sel:[0,1,0] op_sel_hi:[1,1,1] neg_lo:[1,0,0] neg_hi:[1,0,0]
	ds_read_b128 v[80:83], v251 offset:4800
	s_waitcnt lgkmcnt(14)
	v_pk_fma_f32 v[52:53], v[84:85], v[12:13], v[52:53] op_sel:[0,1,0] op_sel_hi:[1,1,1] neg_lo:[1,0,0] neg_hi:[1,0,0]
	v_pk_fma_f32 v[54:55], v[86:87], v[12:13], v[54:55] op_sel:[0,1,0] op_sel_hi:[1,1,1] neg_lo:[1,0,0] neg_hi:[1,0,0]
	ds_read_b128 v[84:87], v251 offset:4816
	s_waitcnt lgkmcnt(14)
	v_pk_fma_f32 v[56:57], v[88:89], v[12:13], v[56:57] op_sel:[0,1,0] op_sel_hi:[1,1,1] neg_lo:[1,0,0] neg_hi:[1,0,0]
	v_pk_fma_f32 v[58:59], v[90:91], v[12:13], v[58:59] op_sel:[0,1,0] op_sel_hi:[1,1,1] neg_lo:[1,0,0] neg_hi:[1,0,0]
	ds_read_b128 v[88:91], v251 offset:4832
	s_waitcnt lgkmcnt(14)
	v_pk_fma_f32 v[60:61], v[92:93], v[12:13], v[60:61] op_sel:[0,1,0] op_sel_hi:[1,1,1] neg_lo:[1,0,0] neg_hi:[1,0,0]
	v_pk_fma_f32 v[62:63], v[94:95], v[12:13], v[62:63] op_sel:[0,1,0] op_sel_hi:[1,1,1] neg_lo:[1,0,0] neg_hi:[1,0,0]
	ds_read_b128 v[92:95], v251 offset:4848
	v_pk_mul_f32 v[126:127], v[14:15], v[128:129] op_sel:[0,0] op_sel_hi:[0,1]
	s_nop 0
	v_cvt_pk_bf16_f32 v126, v126, v127
	s_nop 0
	ds_write_b16 v205, v126 offset:19424
	ds_write_b16_d16_hi v205, v126 offset:28640
	s_waitcnt lgkmcnt(14)
	v_fma_f32 v15, -v233, v14, v15
	ds_read_b128 v[230:233], v251 offset:4928
	s_waitcnt lgkmcnt(14)
	v_pk_fma_f32 v[16:17], v[234:235], v[14:15], v[16:17] op_sel:[0,0,0] op_sel_hi:[1,0,1] neg_lo:[1,0,0] neg_hi:[1,0,0]
	v_pk_fma_f32 v[18:19], v[236:237], v[14:15], v[18:19] op_sel:[0,0,0] op_sel_hi:[1,0,1] neg_lo:[1,0,0] neg_hi:[1,0,0]
	ds_read_b128 v[234:237], v251 offset:4944
	s_waitcnt lgkmcnt(14)
	v_pk_fma_f32 v[20:21], v[238:239], v[14:15], v[20:21] op_sel:[0,0,0] op_sel_hi:[1,0,1] neg_lo:[1,0,0] neg_hi:[1,0,0]
	v_pk_fma_f32 v[22:23], v[240:241], v[14:15], v[22:23] op_sel:[0,0,0] op_sel_hi:[1,0,1] neg_lo:[1,0,0] neg_hi:[1,0,0]
	ds_read_b128 v[238:241], v251 offset:4960
	s_waitcnt lgkmcnt(14)
	v_pk_fma_f32 v[24:25], v[242:243], v[14:15], v[24:25] op_sel:[0,0,0] op_sel_hi:[1,0,1] neg_lo:[1,0,0] neg_hi:[1,0,0]
	v_pk_fma_f32 v[26:27], v[244:245], v[14:15], v[26:27] op_sel:[0,0,0] op_sel_hi:[1,0,1] neg_lo:[1,0,0] neg_hi:[1,0,0]
	ds_read_b128 v[242:245], v251 offset:4976
	s_waitcnt lgkmcnt(14)
	v_pk_fma_f32 v[28:29], v[246:247], v[14:15], v[28:29] op_sel:[0,0,0] op_sel_hi:[1,0,1] neg_lo:[1,0,0] neg_hi:[1,0,0]
	v_pk_fma_f32 v[30:31], v[248:249], v[14:15], v[30:31] op_sel:[0,0,0] op_sel_hi:[1,0,1] neg_lo:[1,0,0] neg_hi:[1,0,0]
	ds_read_b128 v[246:249], v251 offset:4992
	s_waitcnt lgkmcnt(14)
; #define PG8_LAS __attribute__((address_space(3)))
; __device__ __forceinline__ bf16_t f2bf(float x) { return (bf16_t)(pk2(x, x) & 0xffffu); }
; __device__ __forceinline__ void solve64(float (&x)[64], const PG8_LAS float* sLt) {
;     f32x4 cur[16];
; #pragma unroll
;     for (int i4 = 0; i4 < 16; ++i4) cur[i4] = *(const PG8_LAS f32x4*)(sLt + 4 * i4);
;     asm volatile("" ::: "memory");
; #pragma unroll
;     for (int j = 0; j < 63; ++j) {
;         const float xj = x[j];
; #pragma unroll
;         for (int i4 = (j + 1) / 4; i4 < 16; ++i4) {
;             if (4 * i4 + 0 > j) x[4 * i4 + 0] -= cur[i4][0] * xj;
;             if (4 * i4 + 1 > j) x[4 * i4 + 1] -= cur[i4][1] * xj;
;             if (4 * i4 + 2 > j) x[4 * i4 + 2] -= cur[i4][2] * xj;
;             if (4 * i4 + 3 > j) x[4 * i4 + 3] -= cur[i4][3] * xj;
;             if (j + 1 < 63 && i4 >= (j + 2) / 4) cur[i4] = *(const PG8_LAS f32x4*)(sLt + (j + 1) * 64 + 4 * i4); }
;         asm volatile("" ::: "memory");
;     }
; }
; __device__ __forceinline__ void phase_prep(const Args& a, PG8_LAS unsigned char* lds) {
;     ...
;             const float bj = sB[lane], bej = bj * sE[lane];
; #pragma unroll
;             for (int i = 0; i < 64; ++i) { *(PG8_LAS bf16_t*)(Tu + (i * 72 + lane) * 2) = f2bf(x[i] * bj); *(PG8_LAS bf16_t*)(Tw + (i * 72 + lane) * 2) = f2bf(x[i] * bej); }
	v_pk_fma_f32 v[32:33], v[64:65], v[14:15], v[32:33] op_sel:[0,0,0] op_sel_hi:[1,0,1] neg_lo:[1,0,0] neg_hi:[1,0,0]
	v_pk_fma_f32 v[34:35], v[66:67], v[14:15], v[34:35] op_sel:[0,0,0] op_sel_hi:[1,0,1] neg_lo:[1,0,0] neg_hi:[1,0,0]
	ds_read_b128 v[64:67], v251 offset:5008
	s_waitcnt lgkmcnt(14)
	v_pk_fma_f32 v[36:37], v[68:69], v[14:15], v[36:37] op_sel:[0,0,0] op_sel_hi:[1,0,1] neg_lo:[1,0,0] neg_hi:[1,0,0]
	v_pk_fma_f32 v[38:39], v[70:71], v[14:15], v[38:39] op_sel:[0,0,0] op_sel_hi:[1,0,1] neg_lo:[1,0,0] neg_hi:[1,0,0]
	ds_read_b128 v[68:71], v251 offset:5024
	s_waitcnt lgkmcnt(14)
	v_pk_fma_f32 v[40:41], v[72:73], v[14:15], v[40:41] op_sel:[0,0,0] op_sel_hi:[1,0,1] neg_lo:[1,0,0] neg_hi:[1,0,0]
	v_pk_fma_f32 v[42:43], v[74:75], v[14:15], v[42:43] op_sel:[0,0,0] op_sel_hi:[1,0,1] neg_lo:[1,0,0] neg_hi:[1,0,0]
	ds_read_b128 v[72:75], v251 offset:5040
	s_waitcnt lgkmcnt(14)
	v_pk_fma_f32 v[44:45], v[76:77], v[14:15], v[44:45] op_sel:[0,0,0] op_sel_hi:[1,0,1] neg_lo:[1,0,0] neg_hi:[1,0,0]
	v_pk_fma_f32 v[46:47], v[78:79], v[14:15], v[46:47] op_sel:[0,0,0] op_sel_hi:[1,0,1] neg_lo:[1,0,0] neg_hi:[1,0,0]
	ds_read_b128 v[76:79], v251 offset:5056
	s_waitcnt lgkmcnt(14)
	v_pk_fma_f32 v[48:49], v[80:81], v[14:15], v[48:49] op_sel:[0,0,0] op_sel_hi:[1,0,1] neg_lo:[1,0,0] neg_hi:[1,0,0]
	v_pk_fma_f32 v[50:51], v[82:83], v[14:15], v[50:51] op_sel:[0,0,0] op_sel_hi:[1,0,1] neg_lo:[1,0,0] neg_hi:[1,0,0]
	ds_read_b128 v[80:83], v251 offset:5072
	s_waitcnt lgkmcnt(14)
	v_pk_fma_f32 v[52:53], v[84:85], v[14:15], v[52:53] op_sel:[0,0,0] op_sel_hi:[1,0,1] neg_lo:[1,0,0] neg_hi:[1,0,0]
	v_pk_fma_f32 v[54:55], v[86:87], v[14:15], v[54:55] op_sel:[0,0,0] op_sel_hi:[1,0,1] neg_lo:[1,0,0] neg_hi:[1,0,0]
	ds_read_b128 v[84:87], v251 offset:5088
	s_waitcnt lgkmcnt(14)
	v_pk_fma_f32 v[56:57], v[88:89], v[14:15], v[56:57] op_sel:[0,0,0] op_sel_hi:[1,0,1] neg_lo:[1,0,0] neg_hi:[1,0,0]
	v_pk_fma_f32 v[58:59], v[90:91], v[14:15], v[58:59] op_sel:[0,0,0] op_sel_hi:[1,0,1] neg_lo:[1,0,0] neg_hi:[1,0,0]
	ds_read_b128 v[88:91], v251 offset:5104
	s_waitcnt lgkmcnt(14)
	v_pk_fma_f32 v[60:61], v[92:93], v[14:15], v[60:61] op_sel:[0,0,0] op_sel_hi:[1,0,1] neg_lo:[1,0,0] neg_hi:[1,0,0]
	v_pk_fma_f32 v[62:63], v[94:95], v[14:15], v[62:63] op_sel:[0,0,0] op_sel_hi:[1,0,1] neg_lo:[1,0,0] neg_hi:[1,0,0]
	ds_read_b128 v[92:95], v251 offset:5184
	v_pk_mul_f32 v[126:127], v[14:15], v[128:129] op_sel:[1,0] op_sel_hi:[1,1]
	s_nop 0
	v_cvt_pk_bf16_f32 v126, v126, v127
	s_nop 0
	ds_write_b16 v205, v126 offset:19568
	ds_write_b16_d16_hi v205, v126 offset:28784
	s_waitcnt lgkmcnt(14)
	v_pk_fma_f32 v[16:17], v[230:231], v[14:15], v[16:17] op_sel:[0,1,0] op_sel_hi:[1,1,1] neg_lo:[1,0,0] neg_hi:[1,0,0]
	v_pk_fma_f32 v[18:19], v[232:233], v[14:15], v[18:19] op_sel:[0,1,0] op_sel_hi:[1,1,1] neg_lo:[1,0,0] neg_hi:[1,0,0]
	ds_read_b128 v[230:233], v251 offset:5200
	s_waitcnt lgkmcnt(14)
	v_pk_fma_f32 v[20:21], v[234:235], v[14:15], v[20:21] op_sel:[0,1,0] op_sel_hi:[1,1,1] neg_lo:[1,0,0] neg_hi:[1,0,0]
	v_pk_fma_f32 v[22:23], v[236:237], v[14:15], v[22:23] op_sel:[0,1,0] op_sel_hi:[1,1,1] neg_lo:[1,0,0] neg_hi:[1,0,0]
	ds_read_b128 v[234:237], v251 offset:5216
	s_waitcnt lgkmcnt(14)
	v_pk_fma_f32 v[24:25], v[238:239], v[14:15], v[24:25] op_sel:[0,1,0] op_sel_hi:[1,1,1] neg_lo:[1,0,0] neg_hi:[1,0,0]
	v_pk_fma_f32 v[26:27], v[240:241], v[14:15], v[26:27] op_sel:[0,1,0] op_sel_hi:[1,1,1] neg_lo:[1,0,0] neg_hi:[1,0,0]
	ds_read_b128 v[238:241], v251 offset:5232
	s_waitcnt lgkmcnt(14)
	v_pk_fma_f32 v[28:29], v[242:243], v[14:15], v[28:29] op_sel:[0,1,0] op_sel_hi:[1,1,1] neg_lo:[1,0,0] neg_hi:[1,0,0]
	v_pk_fma_f32 v[30:31], v[244:245], v[14:15], v[30:31] op_sel:[0,1,0] op_sel_hi:[1,1,1] neg_lo:[1,0,0] neg_hi:[1,0,0]
	ds_read_b128 v[242:245], v251 offset:5248
	s_waitcnt lgkmcnt(14)
	v_pk_fma_f32 v[32:33], v[246:247], v[14:15], v[32:33] op_sel:[0,1,0] op_sel_hi:[1,1,1] neg_lo:[1,0,0] neg_hi:[1,0,0]
	v_pk_fma_f32 v[34:35], v[248:249], v[14:15], v[34:35] op_sel:[0,1,0] op_sel_hi:[1,1,1] neg_lo:[1,0,0] neg_hi:[1,0,0]
	ds_read_b128 v[246:249], v251 offset:5264
	s_waitcnt lgkmcnt(14)
	v_pk_fma_f32 v[36:37], v[64:65], v[14:15], v[36:37] op_sel:[0,1,0] op_sel_hi:[1,1,1] neg_lo:[1,0,0] neg_hi:[1,0,0]
	v_pk_fma_f32 v[38:39], v[66:67], v[14:15], v[38:39] op_sel:[0,1,0] op_sel_hi:[1,1,1] neg_lo:[1,0,0] neg_hi:[1,0,0]
	ds_read_b128 v[64:67], v251 offset:5280
	s_waitcnt lgkmcnt(14)
	v_pk_fma_f32 v[40:41], v[68:69], v[14:15], v[40:41] op_sel:[0,1,0] op_sel_hi:[1,1,1] neg_lo:[1,0,0] neg_hi:[1,0,0]
	v_pk_fma_f32 v[42:43], v[70:71], v[14:15], v[42:43] op_sel:[0,1,0] op_sel_hi:[1,1,1] neg_lo:[1,0,0] neg_hi:[1,0,0]
	ds_read_b128 v[68:71], v251 offset:5296
	s_waitcnt lgkmcnt(14)
	v_pk_fma_f32 v[44:45], v[72:73], v[14:15], v[44:45] op_sel:[0,1,0] op_sel_hi:[1,1,1] neg_lo:[1,0,0] neg_hi:[1,0,0]
	v_pk_fma_f32 v[46:47], v[74:75], v[14:15], v[46:47] op_sel:[0,1,0] op_sel_hi:[1,1,1] neg_lo:[1,0,0] neg_hi:[1,0,0]
	ds_read_b128 v[72:75], v251 offset:5312
	s_waitcnt lgkmcnt(14)
	v_pk_fma_f32 v[48:49], v[76:77], v[14:15], v[48:49] op_sel:[0,1,0] op_sel_hi:[1,1,1] neg_lo:[1,0,0] neg_hi:[1,0,0]
	v_pk_fma_f32 v[50:51], v[78:79], v[14:15], v[50:51] op_sel:[0,1,0] op_sel_hi:[1,1,1] neg_lo:[1,0,0] neg_hi:[1,0,0]
	ds_read_b128 v[76:79], v251 offset:5328
	s_waitcnt lgkmcnt(14)
	v_pk_fma_f32 v[52:53], v[80:81], v[14:15], v[52:53] op_sel:[0,1,0] op_sel_hi:[1,1,1] neg_lo:[1,0,0] neg_hi:[1,0,0]
	v_pk_fma_f32 v[54:55], v[82:83], v[14:15], v[54:55] op_sel:[0,1,0] op_sel_hi:[1,1,1] neg_lo:[1,0,0] neg_hi:[1,0,0]
	ds_read_b128 v[80:83], v251 offset:5344
	s_waitcnt lgkmcnt(14)
; #define PG8_LAS __attribute__((address_space(3)))
; __device__ __forceinline__ bf16_t f2bf(float x) { return (bf16_t)(pk2(x, x) & 0xffffu); }
; __device__ __forceinline__ void solve64(float (&x)[64], const PG8_LAS float* sLt) {
;     f32x4 cur[16];
; #pragma unroll
;     for (int i4 = 0; i4 < 16; ++i4) cur[i4] = *(const PG8_LAS f32x4*)(sLt + 4 * i4);
;     asm volatile("" ::: "memory");
; #pragma unroll
;     for (int j = 0; j < 63; ++j) {
;         const float xj = x[j];
; #pragma unroll
;         for (int i4 = (j + 1) / 4; i4 < 16; ++i4) {
;             if (4 * i4 + 0 > j) x[4 * i4 + 0] -= cur[i4][0] * xj;
;             if (4 * i4 + 1 > j) x[4 * i4 + 1] -= cur[i4][1] * xj;
;             if (4 * i4 + 2 > j) x[4 * i4 + 2] -= cur[i4][2] * xj;
;             if (4 * i4 + 3 > j) x[4 * i4 + 3] -= cur[i4][3] * xj;
;             if (j + 1 < 63 && i4 >= (j + 2) / 4) cur[i4] = *(const PG8_LAS f32x4*)(sLt + (j + 1) * 64 + 4 * i4); }
;         asm volatile("" ::: "memory");
;     }
; }
; __device__ __forceinline__ void phase_prep(const Args& a, PG8_LAS unsigned char* lds) {
;     ...
;             const float bj = sB[lane], bej = bj * sE[lane];
; #pragma unroll
;             for (int i = 0; i < 64; ++i) { *(PG8_LAS bf16_t*)(Tu + (i * 72 + lane) * 2) = f2bf(x[i] * bj); *(PG8_LAS bf16_t*)(Tw + (i * 72 + lane) * 2) = f2bf(x[i] * bej); }
	v_pk_fma_f32 v[56:57], v[84:85], v[14:15], v[56:57] op_sel:[0,1,0] op_sel_hi:[1,1,1] neg_lo:[1,0,0] neg_hi:[1,0,0]
	v_pk_fma_f32 v[58:59], v[86:87], v[14:15], v[58:59] op_sel:[0,1,0] op_sel_hi:[1,1,1] neg_lo:[1,0,0] neg_hi:[1,0,0]
	ds_read_b128 v[84:87], v251 offset:5360
	s_waitcnt lgkmcnt(14)
	v_pk_fma_f32 v[60:61], v[88:89], v[14:15], v[60:61] op_sel:[0,1,0] op_sel_hi:[1,1,1] neg_lo:[1,0,0] neg_hi:[1,0,0]
	v_pk_fma_f32 v[62:63], v[90:91], v[14:15], v[62:63] op_sel:[0,1,0] op_sel_hi:[1,1,1] neg_lo:[1,0,0] neg_hi:[1,0,0]
	ds_read_b128 v[88:91], v251 offset:5440
	v_pk_mul_f32 v[126:127], v[16:17], v[128:129] op_sel:[0,0] op_sel_hi:[0,1]
	s_nop 0
	v_cvt_pk_bf16_f32 v126, v126, v127
	s_nop 0
	ds_write_b16 v205, v126 offset:19712
	ds_write_b16_d16_hi v205, v126 offset:28928
	s_waitcnt lgkmcnt(15)
	v_fma_f32 v17, -v93, v16, v17
	v_pk_fma_f32 v[18:19], v[94:95], v[16:17], v[18:19] op_sel:[0,0,0] op_sel_hi:[1,0,1] neg_lo:[1,0,0] neg_hi:[1,0,0]
	ds_read_b128 v[92:95], v251 offset:5456
	s_waitcnt lgkmcnt(14)
	v_pk_fma_f32 v[20:21], v[230:231], v[16:17], v[20:21] op_sel:[0,0,0] op_sel_hi:[1,0,1] neg_lo:[1,0,0] neg_hi:[1,0,0]
	v_pk_fma_f32 v[22:23], v[232:233], v[16:17], v[22:23] op_sel:[0,0,0] op_sel_hi:[1,0,1] neg_lo:[1,0,0] neg_hi:[1,0,0]
	ds_read_b128 v[230:233], v251 offset:5472
	s_waitcnt lgkmcnt(14)
	v_pk_fma_f32 v[24:25], v[234:235], v[16:17], v[24:25] op_sel:[0,0,0] op_sel_hi:[1,0,1] neg_lo:[1,0,0] neg_hi:[1,0,0]
	v_pk_fma_f32 v[26:27], v[236:237], v[16:17], v[26:27] op_sel:[0,0,0] op_sel_hi:[1,0,1] neg_lo:[1,0,0] neg_hi:[1,0,0]
	ds_read_b128 v[234:237], v251 offset:5488
	s_waitcnt lgkmcnt(14)
	v_pk_fma_f32 v[28:29], v[238:239], v[16:17], v[28:29] op_sel:[0,0,0] op_sel_hi:[1,0,1] neg_lo:[1,0,0] neg_hi:[1,0,0]
	v_pk_fma_f32 v[30:31], v[240:241], v[16:17], v[30:31] op_sel:[0,0,0] op_sel_hi:[1,0,1] neg_lo:[1,0,0] neg_hi:[1,0,0]
	ds_read_b128 v[238:241], v251 offset:5504
	s_waitcnt lgkmcnt(14)
	v_pk_fma_f32 v[32:33], v[242:243], v[16:17], v[32:33] op_sel:[0,0,0] op_sel_hi:[1,0,1] neg_lo:[1,0,0] neg_hi:[1,0,0]
	v_pk_fma_f32 v[34:35], v[244:245], v[16:17], v[34:35] op_sel:[0,0,0] op_sel_hi:[1,0,1] neg_lo:[1,0,0] neg_hi:[1,0,0]
	ds_read_b128 v[242:245], v251 offset:5520
	s_waitcnt lgkmcnt(14)
	v_pk_fma_f32 v[36:37], v[246:247], v[16:17], v[36:37] op_sel:[0,0,0] op_sel_hi:[1,0,1] neg_lo:[1,0,0] neg_hi:[1,0,0]
	v_pk_fma_f32 v[38:39], v[248:249], v[16:17], v[38:39] op_sel:[0,0,0] op_sel_hi:[1,0,1] neg_lo:[1,0,0] neg_hi:[1,0,0]
	ds_read_b128 v[246:249], v251 offset:5536
	s_waitcnt lgkmcnt(14)
	v_pk_fma_f32 v[40:41], v[64:65], v[16:17], v[40:41] op_sel:[0,0,0] op_sel_hi:[1,0,1] neg_lo:[1,0,0] neg_hi:[1,0,0]
	v_pk_fma_f32 v[42:43], v[66:67], v[16:17], v[42:43] op_sel:[0,0,0] op_sel_hi:[1,0,1] neg_lo:[1,0,0] neg_hi:[1,0,0]
	ds_read_b128 v[64:67], v251 offset:5552
	s_waitcnt lgkmcnt(14)
	v_pk_fma_f32 v[44:45], v[68:69], v[16:17], v[44:45] op_sel:[0,0,0] op_sel_hi:[1,0,1] neg_lo:[1,0,0] neg_hi:[1,0,0]
	v_pk_fma_f32 v[46:47], v[70:71], v[16:17], v[46:47] op_sel:[0,0,0] op_sel_hi:[1,0,1] neg_lo:[1,0,0] neg_hi:[1,0,0]
	ds_read_b128 v[68:71], v251 offset:5568
	s_waitcnt lgkmcnt(14)
	v_pk_fma_f32 v[48:49], v[72:73], v[16:17], v[48:49] op_sel:[0,0,0] op_sel_hi:[1,0,1] neg_lo:[1,0,0] neg_hi:[1,0,0]
	v_pk_fma_f32 v[50:51], v[74:75], v[16:17], v[50:51] op_sel:[0,0,0] op_sel_hi:[1,0,1] neg_lo:[1,0,0] neg_hi:[1,0,0]
	ds_read_b128 v[72:75], v251 offset:5584
	s_waitcnt lgkmcnt(14)
	v_pk_fma_f32 v[52:53], v[76:77], v[16:17], v[52:53] op_sel:[0,0,0] op_sel_hi:[1,0,1] neg_lo:[1,0,0] neg_hi:[1,0,0]
	v_pk_fma_f32 v[54:55], v[78:79], v[16:17], v[54:55] op_sel:[0,0,0] op_sel_hi:[1,0,1] neg_lo:[1,0,0] neg_hi:[1,0,0]
	ds_read_b128 v[76:79], v251 offset:5600
	s_waitcnt lgkmcnt(14)
	v_pk_fma_f32 v[56:57], v[80:81], v[16:17], v[56:57] op_sel:[0,0,0] op_sel_hi:[1,0,1] neg_lo:[1,0,0] neg_hi:[1,0,0]
	v_pk_fma_f32 v[58:59], v[82:83], v[16:17], v[58:59] op_sel:[0,0,0] op_sel_hi:[1,0,1] neg_lo:[1,0,0] neg_hi:[1,0,0]
	ds_read_b128 v[80:83], v251 offset:5616
	s_waitcnt lgkmcnt(14)
	v_pk_fma_f32 v[60:61], v[84:85], v[16:17], v[60:61] op_sel:[0,0,0] op_sel_hi:[1,0,1] neg_lo:[1,0,0] neg_hi:[1,0,0]
	v_pk_fma_f32 v[62:63], v[86:87], v[16:17], v[62:63] op_sel:[0,0,0] op_sel_hi:[1,0,1] neg_lo:[1,0,0] neg_hi:[1,0,0]
	ds_read_b128 v[84:87], v251 offset:5696
	v_pk_mul_f32 v[126:127], v[16:17], v[128:129] op_sel:[1,0] op_sel_hi:[1,1]
	s_nop 0
	v_cvt_pk_bf16_f32 v126, v126, v127
	s_nop 0
	ds_write_b16 v205, v126 offset:19856
	ds_write_b16_d16_hi v205, v126 offset:29072
	s_waitcnt lgkmcnt(15)
	v_pk_fma_f32 v[18:19], v[90:91], v[16:17], v[18:19] op_sel:[0,1,0] op_sel_hi:[1,1,1] neg_lo:[1,0,0] neg_hi:[1,0,0]
	ds_read_b128 v[88:91], v251 offset:5712
	s_waitcnt lgkmcnt(14)
	v_pk_fma_f32 v[20:21], v[92:93], v[16:17], v[20:21] op_sel:[0,1,0] op_sel_hi:[1,1,1] neg_lo:[1,0,0] neg_hi:[1,0,0]
	v_pk_fma_f32 v[22:23], v[94:95], v[16:17], v[22:23] op_sel:[0,1,0] op_sel_hi:[1,1,1] neg_lo:[1,0,0] neg_hi:[1,0,0]
	ds_read_b128 v[92:95], v251 offset:5728
	s_waitcnt lgkmcnt(14)
	v_pk_fma_f32 v[24:25], v[230:231], v[16:17], v[24:25] op_sel:[0,1,0] op_sel_hi:[1,1,1] neg_lo:[1,0,0] neg_hi:[1,0,0]
	v_pk_fma_f32 v[26:27], v[232:233], v[16:17], v[26:27] op_sel:[0,1,0] op_sel_hi:[1,1,1] neg_lo:[1,0,0] neg_hi:[1,0,0]
	ds_read_b128 v[230:233], v251 offset:5744
	s_waitcnt lgkmcnt(14)
	v_pk_fma_f32 v[28:29], v[234:235], v[16:17], v[28:29] op_sel:[0,1,0] op_sel_hi:[1,1,1] neg_lo:[1,0,0] neg_hi:[1,0,0]
	v_pk_fma_f32 v[30:31], v[236:237], v[16:17], v[30:31] op_sel:[0,1,0] op_sel_hi:[1,1,1] neg_lo:[1,0,0] neg_hi:[1,0,0]
	ds_read_b128 v[234:237], v251 offset:5760
	s_waitcnt lgkmcnt(14)
; #define PG8_LAS __attribute__((address_space(3)))
; __device__ __forceinline__ bf16_t f2bf(float x) { return (bf16_t)(pk2(x, x) & 0xffffu); }
; __device__ __forceinline__ void solve64(float (&x)[64], const PG8_LAS float* sLt) {
;     f32x4 cur[16];
; #pragma unroll
;     for (int i4 = 0; i4 < 16; ++i4) cur[i4] = *(const PG8_LAS f32x4*)(sLt + 4 * i4);
;     asm volatile("" ::: "memory");
; #pragma unroll
;     for (int j = 0; j < 63; ++j) {
;         const float xj = x[j];
; #pragma unroll
;         for (int i4 = (j + 1) / 4; i4 < 16; ++i4) {
;             if (4 * i4 + 0 > j) x[4 * i4 + 0] -= cur[i4][0] * xj;
;             if (4 * i4 + 1 > j) x[4 * i4 + 1] -= cur[i4][1] * xj;
;             if (4 * i4 + 2 > j) x[4 * i4 + 2] -= cur[i4][2] * xj;
;             if (4 * i4 + 3 > j) x[4 * i4 + 3] -= cur[i4][3] * xj;
;             if (j + 1 < 63 && i4 >= (j + 2) / 4) cur[i4] = *(const PG8_LAS f32x4*)(sLt + (j + 1) * 64 + 4 * i4); }
;         asm volatile("" ::: "memory");
;     }
; }
; __device__ __forceinline__ void phase_prep(const Args& a, PG8_LAS unsigned char* lds) {
;     ...
;             const float bj = sB[lane], bej = bj * sE[lane];
; #pragma unroll
;             for (int i = 0; i < 64; ++i) { *(PG8_LAS bf16_t*)(Tu + (i * 72 + lane) * 2) = f2bf(x[i] * bj); *(PG8_LAS bf16_t*)(Tw + (i * 72 + lane) * 2) = f2bf(x[i] * bej); }
	v_pk_fma_f32 v[32:33], v[238:239], v[16:17], v[32:33] op_sel:[0,1,0] op_sel_hi:[1,1,1] neg_lo:[1,0,0] neg_hi:[1,0,0]
	v_pk_fma_f32 v[34:35], v[240:241], v[16:17], v[34:35] op_sel:[0,1,0] op_sel_hi:[1,1,1] neg_lo:[1,0,0] neg_hi:[1,0,0]
	ds_read_b128 v[238:241], v251 offset:5776
	s_waitcnt lgkmcnt(14)
	v_pk_fma_f32 v[36:37], v[242:243], v[16:17], v[36:37] op_sel:[0,1,0] op_sel_hi:[1,1,1] neg_lo:[1,0,0] neg_hi:[1,0,0]
	v_pk_fma_f32 v[38:39], v[244:245], v[16:17], v[38:39] op_sel:[0,1,0] op_sel_hi:[1,1,1] neg_lo:[1,0,0] neg_hi:[1,0,0]
	ds_read_b128 v[242:245], v251 offset:5792
	s_waitcnt lgkmcnt(14)
	v_pk_fma_f32 v[40:41], v[246:247], v[16:17], v[40:41] op_sel:[0,1,0] op_sel_hi:[1,1,1] neg_lo:[1,0,0] neg_hi:[1,0,0]
	v_pk_fma_f32 v[42:43], v[248:249], v[16:17], v[42:43] op_sel:[0,1,0] op_sel_hi:[1,1,1] neg_lo:[1,0,0] neg_hi:[1,0,0]
	ds_read_b128 v[246:249], v251 offset:5808
	s_waitcnt lgkmcnt(14)
	v_pk_fma_f32 v[44:45], v[64:65], v[16:17], v[44:45] op_sel:[0,1,0] op_sel_hi:[1,1,1] neg_lo:[1,0,0] neg_hi:[1,0,0]
	v_pk_fma_f32 v[46:47], v[66:67], v[16:17], v[46:47] op_sel:[0,1,0] op_sel_hi:[1,1,1] neg_lo:[1,0,0] neg_hi:[1,0,0]
	ds_read_b128 v[64:67], v251 offset:5824
	s_waitcnt lgkmcnt(14)
	v_pk_fma_f32 v[48:49], v[68:69], v[16:17], v[48:49] op_sel:[0,1,0] op_sel_hi:[1,1,1] neg_lo:[1,0,0] neg_hi:[1,0,0]
	v_pk_fma_f32 v[50:51], v[70:71], v[16:17], v[50:51] op_sel:[0,1,0] op_sel_hi:[1,1,1] neg_lo:[1,0,0] neg_hi:[1,0,0]
	ds_read_b128 v[68:71], v251 offset:5840
	s_waitcnt lgkmcnt(14)
	v_pk_fma_f32 v[52:53], v[72:73], v[16:17], v[52:53] op_sel:[0,1,0] op_sel_hi:[1,1,1] neg_lo:[1,0,0] neg_hi:[1,0,0]
	v_pk_fma_f32 v[54:55], v[74:75], v[16:17], v[54:55] op_sel:[0,1,0] op_sel_hi:[1,1,1] neg_lo:[1,0,0] neg_hi:[1,0,0]
	ds_read_b128 v[72:75], v251 offset:5856
	s_waitcnt lgkmcnt(14)
	v_pk_fma_f32 v[56:57], v[76:77], v[16:17], v[56:57] op_sel:[0,1,0] op_sel_hi:[1,1,1] neg_lo:[1,0,0] neg_hi:[1,0,0]
	v_pk_fma_f32 v[58:59], v[78:79], v[16:17], v[58:59] op_sel:[0,1,0] op_sel_hi:[1,1,1] neg_lo:[1,0,0] neg_hi:[1,0,0]
	ds_read_b128 v[76:79], v251 offset:5872
	s_waitcnt lgkmcnt(14)
	v_pk_fma_f32 v[60:61], v[80:81], v[16:17], v[60:61] op_sel:[0,1,0] op_sel_hi:[1,1,1] neg_lo:[1,0,0] neg_hi:[1,0,0]
	v_pk_fma_f32 v[62:63], v[82:83], v[16:17], v[62:63] op_sel:[0,1,0] op_sel_hi:[1,1,1] neg_lo:[1,0,0] neg_hi:[1,0,0]
	ds_read_b128 v[80:83], v251 offset:5968
	v_pk_mul_f32 v[126:127], v[18:19], v[128:129] op_sel:[0,0] op_sel_hi:[0,1]
	s_nop 0
	v_cvt_pk_bf16_f32 v126, v126, v127
	s_nop 0
	ds_write_b16 v205, v126 offset:20000
	ds_write_b16_d16_hi v205, v126 offset:29216
	s_waitcnt lgkmcnt(15)
	v_fma_f32 v19, -v87, v18, v19
	ds_read_b128 v[84:87], v251 offset:5984
	s_waitcnt lgkmcnt(14)
	v_pk_fma_f32 v[20:21], v[88:89], v[18:19], v[20:21] op_sel:[0,0,0] op_sel_hi:[1,0,1] neg_lo:[1,0,0] neg_hi:[1,0,0]
	v_pk_fma_f32 v[22:23], v[90:91], v[18:19], v[22:23] op_sel:[0,0,0] op_sel_hi:[1,0,1] neg_lo:[1,0,0] neg_hi:[1,0,0]
	ds_read_b128 v[88:91], v251 offset:6000
	s_waitcnt lgkmcnt(14)
	v_pk_fma_f32 v[24:25], v[92:93], v[18:19], v[24:25] op_sel:[0,0,0] op_sel_hi:[1,0,1] neg_lo:[1,0,0] neg_hi:[1,0,0]
	v_pk_fma_f32 v[26:27], v[94:95], v[18:19], v[26:27] op_sel:[0,0,0] op_sel_hi:[1,0,1] neg_lo:[1,0,0] neg_hi:[1,0,0]
	ds_read_b128 v[92:95], v251 offset:6016
	s_waitcnt lgkmcnt(14)
	v_pk_fma_f32 v[28:29], v[230:231], v[18:19], v[28:29] op_sel:[0,0,0] op_sel_hi:[1,0,1] neg_lo:[1,0,0] neg_hi:[1,0,0]
	v_pk_fma_f32 v[30:31], v[232:233], v[18:19], v[30:31] op_sel:[0,0,0] op_sel_hi:[1,0,1] neg_lo:[1,0,0] neg_hi:[1,0,0]
	ds_read_b128 v[230:233], v251 offset:6032
	s_waitcnt lgkmcnt(14)
	v_pk_fma_f32 v[32:33], v[234:235], v[18:19], v[32:33] op_sel:[0,0,0] op_sel_hi:[1,0,1] neg_lo:[1,0,0] neg_hi:[1,0,0]
	v_pk_fma_f32 v[34:35], v[236:237], v[18:19], v[34:35] op_sel:[0,0,0] op_sel_hi:[1,0,1] neg_lo:[1,0,0] neg_hi:[1,0,0]
	ds_read_b128 v[234:237], v251 offset:6048
	s_waitcnt lgkmcnt(14)
	v_pk_fma_f32 v[36:37], v[238:239], v[18:19], v[36:37] op_sel:[0,0,0] op_sel_hi:[1,0,1] neg_lo:[1,0,0] neg_hi:[1,0,0]
	v_pk_fma_f32 v[38:39], v[240:241], v[18:19], v[38:39] op_sel:[0,0,0] op_sel_hi:[1,0,1] neg_lo:[1,0,0] neg_hi:[1,0,0]
	ds_read_b128 v[238:241], v251 offset:6064
	s_waitcnt lgkmcnt(14)
	v_pk_fma_f32 v[40:41], v[242:243], v[18:19], v[40:41] op_sel:[0,0,0] op_sel_hi:[1,0,1] neg_lo:[1,0,0] neg_hi:[1,0,0]
	v_pk_fma_f32 v[42:43], v[244:245], v[18:19], v[42:43] op_sel:[0,0,0] op_sel_hi:[1,0,1] neg_lo:[1,0,0] neg_hi:[1,0,0]
	ds_read_b128 v[242:245], v251 offset:6080
	s_waitcnt lgkmcnt(14)
	v_pk_fma_f32 v[44:45], v[246:247], v[18:19], v[44:45] op_sel:[0,0,0] op_sel_hi:[1,0,1] neg_lo:[1,0,0] neg_hi:[1,0,0]
	v_pk_fma_f32 v[46:47], v[248:249], v[18:19], v[46:47] op_sel:[0,0,0] op_sel_hi:[1,0,1] neg_lo:[1,0,0] neg_hi:[1,0,0]
	ds_read_b128 v[246:249], v251 offset:6096
	s_waitcnt lgkmcnt(14)
	v_pk_fma_f32 v[48:49], v[64:65], v[18:19], v[48:49] op_sel:[0,0,0] op_sel_hi:[1,0,1] neg_lo:[1,0,0] neg_hi:[1,0,0]
	v_pk_fma_f32 v[50:51], v[66:67], v[18:19], v[50:51] op_sel:[0,0,0] op_sel_hi:[1,0,1] neg_lo:[1,0,0] neg_hi:[1,0,0]
	ds_read_b128 v[64:67], v251 offset:6112
	s_waitcnt lgkmcnt(14)
	v_pk_fma_f32 v[52:53], v[68:69], v[18:19], v[52:53] op_sel:[0,0,0] op_sel_hi:[1,0,1] neg_lo:[1,0,0] neg_hi:[1,0,0]
	v_pk_fma_f32 v[54:55], v[70:71], v[18:19], v[54:55] op_sel:[0,0,0] op_sel_hi:[1,0,1] neg_lo:[1,0,0] neg_hi:[1,0,0]
	ds_read_b128 v[68:71], v251 offset:6128
	s_waitcnt lgkmcnt(14)
	v_pk_fma_f32 v[56:57], v[72:73], v[18:19], v[56:57] op_sel:[0,0,0] op_sel_hi:[1,0,1] neg_lo:[1,0,0] neg_hi:[1,0,0]
	v_pk_fma_f32 v[58:59], v[74:75], v[18:19], v[58:59] op_sel:[0,0,0] op_sel_hi:[1,0,1] neg_lo:[1,0,0] neg_hi:[1,0,0]
	ds_read_b128 v[72:75], v251 offset:6224
	s_waitcnt lgkmcnt(14)
; #define PG8_LAS __attribute__((address_space(3)))
; __device__ __forceinline__ bf16_t f2bf(float x) { return (bf16_t)(pk2(x, x) & 0xffffu); }
; __device__ __forceinline__ void solve64(float (&x)[64], const PG8_LAS float* sLt) {
;     f32x4 cur[16];
; #pragma unroll
;     for (int i4 = 0; i4 < 16; ++i4) cur[i4] = *(const PG8_LAS f32x4*)(sLt + 4 * i4);
;     asm volatile("" ::: "memory");
; #pragma unroll
;     for (int j = 0; j < 63; ++j) {
;         const float xj = x[j];
; #pragma unroll
;         for (int i4 = (j + 1) / 4; i4 < 16; ++i4) {
;             if (4 * i4 + 0 > j) x[4 * i4 + 0] -= cur[i4][0] * xj;
;             if (4 * i4 + 1 > j) x[4 * i4 + 1] -= cur[i4][1] * xj;
;             if (4 * i4 + 2 > j) x[4 * i4 + 2] -= cur[i4][2] * xj;
;             if (4 * i4 + 3 > j) x[4 * i4 + 3] -= cur[i4][3] * xj;
;             if (j + 1 < 63 && i4 >= (j + 2) / 4) cur[i4] = *(const PG8_LAS f32x4*)(sLt + (j + 1) * 64 + 4 * i4); }
;         asm volatile("" ::: "memory");
;     }
; }
; __device__ __forceinline__ void phase_prep(const Args& a, PG8_LAS unsigned char* lds) {
;     ...
;             const float bj = sB[lane], bej = bj * sE[lane];
; #pragma unroll
;             for (int i = 0; i < 64; ++i) { *(PG8_LAS bf16_t*)(Tu + (i * 72 + lane) * 2) = f2bf(x[i] * bj); *(PG8_LAS bf16_t*)(Tw + (i * 72 + lane) * 2) = f2bf(x[i] * bej); }
	v_pk_fma_f32 v[60:61], v[76:77], v[18:19], v[60:61] op_sel:[0,0,0] op_sel_hi:[1,0,1] neg_lo:[1,0,0] neg_hi:[1,0,0]
	v_pk_fma_f32 v[62:63], v[78:79], v[18:19], v[62:63] op_sel:[0,0,0] op_sel_hi:[1,0,1] neg_lo:[1,0,0] neg_hi:[1,0,0]
	ds_read_b128 v[76:79], v251 offset:6240
	v_pk_mul_f32 v[126:127], v[18:19], v[128:129] op_sel:[1,0] op_sel_hi:[1,1]
	s_nop 0
	v_cvt_pk_bf16_f32 v126, v126, v127
	s_nop 0
	ds_write_b16 v205, v126 offset:20144
	ds_write_b16_d16_hi v205, v126 offset:29360
	s_waitcnt lgkmcnt(15)
	v_pk_fma_f32 v[20:21], v[80:81], v[18:19], v[20:21] op_sel:[0,1,0] op_sel_hi:[1,1,1] neg_lo:[1,0,0] neg_hi:[1,0,0]
	v_pk_fma_f32 v[22:23], v[82:83], v[18:19], v[22:23] op_sel:[0,1,0] op_sel_hi:[1,1,1] neg_lo:[1,0,0] neg_hi:[1,0,0]
	ds_read_b128 v[80:83], v251 offset:6256
	s_waitcnt lgkmcnt(14)
	v_pk_fma_f32 v[24:25], v[84:85], v[18:19], v[24:25] op_sel:[0,1,0] op_sel_hi:[1,1,1] neg_lo:[1,0,0] neg_hi:[1,0,0]
	v_pk_fma_f32 v[26:27], v[86:87], v[18:19], v[26:27] op_sel:[0,1,0] op_sel_hi:[1,1,1] neg_lo:[1,0,0] neg_hi:[1,0,0]
	ds_read_b128 v[84:87], v251 offset:6272
	s_waitcnt lgkmcnt(14)
	v_pk_fma_f32 v[28:29], v[88:89], v[18:19], v[28:29] op_sel:[0,1,0] op_sel_hi:[1,1,1] neg_lo:[1,0,0] neg_hi:[1,0,0]
	v_pk_fma_f32 v[30:31], v[90:91], v[18:19], v[30:31] op_sel:[0,1,0] op_sel_hi:[1,1,1] neg_lo:[1,0,0] neg_hi:[1,0,0]
	ds_read_b128 v[88:91], v251 offset:6288
	s_waitcnt lgkmcnt(14)
	v_pk_fma_f32 v[32:33], v[92:93], v[18:19], v[32:33] op_sel:[0,1,0] op_sel_hi:[1,1,1] neg_lo:[1,0,0] neg_hi:[1,0,0]
	v_pk_fma_f32 v[34:35], v[94:95], v[18:19], v[34:35] op_sel:[0,1,0] op_sel_hi:[1,1,1] neg_lo:[1,0,0] neg_hi:[1,0,0]
	ds_read_b128 v[92:95], v251 offset:6304
	s_waitcnt lgkmcnt(14)
	v_pk_fma_f32 v[36:37], v[230:231], v[18:19], v[36:37] op_sel:[0,1,0] op_sel_hi:[1,1,1] neg_lo:[1,0,0] neg_hi:[1,0,0]
	v_pk_fma_f32 v[38:39], v[232:233], v[18:19], v[38:39] op_sel:[0,1,0] op_sel_hi:[1,1,1] neg_lo:[1,0,0] neg_hi:[1,0,0]
	ds_read_b128 v[230:233], v251 offset:6320
	s_waitcnt lgkmcnt(14)
	v_pk_fma_f32 v[40:41], v[234:235], v[18:19], v[40:41] op_sel:[0,1,0] op_sel_hi:[1,1,1] neg_lo:[1,0,0] neg_hi:[1,0,0]
	v_pk_fma_f32 v[42:43], v[236:237], v[18:19], v[42:43] op_sel:[0,1,0] op_sel_hi:[1,1,1] neg_lo:[1,0,0] neg_hi:[1,0,0]
	ds_read_b128 v[234:237], v251 offset:6336
	s_waitcnt lgkmcnt(14)
	v_pk_fma_f32 v[44:45], v[238:239], v[18:19], v[44:45] op_sel:[0,1,0] op_sel_hi:[1,1,1] neg_lo:[1,0,0] neg_hi:[1,0,0]
	v_pk_fma_f32 v[46:47], v[240:241], v[18:19], v[46:47] op_sel:[0,1,0] op_sel_hi:[1,1,1] neg_lo:[1,0,0] neg_hi:[1,0,0]
	ds_read_b128 v[238:241], v251 offset:6352
	s_waitcnt lgkmcnt(14)
	v_pk_fma_f32 v[48:49], v[242:243], v[18:19], v[48:49] op_sel:[0,1,0] op_sel_hi:[1,1,1] neg_lo:[1,0,0] neg_hi:[1,0,0]
	v_pk_fma_f32 v[50:51], v[244:245], v[18:19], v[50:51] op_sel:[0,1,0] op_sel_hi:[1,1,1] neg_lo:[1,0,0] neg_hi:[1,0,0]
	ds_read_b128 v[242:245], v251 offset:6368
	s_waitcnt lgkmcnt(14)
	v_pk_fma_f32 v[52:53], v[246:247], v[18:19], v[52:53] op_sel:[0,1,0] op_sel_hi:[1,1,1] neg_lo:[1,0,0] neg_hi:[1,0,0]
	v_pk_fma_f32 v[54:55], v[248:249], v[18:19], v[54:55] op_sel:[0,1,0] op_sel_hi:[1,1,1] neg_lo:[1,0,0] neg_hi:[1,0,0]
	ds_read_b128 v[246:249], v251 offset:6384
	s_waitcnt lgkmcnt(14)
	v_pk_fma_f32 v[56:57], v[64:65], v[18:19], v[56:57] op_sel:[0,1,0] op_sel_hi:[1,1,1] neg_lo:[1,0,0] neg_hi:[1,0,0]
	v_pk_fma_f32 v[58:59], v[66:67], v[18:19], v[58:59] op_sel:[0,1,0] op_sel_hi:[1,1,1] neg_lo:[1,0,0] neg_hi:[1,0,0]
	ds_read_b128 v[64:67], v251 offset:6480
	s_waitcnt lgkmcnt(14)
	v_pk_fma_f32 v[60:61], v[68:69], v[18:19], v[60:61] op_sel:[0,1,0] op_sel_hi:[1,1,1] neg_lo:[1,0,0] neg_hi:[1,0,0]
	v_pk_fma_f32 v[62:63], v[70:71], v[18:19], v[62:63] op_sel:[0,1,0] op_sel_hi:[1,1,1] neg_lo:[1,0,0] neg_hi:[1,0,0]
	ds_read_b128 v[68:71], v251 offset:6496
	v_pk_mul_f32 v[126:127], v[20:21], v[128:129] op_sel:[0,0] op_sel_hi:[0,1]
	s_nop 0
	v_cvt_pk_bf16_f32 v126, v126, v127
	s_nop 0
	ds_write_b16 v205, v126 offset:20288
	ds_write_b16_d16_hi v205, v126 offset:29504
	s_waitcnt lgkmcnt(15)
	v_fma_f32 v21, -v73, v20, v21
	v_pk_fma_f32 v[22:23], v[74:75], v[20:21], v[22:23] op_sel:[0,0,0] op_sel_hi:[1,0,1] neg_lo:[1,0,0] neg_hi:[1,0,0]
	ds_read_b128 v[72:75], v251 offset:6512
	s_waitcnt lgkmcnt(15)
	v_pk_fma_f32 v[24:25], v[76:77], v[20:21], v[24:25] op_sel:[0,0,0] op_sel_hi:[1,0,1] neg_lo:[1,0,0] neg_hi:[1,0,0]
	v_pk_fma_f32 v[26:27], v[78:79], v[20:21], v[26:27] op_sel:[0,0,0] op_sel_hi:[1,0,1] neg_lo:[1,0,0] neg_hi:[1,0,0]
	ds_read_b128 v[76:79], v251 offset:6528
	s_waitcnt lgkmcnt(14)
	v_pk_fma_f32 v[28:29], v[80:81], v[20:21], v[28:29] op_sel:[0,0,0] op_sel_hi:[1,0,1] neg_lo:[1,0,0] neg_hi:[1,0,0]
	v_pk_fma_f32 v[30:31], v[82:83], v[20:21], v[30:31] op_sel:[0,0,0] op_sel_hi:[1,0,1] neg_lo:[1,0,0] neg_hi:[1,0,0]
	ds_read_b128 v[80:83], v251 offset:6544
	s_waitcnt lgkmcnt(14)
	v_pk_fma_f32 v[32:33], v[84:85], v[20:21], v[32:33] op_sel:[0,0,0] op_sel_hi:[1,0,1] neg_lo:[1,0,0] neg_hi:[1,0,0]
	v_pk_fma_f32 v[34:35], v[86:87], v[20:21], v[34:35] op_sel:[0,0,0] op_sel_hi:[1,0,1] neg_lo:[1,0,0] neg_hi:[1,0,0]
	ds_read_b128 v[84:87], v251 offset:6560
	s_waitcnt lgkmcnt(14)
	v_pk_fma_f32 v[36:37], v[88:89], v[20:21], v[36:37] op_sel:[0,0,0] op_sel_hi:[1,0,1] neg_lo:[1,0,0] neg_hi:[1,0,0]
	v_pk_fma_f32 v[38:39], v[90:91], v[20:21], v[38:39] op_sel:[0,0,0] op_sel_hi:[1,0,1] neg_lo:[1,0,0] neg_hi:[1,0,0]
	ds_read_b128 v[88:91], v251 offset:6576
	s_waitcnt lgkmcnt(14)
	v_pk_fma_f32 v[40:41], v[92:93], v[20:21], v[40:41] op_sel:[0,0,0] op_sel_hi:[1,0,1] neg_lo:[1,0,0] neg_hi:[1,0,0]
	v_pk_fma_f32 v[42:43], v[94:95], v[20:21], v[42:43] op_sel:[0,0,0] op_sel_hi:[1,0,1] neg_lo:[1,0,0] neg_hi:[1,0,0]
	ds_read_b128 v[92:95], v251 offset:6592
	s_waitcnt lgkmcnt(14)
; #define PG8_LAS __attribute__((address_space(3)))
; __device__ __forceinline__ bf16_t f2bf(float x) { return (bf16_t)(pk2(x, x) & 0xffffu); }
; __device__ __forceinline__ void solve64(float (&x)[64], const PG8_LAS float* sLt) {
;     f32x4 cur[16];
; #pragma unroll
;     for (int i4 = 0; i4 < 16; ++i4) cur[i4] = *(const PG8_LAS f32x4*)(sLt + 4 * i4);
;     asm volatile("" ::: "memory");
; #pragma unroll
;     for (int j = 0; j < 63; ++j) {
;         const float xj = x[j];
; #pragma unroll
;         for (int i4 = (j + 1) / 4; i4 < 16; ++i4) {
;             if (4 * i4 + 0 > j) x[4 * i4 + 0] -= cur[i4][0] * xj;
;             if (4 * i4 + 1 > j) x[4 * i4 + 1] -= cur[i4][1] * xj;
;             if (4 * i4 + 2 > j) x[4 * i4 + 2] -= cur[i4][2] * xj;
;             if (4 * i4 + 3 > j) x[4 * i4 + 3] -= cur[i4][3] * xj;
;             if (j + 1 < 63 && i4 >= (j + 2) / 4) cur[i4] = *(const PG8_LAS f32x4*)(sLt + (j + 1) * 64 + 4 * i4); }
;         asm volatile("" ::: "memory");
;     }
; }
; __device__ __forceinline__ void phase_prep(const Args& a, PG8_LAS unsigned char* lds) {
;     ...
;             const float bj = sB[lane], bej = bj * sE[lane];
; #pragma unroll
;             for (int i = 0; i < 64; ++i) { *(PG8_LAS bf16_t*)(Tu + (i * 72 + lane) * 2) = f2bf(x[i] * bj); *(PG8_LAS bf16_t*)(Tw + (i * 72 + lane) * 2) = f2bf(x[i] * bej); }
	v_pk_fma_f32 v[44:45], v[230:231], v[20:21], v[44:45] op_sel:[0,0,0] op_sel_hi:[1,0,1] neg_lo:[1,0,0] neg_hi:[1,0,0]
	v_pk_fma_f32 v[46:47], v[232:233], v[20:21], v[46:47] op_sel:[0,0,0] op_sel_hi:[1,0,1] neg_lo:[1,0,0] neg_hi:[1,0,0]
	ds_read_b128 v[230:233], v251 offset:6608
	s_waitcnt lgkmcnt(14)
	v_pk_fma_f32 v[48:49], v[234:235], v[20:21], v[48:49] op_sel:[0,0,0] op_sel_hi:[1,0,1] neg_lo:[1,0,0] neg_hi:[1,0,0]
	v_pk_fma_f32 v[50:51], v[236:237], v[20:21], v[50:51] op_sel:[0,0,0] op_sel_hi:[1,0,1] neg_lo:[1,0,0] neg_hi:[1,0,0]
	ds_read_b128 v[234:237], v251 offset:6624
	s_waitcnt lgkmcnt(14)
	v_pk_fma_f32 v[52:53], v[238:239], v[20:21], v[52:53] op_sel:[0,0,0] op_sel_hi:[1,0,1] neg_lo:[1,0,0] neg_hi:[1,0,0]
	v_pk_fma_f32 v[54:55], v[240:241], v[20:21], v[54:55] op_sel:[0,0,0] op_sel_hi:[1,0,1] neg_lo:[1,0,0] neg_hi:[1,0,0]
	ds_read_b128 v[238:241], v251 offset:6640
	s_waitcnt lgkmcnt(14)
	v_pk_fma_f32 v[56:57], v[242:243], v[20:21], v[56:57] op_sel:[0,0,0] op_sel_hi:[1,0,1] neg_lo:[1,0,0] neg_hi:[1,0,0]
	v_pk_fma_f32 v[58:59], v[244:245], v[20:21], v[58:59] op_sel:[0,0,0] op_sel_hi:[1,0,1] neg_lo:[1,0,0] neg_hi:[1,0,0]
	ds_read_b128 v[242:245], v251 offset:6736
	s_waitcnt lgkmcnt(14)
	v_pk_fma_f32 v[60:61], v[246:247], v[20:21], v[60:61] op_sel:[0,0,0] op_sel_hi:[1,0,1] neg_lo:[1,0,0] neg_hi:[1,0,0]
	v_pk_fma_f32 v[62:63], v[248:249], v[20:21], v[62:63] op_sel:[0,0,0] op_sel_hi:[1,0,1] neg_lo:[1,0,0] neg_hi:[1,0,0]
	ds_read_b128 v[246:249], v251 offset:6752
	v_pk_mul_f32 v[126:127], v[20:21], v[128:129] op_sel:[1,0] op_sel_hi:[1,1]
	s_nop 0
	v_cvt_pk_bf16_f32 v126, v126, v127
	s_nop 0
	ds_write_b16 v205, v126 offset:20432
	ds_write_b16_d16_hi v205, v126 offset:29648
	s_waitcnt lgkmcnt(15)
	v_pk_fma_f32 v[22:23], v[66:67], v[20:21], v[22:23] op_sel:[0,1,0] op_sel_hi:[1,1,1] neg_lo:[1,0,0] neg_hi:[1,0,0]
	ds_read_b128 v[64:67], v251 offset:6768
	s_waitcnt lgkmcnt(15)
	v_pk_fma_f32 v[24:25], v[68:69], v[20:21], v[24:25] op_sel:[0,1,0] op_sel_hi:[1,1,1] neg_lo:[1,0,0] neg_hi:[1,0,0]
	v_pk_fma_f32 v[26:27], v[70:71], v[20:21], v[26:27] op_sel:[0,1,0] op_sel_hi:[1,1,1] neg_lo:[1,0,0] neg_hi:[1,0,0]
	ds_read_b128 v[68:71], v251 offset:6784
	s_waitcnt lgkmcnt(14)
	v_pk_fma_f32 v[28:29], v[72:73], v[20:21], v[28:29] op_sel:[0,1,0] op_sel_hi:[1,1,1] neg_lo:[1,0,0] neg_hi:[1,0,0]
	v_pk_fma_f32 v[30:31], v[74:75], v[20:21], v[30:31] op_sel:[0,1,0] op_sel_hi:[1,1,1] neg_lo:[1,0,0] neg_hi:[1,0,0]
	ds_read_b128 v[72:75], v251 offset:6800
	s_waitcnt lgkmcnt(14)
	v_pk_fma_f32 v[32:33], v[76:77], v[20:21], v[32:33] op_sel:[0,1,0] op_sel_hi:[1,1,1] neg_lo:[1,0,0] neg_hi:[1,0,0]
	v_pk_fma_f32 v[34:35], v[78:79], v[20:21], v[34:35] op_sel:[0,1,0] op_sel_hi:[1,1,1] neg_lo:[1,0,0] neg_hi:[1,0,0]
	ds_read_b128 v[76:79], v251 offset:6816
	s_waitcnt lgkmcnt(14)
	v_pk_fma_f32 v[36:37], v[80:81], v[20:21], v[36:37] op_sel:[0,1,0] op_sel_hi:[1,1,1] neg_lo:[1,0,0] neg_hi:[1,0,0]
	v_pk_fma_f32 v[38:39], v[82:83], v[20:21], v[38:39] op_sel:[0,1,0] op_sel_hi:[1,1,1] neg_lo:[1,0,0] neg_hi:[1,0,0]
	ds_read_b128 v[80:83], v251 offset:6832
	s_waitcnt lgkmcnt(14)
	v_pk_fma_f32 v[40:41], v[84:85], v[20:21], v[40:41] op_sel:[0,1,0] op_sel_hi:[1,1,1] neg_lo:[1,0,0] neg_hi:[1,0,0]
	v_pk_fma_f32 v[42:43], v[86:87], v[20:21], v[42:43] op_sel:[0,1,0] op_sel_hi:[1,1,1] neg_lo:[1,0,0] neg_hi:[1,0,0]
	ds_read_b128 v[84:87], v251 offset:6848
	s_waitcnt lgkmcnt(14)
	v_pk_fma_f32 v[44:45], v[88:89], v[20:21], v[44:45] op_sel:[0,1,0] op_sel_hi:[1,1,1] neg_lo:[1,0,0] neg_hi:[1,0,0]
	v_pk_fma_f32 v[46:47], v[90:91], v[20:21], v[46:47] op_sel:[0,1,0] op_sel_hi:[1,1,1] neg_lo:[1,0,0] neg_hi:[1,0,0]
	ds_read_b128 v[88:91], v251 offset:6864
	s_waitcnt lgkmcnt(14)
	v_pk_fma_f32 v[48:49], v[92:93], v[20:21], v[48:49] op_sel:[0,1,0] op_sel_hi:[1,1,1] neg_lo:[1,0,0] neg_hi:[1,0,0]
	v_pk_fma_f32 v[50:51], v[94:95], v[20:21], v[50:51] op_sel:[0,1,0] op_sel_hi:[1,1,1] neg_lo:[1,0,0] neg_hi:[1,0,0]
	ds_read_b128 v[92:95], v251 offset:6880
	s_waitcnt lgkmcnt(14)
	v_pk_fma_f32 v[52:53], v[230:231], v[20:21], v[52:53] op_sel:[0,1,0] op_sel_hi:[1,1,1] neg_lo:[1,0,0] neg_hi:[1,0,0]
	v_pk_fma_f32 v[54:55], v[232:233], v[20:21], v[54:55] op_sel:[0,1,0] op_sel_hi:[1,1,1] neg_lo:[1,0,0] neg_hi:[1,0,0]
	ds_read_b128 v[230:233], v251 offset:6896
	s_waitcnt lgkmcnt(14)
	v_pk_fma_f32 v[56:57], v[234:235], v[20:21], v[56:57] op_sel:[0,1,0] op_sel_hi:[1,1,1] neg_lo:[1,0,0] neg_hi:[1,0,0]
	v_pk_fma_f32 v[58:59], v[236:237], v[20:21], v[58:59] op_sel:[0,1,0] op_sel_hi:[1,1,1] neg_lo:[1,0,0] neg_hi:[1,0,0]
	ds_read_b128 v[234:237], v251 offset:7008
	s_waitcnt lgkmcnt(14)
	v_pk_fma_f32 v[60:61], v[238:239], v[20:21], v[60:61] op_sel:[0,1,0] op_sel_hi:[1,1,1] neg_lo:[1,0,0] neg_hi:[1,0,0]
	v_pk_fma_f32 v[62:63], v[240:241], v[20:21], v[62:63] op_sel:[0,1,0] op_sel_hi:[1,1,1] neg_lo:[1,0,0] neg_hi:[1,0,0]
	ds_read_b128 v[238:241], v251 offset:7024
	v_pk_mul_f32 v[126:127], v[22:23], v[128:129] op_sel:[0,0] op_sel_hi:[0,1]
	s_nop 0
	v_cvt_pk_bf16_f32 v126, v126, v127
	s_nop 0
	ds_write_b16 v205, v126 offset:20576
	ds_write_b16_d16_hi v205, v126 offset:29792
	s_waitcnt lgkmcnt(15)
	v_fma_f32 v23, -v245, v22, v23
	ds_read_b128 v[242:245], v251 offset:7040
	s_waitcnt lgkmcnt(15)
	v_pk_fma_f32 v[24:25], v[246:247], v[22:23], v[24:25] op_sel:[0,0,0] op_sel_hi:[1,0,1] neg_lo:[1,0,0] neg_hi:[1,0,0]
	v_pk_fma_f32 v[26:27], v[248:249], v[22:23], v[26:27] op_sel:[0,0,0] op_sel_hi:[1,0,1] neg_lo:[1,0,0] neg_hi:[1,0,0]
	ds_read_b128 v[246:249], v251 offset:7056
	s_waitcnt lgkmcnt(14)
; #define PG8_LAS __attribute__((address_space(3)))
; __device__ __forceinline__ bf16_t f2bf(float x) { return (bf16_t)(pk2(x, x) & 0xffffu); }
; __device__ __forceinline__ void solve64(float (&x)[64], const PG8_LAS float* sLt) {
;     f32x4 cur[16];
; #pragma unroll
;     for (int i4 = 0; i4 < 16; ++i4) cur[i4] = *(const PG8_LAS f32x4*)(sLt + 4 * i4);
;     asm volatile("" ::: "memory");
; #pragma unroll
;     for (int j = 0; j < 63; ++j) {
;         const float xj = x[j];
; #pragma unroll
;         for (int i4 = (j + 1) / 4; i4 < 16; ++i4) {
;             if (4 * i4 + 0 > j) x[4 * i4 + 0] -= cur[i4][0] * xj;
;             if (4 * i4 + 1 > j) x[4 * i4 + 1] -= cur[i4][1] * xj;
;             if (4 * i4 + 2 > j) x[4 * i4 + 2] -= cur[i4][2] * xj;
;             if (4 * i4 + 3 > j) x[4 * i4 + 3] -= cur[i4][3] * xj;
;             if (j + 1 < 63 && i4 >= (j + 2) / 4) cur[i4] = *(const PG8_LAS f32x4*)(sLt + (j + 1) * 64 + 4 * i4); }
;         asm volatile("" ::: "memory");
;     }
; }
; __device__ __forceinline__ void phase_prep(const Args& a, PG8_LAS unsigned char* lds) {
;     ...
;             const float bj = sB[lane], bej = bj * sE[lane];
; #pragma unroll
;             for (int i = 0; i < 64; ++i) { *(PG8_LAS bf16_t*)(Tu + (i * 72 + lane) * 2) = f2bf(x[i] * bj); *(PG8_LAS bf16_t*)(Tw + (i * 72 + lane) * 2) = f2bf(x[i] * bej); }
	v_pk_fma_f32 v[28:29], v[64:65], v[22:23], v[28:29] op_sel:[0,0,0] op_sel_hi:[1,0,1] neg_lo:[1,0,0] neg_hi:[1,0,0]
	v_pk_fma_f32 v[30:31], v[66:67], v[22:23], v[30:31] op_sel:[0,0,0] op_sel_hi:[1,0,1] neg_lo:[1,0,0] neg_hi:[1,0,0]
	ds_read_b128 v[64:67], v251 offset:7072
	s_waitcnt lgkmcnt(14)
	v_pk_fma_f32 v[32:33], v[68:69], v[22:23], v[32:33] op_sel:[0,0,0] op_sel_hi:[1,0,1] neg_lo:[1,0,0] neg_hi:[1,0,0]
	v_pk_fma_f32 v[34:35], v[70:71], v[22:23], v[34:35] op_sel:[0,0,0] op_sel_hi:[1,0,1] neg_lo:[1,0,0] neg_hi:[1,0,0]
	ds_read_b128 v[68:71], v251 offset:7088
	s_waitcnt lgkmcnt(14)
	v_pk_fma_f32 v[36:37], v[72:73], v[22:23], v[36:37] op_sel:[0,0,0] op_sel_hi:[1,0,1] neg_lo:[1,0,0] neg_hi:[1,0,0]
	v_pk_fma_f32 v[38:39], v[74:75], v[22:23], v[38:39] op_sel:[0,0,0] op_sel_hi:[1,0,1] neg_lo:[1,0,0] neg_hi:[1,0,0]
	ds_read_b128 v[72:75], v251 offset:7104
	s_waitcnt lgkmcnt(14)
	v_pk_fma_f32 v[40:41], v[76:77], v[22:23], v[40:41] op_sel:[0,0,0] op_sel_hi:[1,0,1] neg_lo:[1,0,0] neg_hi:[1,0,0]
	v_pk_fma_f32 v[42:43], v[78:79], v[22:23], v[42:43] op_sel:[0,0,0] op_sel_hi:[1,0,1] neg_lo:[1,0,0] neg_hi:[1,0,0]
	ds_read_b128 v[76:79], v251 offset:7120
	s_waitcnt lgkmcnt(14)
	v_pk_fma_f32 v[44:45], v[80:81], v[22:23], v[44:45] op_sel:[0,0,0] op_sel_hi:[1,0,1] neg_lo:[1,0,0] neg_hi:[1,0,0]
	v_pk_fma_f32 v[46:47], v[82:83], v[22:23], v[46:47] op_sel:[0,0,0] op_sel_hi:[1,0,1] neg_lo:[1,0,0] neg_hi:[1,0,0]
	ds_read_b128 v[80:83], v251 offset:7136
	s_waitcnt lgkmcnt(14)
	v_pk_fma_f32 v[48:49], v[84:85], v[22:23], v[48:49] op_sel:[0,0,0] op_sel_hi:[1,0,1] neg_lo:[1,0,0] neg_hi:[1,0,0]
	v_pk_fma_f32 v[50:51], v[86:87], v[22:23], v[50:51] op_sel:[0,0,0] op_sel_hi:[1,0,1] neg_lo:[1,0,0] neg_hi:[1,0,0]
	ds_read_b128 v[84:87], v251 offset:7152
	s_waitcnt lgkmcnt(14)
	v_pk_fma_f32 v[52:53], v[88:89], v[22:23], v[52:53] op_sel:[0,0,0] op_sel_hi:[1,0,1] neg_lo:[1,0,0] neg_hi:[1,0,0]
	v_pk_fma_f32 v[54:55], v[90:91], v[22:23], v[54:55] op_sel:[0,0,0] op_sel_hi:[1,0,1] neg_lo:[1,0,0] neg_hi:[1,0,0]
	ds_read_b128 v[88:91], v251 offset:7264
	s_waitcnt lgkmcnt(14)
	v_pk_fma_f32 v[56:57], v[92:93], v[22:23], v[56:57] op_sel:[0,0,0] op_sel_hi:[1,0,1] neg_lo:[1,0,0] neg_hi:[1,0,0]
	v_pk_fma_f32 v[58:59], v[94:95], v[22:23], v[58:59] op_sel:[0,0,0] op_sel_hi:[1,0,1] neg_lo:[1,0,0] neg_hi:[1,0,0]
	ds_read_b128 v[92:95], v251 offset:7280
	s_waitcnt lgkmcnt(14)
	v_pk_fma_f32 v[60:61], v[230:231], v[22:23], v[60:61] op_sel:[0,0,0] op_sel_hi:[1,0,1] neg_lo:[1,0,0] neg_hi:[1,0,0]
	v_pk_fma_f32 v[62:63], v[232:233], v[22:23], v[62:63] op_sel:[0,0,0] op_sel_hi:[1,0,1] neg_lo:[1,0,0] neg_hi:[1,0,0]
	ds_read_b128 v[230:233], v251 offset:7296
	v_pk_mul_f32 v[126:127], v[22:23], v[128:129] op_sel:[1,0] op_sel_hi:[1,1]
	s_nop 0
	v_cvt_pk_bf16_f32 v126, v126, v127
	s_nop 0
	ds_write_b16 v205, v126 offset:20720
	ds_write_b16_d16_hi v205, v126 offset:29936
	s_waitcnt lgkmcnt(15)
	v_pk_fma_f32 v[24:25], v[234:235], v[22:23], v[24:25] op_sel:[0,1,0] op_sel_hi:[1,1,1] neg_lo:[1,0,0] neg_hi:[1,0,0]
	v_pk_fma_f32 v[26:27], v[236:237], v[22:23], v[26:27] op_sel:[0,1,0] op_sel_hi:[1,1,1] neg_lo:[1,0,0] neg_hi:[1,0,0]
	ds_read_b128 v[234:237], v251 offset:7312
	s_waitcnt lgkmcnt(15)
	v_pk_fma_f32 v[28:29], v[238:239], v[22:23], v[28:29] op_sel:[0,1,0] op_sel_hi:[1,1,1] neg_lo:[1,0,0] neg_hi:[1,0,0]
	v_pk_fma_f32 v[30:31], v[240:241], v[22:23], v[30:31] op_sel:[0,1,0] op_sel_hi:[1,1,1] neg_lo:[1,0,0] neg_hi:[1,0,0]
	ds_read_b128 v[238:241], v251 offset:7328
	s_waitcnt lgkmcnt(14)
	v_pk_fma_f32 v[32:33], v[242:243], v[22:23], v[32:33] op_sel:[0,1,0] op_sel_hi:[1,1,1] neg_lo:[1,0,0] neg_hi:[1,0,0]
	v_pk_fma_f32 v[34:35], v[244:245], v[22:23], v[34:35] op_sel:[0,1,0] op_sel_hi:[1,1,1] neg_lo:[1,0,0] neg_hi:[1,0,0]
	ds_read_b128 v[242:245], v251 offset:7344
	s_waitcnt lgkmcnt(14)
	v_pk_fma_f32 v[36:37], v[246:247], v[22:23], v[36:37] op_sel:[0,1,0] op_sel_hi:[1,1,1] neg_lo:[1,0,0] neg_hi:[1,0,0]
	v_pk_fma_f32 v[38:39], v[248:249], v[22:23], v[38:39] op_sel:[0,1,0] op_sel_hi:[1,1,1] neg_lo:[1,0,0] neg_hi:[1,0,0]
	ds_read_b128 v[246:249], v251 offset:7360
	s_waitcnt lgkmcnt(14)
	v_pk_fma_f32 v[40:41], v[64:65], v[22:23], v[40:41] op_sel:[0,1,0] op_sel_hi:[1,1,1] neg_lo:[1,0,0] neg_hi:[1,0,0]
	v_pk_fma_f32 v[42:43], v[66:67], v[22:23], v[42:43] op_sel:[0,1,0] op_sel_hi:[1,1,1] neg_lo:[1,0,0] neg_hi:[1,0,0]
	ds_read_b128 v[64:67], v251 offset:7376
	s_waitcnt lgkmcnt(14)
	v_pk_fma_f32 v[44:45], v[68:69], v[22:23], v[44:45] op_sel:[0,1,0] op_sel_hi:[1,1,1] neg_lo:[1,0,0] neg_hi:[1,0,0]
	v_pk_fma_f32 v[46:47], v[70:71], v[22:23], v[46:47] op_sel:[0,1,0] op_sel_hi:[1,1,1] neg_lo:[1,0,0] neg_hi:[1,0,0]
	ds_read_b128 v[68:71], v251 offset:7392
	s_waitcnt lgkmcnt(14)
	v_pk_fma_f32 v[48:49], v[72:73], v[22:23], v[48:49] op_sel:[0,1,0] op_sel_hi:[1,1,1] neg_lo:[1,0,0] neg_hi:[1,0,0]
	v_pk_fma_f32 v[50:51], v[74:75], v[22:23], v[50:51] op_sel:[0,1,0] op_sel_hi:[1,1,1] neg_lo:[1,0,0] neg_hi:[1,0,0]
	ds_read_b128 v[72:75], v251 offset:7408
	s_waitcnt lgkmcnt(14)
	v_pk_fma_f32 v[52:53], v[76:77], v[22:23], v[52:53] op_sel:[0,1,0] op_sel_hi:[1,1,1] neg_lo:[1,0,0] neg_hi:[1,0,0]
	v_pk_fma_f32 v[54:55], v[78:79], v[22:23], v[54:55] op_sel:[0,1,0] op_sel_hi:[1,1,1] neg_lo:[1,0,0] neg_hi:[1,0,0]
	ds_read_b128 v[76:79], v251 offset:7520
	s_waitcnt lgkmcnt(14)
	v_pk_fma_f32 v[56:57], v[80:81], v[22:23], v[56:57] op_sel:[0,1,0] op_sel_hi:[1,1,1] neg_lo:[1,0,0] neg_hi:[1,0,0]
	v_pk_fma_f32 v[58:59], v[82:83], v[22:23], v[58:59] op_sel:[0,1,0] op_sel_hi:[1,1,1] neg_lo:[1,0,0] neg_hi:[1,0,0]
	ds_read_b128 v[80:83], v251 offset:7536
	s_waitcnt lgkmcnt(14)
; #define PG8_LAS __attribute__((address_space(3)))
; __device__ __forceinline__ bf16_t f2bf(float x) { return (bf16_t)(pk2(x, x) & 0xffffu); }
; __device__ __forceinline__ void solve64(float (&x)[64], const PG8_LAS float* sLt) {
;     f32x4 cur[16];
; #pragma unroll
;     for (int i4 = 0; i4 < 16; ++i4) cur[i4] = *(const PG8_LAS f32x4*)(sLt + 4 * i4);
;     asm volatile("" ::: "memory");
; #pragma unroll
;     for (int j = 0; j < 63; ++j) {
;         const float xj = x[j];
; #pragma unroll
;         for (int i4 = (j + 1) / 4; i4 < 16; ++i4) {
;             if (4 * i4 + 0 > j) x[4 * i4 + 0] -= cur[i4][0] * xj;
;             if (4 * i4 + 1 > j) x[4 * i4 + 1] -= cur[i4][1] * xj;
;             if (4 * i4 + 2 > j) x[4 * i4 + 2] -= cur[i4][2] * xj;
;             if (4 * i4 + 3 > j) x[4 * i4 + 3] -= cur[i4][3] * xj;
;             if (j + 1 < 63 && i4 >= (j + 2) / 4) cur[i4] = *(const PG8_LAS f32x4*)(sLt + (j + 1) * 64 + 4 * i4); }
;         asm volatile("" ::: "memory");
;     }
; }
; __device__ __forceinline__ void phase_prep(const Args& a, PG8_LAS unsigned char* lds) {
;     ...
;             const float bj = sB[lane], bej = bj * sE[lane];
; #pragma unroll
;             for (int i = 0; i < 64; ++i) { *(PG8_LAS bf16_t*)(Tu + (i * 72 + lane) * 2) = f2bf(x[i] * bj); *(PG8_LAS bf16_t*)(Tw + (i * 72 + lane) * 2) = f2bf(x[i] * bej); }
	v_pk_fma_f32 v[60:61], v[84:85], v[22:23], v[60:61] op_sel:[0,1,0] op_sel_hi:[1,1,1] neg_lo:[1,0,0] neg_hi:[1,0,0]
	v_pk_fma_f32 v[62:63], v[86:87], v[22:23], v[62:63] op_sel:[0,1,0] op_sel_hi:[1,1,1] neg_lo:[1,0,0] neg_hi:[1,0,0]
	ds_read_b128 v[84:87], v251 offset:7552
	v_pk_mul_f32 v[126:127], v[24:25], v[128:129] op_sel:[0,0] op_sel_hi:[0,1]
	s_nop 0
	v_cvt_pk_bf16_f32 v126, v126, v127
	s_nop 0
	ds_write_b16 v205, v126 offset:20864
	ds_write_b16_d16_hi v205, v126 offset:30080
	s_waitcnt lgkmcnt(15)
	v_fma_f32 v25, -v89, v24, v25
	v_pk_fma_f32 v[26:27], v[90:91], v[24:25], v[26:27] op_sel:[0,0,0] op_sel_hi:[1,0,1] neg_lo:[1,0,0] neg_hi:[1,0,0]
	ds_read_b128 v[88:91], v251 offset:7568
	s_waitcnt lgkmcnt(15)
	v_pk_fma_f32 v[28:29], v[92:93], v[24:25], v[28:29] op_sel:[0,0,0] op_sel_hi:[1,0,1] neg_lo:[1,0,0] neg_hi:[1,0,0]
	v_pk_fma_f32 v[30:31], v[94:95], v[24:25], v[30:31] op_sel:[0,0,0] op_sel_hi:[1,0,1] neg_lo:[1,0,0] neg_hi:[1,0,0]
	ds_read_b128 v[92:95], v251 offset:7584
	s_waitcnt lgkmcnt(15)
	v_pk_fma_f32 v[32:33], v[230:231], v[24:25], v[32:33] op_sel:[0,0,0] op_sel_hi:[1,0,1] neg_lo:[1,0,0] neg_hi:[1,0,0]
	v_pk_fma_f32 v[34:35], v[232:233], v[24:25], v[34:35] op_sel:[0,0,0] op_sel_hi:[1,0,1] neg_lo:[1,0,0] neg_hi:[1,0,0]
	ds_read_b128 v[230:233], v251 offset:7600
	s_waitcnt lgkmcnt(14)
	v_pk_fma_f32 v[36:37], v[234:235], v[24:25], v[36:37] op_sel:[0,0,0] op_sel_hi:[1,0,1] neg_lo:[1,0,0] neg_hi:[1,0,0]
	v_pk_fma_f32 v[38:39], v[236:237], v[24:25], v[38:39] op_sel:[0,0,0] op_sel_hi:[1,0,1] neg_lo:[1,0,0] neg_hi:[1,0,0]
	ds_read_b128 v[234:237], v251 offset:7616
	s_waitcnt lgkmcnt(14)
	v_pk_fma_f32 v[40:41], v[238:239], v[24:25], v[40:41] op_sel:[0,0,0] op_sel_hi:[1,0,1] neg_lo:[1,0,0] neg_hi:[1,0,0]
	v_pk_fma_f32 v[42:43], v[240:241], v[24:25], v[42:43] op_sel:[0,0,0] op_sel_hi:[1,0,1] neg_lo:[1,0,0] neg_hi:[1,0,0]
	ds_read_b128 v[238:241], v251 offset:7632
	s_waitcnt lgkmcnt(14)
	v_pk_fma_f32 v[44:45], v[242:243], v[24:25], v[44:45] op_sel:[0,0,0] op_sel_hi:[1,0,1] neg_lo:[1,0,0] neg_hi:[1,0,0]
	v_pk_fma_f32 v[46:47], v[244:245], v[24:25], v[46:47] op_sel:[0,0,0] op_sel_hi:[1,0,1] neg_lo:[1,0,0] neg_hi:[1,0,0]
	ds_read_b128 v[242:245], v251 offset:7648
	s_waitcnt lgkmcnt(14)
	v_pk_fma_f32 v[48:49], v[246:247], v[24:25], v[48:49] op_sel:[0,0,0] op_sel_hi:[1,0,1] neg_lo:[1,0,0] neg_hi:[1,0,0]
	v_pk_fma_f32 v[50:51], v[248:249], v[24:25], v[50:51] op_sel:[0,0,0] op_sel_hi:[1,0,1] neg_lo:[1,0,0] neg_hi:[1,0,0]
	ds_read_b128 v[246:249], v251 offset:7664
	s_waitcnt lgkmcnt(14)
	v_pk_fma_f32 v[52:53], v[64:65], v[24:25], v[52:53] op_sel:[0,0,0] op_sel_hi:[1,0,1] neg_lo:[1,0,0] neg_hi:[1,0,0]
	v_pk_fma_f32 v[54:55], v[66:67], v[24:25], v[54:55] op_sel:[0,0,0] op_sel_hi:[1,0,1] neg_lo:[1,0,0] neg_hi:[1,0,0]
	ds_read_b128 v[64:67], v251 offset:7776
	s_waitcnt lgkmcnt(14)
	v_pk_fma_f32 v[56:57], v[68:69], v[24:25], v[56:57] op_sel:[0,0,0] op_sel_hi:[1,0,1] neg_lo:[1,0,0] neg_hi:[1,0,0]
	v_pk_fma_f32 v[58:59], v[70:71], v[24:25], v[58:59] op_sel:[0,0,0] op_sel_hi:[1,0,1] neg_lo:[1,0,0] neg_hi:[1,0,0]
	ds_read_b128 v[68:71], v251 offset:7792
	s_waitcnt lgkmcnt(14)
	v_pk_fma_f32 v[60:61], v[72:73], v[24:25], v[60:61] op_sel:[0,0,0] op_sel_hi:[1,0,1] neg_lo:[1,0,0] neg_hi:[1,0,0]
	v_pk_fma_f32 v[62:63], v[74:75], v[24:25], v[62:63] op_sel:[0,0,0] op_sel_hi:[1,0,1] neg_lo:[1,0,0] neg_hi:[1,0,0]
	ds_read_b128 v[72:75], v251 offset:7808
	v_pk_mul_f32 v[126:127], v[24:25], v[128:129] op_sel:[1,0] op_sel_hi:[1,1]
	s_nop 0
	v_cvt_pk_bf16_f32 v126, v126, v127
	s_nop 0
	ds_write_b16 v205, v126 offset:21008
	ds_write_b16_d16_hi v205, v126 offset:30224
	s_waitcnt lgkmcnt(15)
	v_pk_fma_f32 v[26:27], v[78:79], v[24:25], v[26:27] op_sel:[0,1,0] op_sel_hi:[1,1,1] neg_lo:[1,0,0] neg_hi:[1,0,0]
	ds_read_b128 v[76:79], v251 offset:7824
	s_waitcnt lgkmcnt(15)
	v_pk_fma_f32 v[28:29], v[80:81], v[24:25], v[28:29] op_sel:[0,1,0] op_sel_hi:[1,1,1] neg_lo:[1,0,0] neg_hi:[1,0,0]
	v_pk_fma_f32 v[30:31], v[82:83], v[24:25], v[30:31] op_sel:[0,1,0] op_sel_hi:[1,1,1] neg_lo:[1,0,0] neg_hi:[1,0,0]
	ds_read_b128 v[80:83], v251 offset:7840
	s_waitcnt lgkmcnt(15)
	v_pk_fma_f32 v[32:33], v[84:85], v[24:25], v[32:33] op_sel:[0,1,0] op_sel_hi:[1,1,1] neg_lo:[1,0,0] neg_hi:[1,0,0]
	v_pk_fma_f32 v[34:35], v[86:87], v[24:25], v[34:35] op_sel:[0,1,0] op_sel_hi:[1,1,1] neg_lo:[1,0,0] neg_hi:[1,0,0]
	ds_read_b128 v[84:87], v251 offset:7856
	s_waitcnt lgkmcnt(14)
	v_pk_fma_f32 v[36:37], v[88:89], v[24:25], v[36:37] op_sel:[0,1,0] op_sel_hi:[1,1,1] neg_lo:[1,0,0] neg_hi:[1,0,0]
	v_pk_fma_f32 v[38:39], v[90:91], v[24:25], v[38:39] op_sel:[0,1,0] op_sel_hi:[1,1,1] neg_lo:[1,0,0] neg_hi:[1,0,0]
	ds_read_b128 v[88:91], v251 offset:7872
	s_waitcnt lgkmcnt(14)
	v_pk_fma_f32 v[40:41], v[92:93], v[24:25], v[40:41] op_sel:[0,1,0] op_sel_hi:[1,1,1] neg_lo:[1,0,0] neg_hi:[1,0,0]
	v_pk_fma_f32 v[42:43], v[94:95], v[24:25], v[42:43] op_sel:[0,1,0] op_sel_hi:[1,1,1] neg_lo:[1,0,0] neg_hi:[1,0,0]
	ds_read_b128 v[92:95], v251 offset:7888
	s_waitcnt lgkmcnt(14)
	v_pk_fma_f32 v[44:45], v[230:231], v[24:25], v[44:45] op_sel:[0,1,0] op_sel_hi:[1,1,1] neg_lo:[1,0,0] neg_hi:[1,0,0]
	v_pk_fma_f32 v[46:47], v[232:233], v[24:25], v[46:47] op_sel:[0,1,0] op_sel_hi:[1,1,1] neg_lo:[1,0,0] neg_hi:[1,0,0]
	ds_read_b128 v[230:233], v251 offset:7904
	s_waitcnt lgkmcnt(14)
	v_pk_fma_f32 v[48:49], v[234:235], v[24:25], v[48:49] op_sel:[0,1,0] op_sel_hi:[1,1,1] neg_lo:[1,0,0] neg_hi:[1,0,0]
	v_pk_fma_f32 v[50:51], v[236:237], v[24:25], v[50:51] op_sel:[0,1,0] op_sel_hi:[1,1,1] neg_lo:[1,0,0] neg_hi:[1,0,0]
	ds_read_b128 v[234:237], v251 offset:7920
	s_waitcnt lgkmcnt(14)
; #define PG8_LAS __attribute__((address_space(3)))
; __device__ __forceinline__ bf16_t f2bf(float x) { return (bf16_t)(pk2(x, x) & 0xffffu); }
; __device__ __forceinline__ void solve64(float (&x)[64], const PG8_LAS float* sLt) {
;     f32x4 cur[16];
; #pragma unroll
;     for (int i4 = 0; i4 < 16; ++i4) cur[i4] = *(const PG8_LAS f32x4*)(sLt + 4 * i4);
;     asm volatile("" ::: "memory");
; #pragma unroll
;     for (int j = 0; j < 63; ++j) {
;         const float xj = x[j];
; #pragma unroll
;         for (int i4 = (j + 1) / 4; i4 < 16; ++i4) {
;             if (4 * i4 + 0 > j) x[4 * i4 + 0] -= cur[i4][0] * xj;
;             if (4 * i4 + 1 > j) x[4 * i4 + 1] -= cur[i4][1] * xj;
;             if (4 * i4 + 2 > j) x[4 * i4 + 2] -= cur[i4][2] * xj;
;             if (4 * i4 + 3 > j) x[4 * i4 + 3] -= cur[i4][3] * xj;
;             if (j + 1 < 63 && i4 >= (j + 2) / 4) cur[i4] = *(const PG8_LAS f32x4*)(sLt + (j + 1) * 64 + 4 * i4); }
;         asm volatile("" ::: "memory");
;     }
; }
; __device__ __forceinline__ void phase_prep(const Args& a, PG8_LAS unsigned char* lds) {
;     ...
;             const float bj = sB[lane], bej = bj * sE[lane];
; #pragma unroll
;             for (int i = 0; i < 64; ++i) { *(PG8_LAS bf16_t*)(Tu + (i * 72 + lane) * 2) = f2bf(x[i] * bj); *(PG8_LAS bf16_t*)(Tw + (i * 72 + lane) * 2) = f2bf(x[i] * bej); }
	v_pk_fma_f32 v[52:53], v[238:239], v[24:25], v[52:53] op_sel:[0,1,0] op_sel_hi:[1,1,1] neg_lo:[1,0,0] neg_hi:[1,0,0]
	v_pk_fma_f32 v[54:55], v[240:241], v[24:25], v[54:55] op_sel:[0,1,0] op_sel_hi:[1,1,1] neg_lo:[1,0,0] neg_hi:[1,0,0]
	ds_read_b128 v[238:241], v251 offset:8048
	s_waitcnt lgkmcnt(14)
	v_pk_fma_f32 v[56:57], v[242:243], v[24:25], v[56:57] op_sel:[0,1,0] op_sel_hi:[1,1,1] neg_lo:[1,0,0] neg_hi:[1,0,0]
	v_pk_fma_f32 v[58:59], v[244:245], v[24:25], v[58:59] op_sel:[0,1,0] op_sel_hi:[1,1,1] neg_lo:[1,0,0] neg_hi:[1,0,0]
	ds_read_b128 v[242:245], v251 offset:8064
	s_waitcnt lgkmcnt(14)
	v_pk_fma_f32 v[60:61], v[246:247], v[24:25], v[60:61] op_sel:[0,1,0] op_sel_hi:[1,1,1] neg_lo:[1,0,0] neg_hi:[1,0,0]
	v_pk_fma_f32 v[62:63], v[248:249], v[24:25], v[62:63] op_sel:[0,1,0] op_sel_hi:[1,1,1] neg_lo:[1,0,0] neg_hi:[1,0,0]
	ds_read_b128 v[246:249], v251 offset:8080
	v_pk_mul_f32 v[126:127], v[26:27], v[128:129] op_sel:[0,0] op_sel_hi:[0,1]
	s_nop 0
	v_cvt_pk_bf16_f32 v126, v126, v127
	s_nop 0
	ds_write_b16 v205, v126 offset:21152
	ds_write_b16_d16_hi v205, v126 offset:30368
	s_waitcnt lgkmcnt(15)
	v_fma_f32 v27, -v67, v26, v27
	ds_read_b128 v[64:67], v251 offset:8096
	s_waitcnt lgkmcnt(15)
	v_pk_fma_f32 v[28:29], v[68:69], v[26:27], v[28:29] op_sel:[0,0,0] op_sel_hi:[1,0,1] neg_lo:[1,0,0] neg_hi:[1,0,0]
	v_pk_fma_f32 v[30:31], v[70:71], v[26:27], v[30:31] op_sel:[0,0,0] op_sel_hi:[1,0,1] neg_lo:[1,0,0] neg_hi:[1,0,0]
	ds_read_b128 v[68:71], v251 offset:8112
	s_waitcnt lgkmcnt(15)
	v_pk_fma_f32 v[32:33], v[72:73], v[26:27], v[32:33] op_sel:[0,0,0] op_sel_hi:[1,0,1] neg_lo:[1,0,0] neg_hi:[1,0,0]
	v_pk_fma_f32 v[34:35], v[74:75], v[26:27], v[34:35] op_sel:[0,0,0] op_sel_hi:[1,0,1] neg_lo:[1,0,0] neg_hi:[1,0,0]
	ds_read_b128 v[72:75], v251 offset:8128
	s_waitcnt lgkmcnt(14)
	v_pk_fma_f32 v[36:37], v[76:77], v[26:27], v[36:37] op_sel:[0,0,0] op_sel_hi:[1,0,1] neg_lo:[1,0,0] neg_hi:[1,0,0]
	v_pk_fma_f32 v[38:39], v[78:79], v[26:27], v[38:39] op_sel:[0,0,0] op_sel_hi:[1,0,1] neg_lo:[1,0,0] neg_hi:[1,0,0]
	ds_read_b128 v[76:79], v251 offset:8144
	s_waitcnt lgkmcnt(14)
	v_pk_fma_f32 v[40:41], v[80:81], v[26:27], v[40:41] op_sel:[0,0,0] op_sel_hi:[1,0,1] neg_lo:[1,0,0] neg_hi:[1,0,0]
	v_pk_fma_f32 v[42:43], v[82:83], v[26:27], v[42:43] op_sel:[0,0,0] op_sel_hi:[1,0,1] neg_lo:[1,0,0] neg_hi:[1,0,0]
	ds_read_b128 v[80:83], v251 offset:8160
	s_waitcnt lgkmcnt(14)
	v_pk_fma_f32 v[44:45], v[84:85], v[26:27], v[44:45] op_sel:[0,0,0] op_sel_hi:[1,0,1] neg_lo:[1,0,0] neg_hi:[1,0,0]
	v_pk_fma_f32 v[46:47], v[86:87], v[26:27], v[46:47] op_sel:[0,0,0] op_sel_hi:[1,0,1] neg_lo:[1,0,0] neg_hi:[1,0,0]
	ds_read_b128 v[84:87], v251 offset:8176
	s_waitcnt lgkmcnt(14)
	v_pk_fma_f32 v[48:49], v[88:89], v[26:27], v[48:49] op_sel:[0,0,0] op_sel_hi:[1,0,1] neg_lo:[1,0,0] neg_hi:[1,0,0]
	v_pk_fma_f32 v[50:51], v[90:91], v[26:27], v[50:51] op_sel:[0,0,0] op_sel_hi:[1,0,1] neg_lo:[1,0,0] neg_hi:[1,0,0]
	ds_read_b128 v[88:91], v251 offset:8304
	s_waitcnt lgkmcnt(14)
	v_pk_fma_f32 v[52:53], v[92:93], v[26:27], v[52:53] op_sel:[0,0,0] op_sel_hi:[1,0,1] neg_lo:[1,0,0] neg_hi:[1,0,0]
	v_pk_fma_f32 v[54:55], v[94:95], v[26:27], v[54:55] op_sel:[0,0,0] op_sel_hi:[1,0,1] neg_lo:[1,0,0] neg_hi:[1,0,0]
	ds_read_b128 v[92:95], v251 offset:8320
	s_waitcnt lgkmcnt(14)
	v_pk_fma_f32 v[56:57], v[230:231], v[26:27], v[56:57] op_sel:[0,0,0] op_sel_hi:[1,0,1] neg_lo:[1,0,0] neg_hi:[1,0,0]
	v_pk_fma_f32 v[58:59], v[232:233], v[26:27], v[58:59] op_sel:[0,0,0] op_sel_hi:[1,0,1] neg_lo:[1,0,0] neg_hi:[1,0,0]
	ds_read_b128 v[230:233], v251 offset:8336
	s_waitcnt lgkmcnt(14)
	v_pk_fma_f32 v[60:61], v[234:235], v[26:27], v[60:61] op_sel:[0,0,0] op_sel_hi:[1,0,1] neg_lo:[1,0,0] neg_hi:[1,0,0]
	v_pk_fma_f32 v[62:63], v[236:237], v[26:27], v[62:63] op_sel:[0,0,0] op_sel_hi:[1,0,1] neg_lo:[1,0,0] neg_hi:[1,0,0]
	ds_read_b128 v[234:237], v251 offset:8352
	v_pk_mul_f32 v[126:127], v[26:27], v[128:129] op_sel:[1,0] op_sel_hi:[1,1]
	s_nop 0
	v_cvt_pk_bf16_f32 v126, v126, v127
	s_nop 0
	ds_write_b16 v205, v126 offset:21296
	ds_write_b16_d16_hi v205, v126 offset:30512
	s_waitcnt lgkmcnt(15)
	v_pk_fma_f32 v[28:29], v[238:239], v[26:27], v[28:29] op_sel:[0,1,0] op_sel_hi:[1,1,1] neg_lo:[1,0,0] neg_hi:[1,0,0]
	v_pk_fma_f32 v[30:31], v[240:241], v[26:27], v[30:31] op_sel:[0,1,0] op_sel_hi:[1,1,1] neg_lo:[1,0,0] neg_hi:[1,0,0]
	ds_read_b128 v[238:241], v251 offset:8368
	s_waitcnt lgkmcnt(15)
	v_pk_fma_f32 v[32:33], v[242:243], v[26:27], v[32:33] op_sel:[0,1,0] op_sel_hi:[1,1,1] neg_lo:[1,0,0] neg_hi:[1,0,0]
	v_pk_fma_f32 v[34:35], v[244:245], v[26:27], v[34:35] op_sel:[0,1,0] op_sel_hi:[1,1,1] neg_lo:[1,0,0] neg_hi:[1,0,0]
	ds_read_b128 v[242:245], v251 offset:8384
	s_waitcnt lgkmcnt(15)
	v_pk_fma_f32 v[36:37], v[246:247], v[26:27], v[36:37] op_sel:[0,1,0] op_sel_hi:[1,1,1] neg_lo:[1,0,0] neg_hi:[1,0,0]
	v_pk_fma_f32 v[38:39], v[248:249], v[26:27], v[38:39] op_sel:[0,1,0] op_sel_hi:[1,1,1] neg_lo:[1,0,0] neg_hi:[1,0,0]
	ds_read_b128 v[246:249], v251 offset:8400
	s_waitcnt lgkmcnt(14)
	v_pk_fma_f32 v[40:41], v[64:65], v[26:27], v[40:41] op_sel:[0,1,0] op_sel_hi:[1,1,1] neg_lo:[1,0,0] neg_hi:[1,0,0]
	v_pk_fma_f32 v[42:43], v[66:67], v[26:27], v[42:43] op_sel:[0,1,0] op_sel_hi:[1,1,1] neg_lo:[1,0,0] neg_hi:[1,0,0]
	ds_read_b128 v[64:67], v251 offset:8416
	s_waitcnt lgkmcnt(14)
	v_pk_fma_f32 v[44:45], v[68:69], v[26:27], v[44:45] op_sel:[0,1,0] op_sel_hi:[1,1,1] neg_lo:[1,0,0] neg_hi:[1,0,0]
	v_pk_fma_f32 v[46:47], v[70:71], v[26:27], v[46:47] op_sel:[0,1,0] op_sel_hi:[1,1,1] neg_lo:[1,0,0] neg_hi:[1,0,0]
	ds_read_b128 v[68:71], v251 offset:8432
	s_waitcnt lgkmcnt(14)
; #define PG8_LAS __attribute__((address_space(3)))
; __device__ __forceinline__ bf16_t f2bf(float x) { return (bf16_t)(pk2(x, x) & 0xffffu); }
; __device__ __forceinline__ void solve64(float (&x)[64], const PG8_LAS float* sLt) {
;     f32x4 cur[16];
; #pragma unroll
;     for (int i4 = 0; i4 < 16; ++i4) cur[i4] = *(const PG8_LAS f32x4*)(sLt + 4 * i4);
;     asm volatile("" ::: "memory");
; #pragma unroll
;     for (int j = 0; j < 63; ++j) {
;         const float xj = x[j];
; #pragma unroll
;         for (int i4 = (j + 1) / 4; i4 < 16; ++i4) {
;             if (4 * i4 + 0 > j) x[4 * i4 + 0] -= cur[i4][0] * xj;
;             if (4 * i4 + 1 > j) x[4 * i4 + 1] -= cur[i4][1] * xj;
;             if (4 * i4 + 2 > j) x[4 * i4 + 2] -= cur[i4][2] * xj;
;             if (4 * i4 + 3 > j) x[4 * i4 + 3] -= cur[i4][3] * xj;
;             if (j + 1 < 63 && i4 >= (j + 2) / 4) cur[i4] = *(const PG8_LAS f32x4*)(sLt + (j + 1) * 64 + 4 * i4); }
;         asm volatile("" ::: "memory");
;     }
; }
; __device__ __forceinline__ void phase_prep(const Args& a, PG8_LAS unsigned char* lds) {
;     ...
;             const float bj = sB[lane], bej = bj * sE[lane];
; #pragma unroll
;             for (int i = 0; i < 64; ++i) { *(PG8_LAS bf16_t*)(Tu + (i * 72 + lane) * 2) = f2bf(x[i] * bj); *(PG8_LAS bf16_t*)(Tw + (i * 72 + lane) * 2) = f2bf(x[i] * bej); }
	v_pk_fma_f32 v[48:49], v[72:73], v[26:27], v[48:49] op_sel:[0,1,0] op_sel_hi:[1,1,1] neg_lo:[1,0,0] neg_hi:[1,0,0]
	v_pk_fma_f32 v[50:51], v[74:75], v[26:27], v[50:51] op_sel:[0,1,0] op_sel_hi:[1,1,1] neg_lo:[1,0,0] neg_hi:[1,0,0]
	ds_read_b128 v[72:75], v251 offset:8560
	s_waitcnt lgkmcnt(14)
	v_pk_fma_f32 v[52:53], v[76:77], v[26:27], v[52:53] op_sel:[0,1,0] op_sel_hi:[1,1,1] neg_lo:[1,0,0] neg_hi:[1,0,0]
	v_pk_fma_f32 v[54:55], v[78:79], v[26:27], v[54:55] op_sel:[0,1,0] op_sel_hi:[1,1,1] neg_lo:[1,0,0] neg_hi:[1,0,0]
	ds_read_b128 v[76:79], v251 offset:8576
	s_waitcnt lgkmcnt(14)
	v_pk_fma_f32 v[56:57], v[80:81], v[26:27], v[56:57] op_sel:[0,1,0] op_sel_hi:[1,1,1] neg_lo:[1,0,0] neg_hi:[1,0,0]
	v_pk_fma_f32 v[58:59], v[82:83], v[26:27], v[58:59] op_sel:[0,1,0] op_sel_hi:[1,1,1] neg_lo:[1,0,0] neg_hi:[1,0,0]
	ds_read_b128 v[80:83], v251 offset:8592
	s_waitcnt lgkmcnt(14)
	v_pk_fma_f32 v[60:61], v[84:85], v[26:27], v[60:61] op_sel:[0,1,0] op_sel_hi:[1,1,1] neg_lo:[1,0,0] neg_hi:[1,0,0]
	v_pk_fma_f32 v[62:63], v[86:87], v[26:27], v[62:63] op_sel:[0,1,0] op_sel_hi:[1,1,1] neg_lo:[1,0,0] neg_hi:[1,0,0]
	ds_read_b128 v[84:87], v251 offset:8608
	v_pk_mul_f32 v[126:127], v[28:29], v[128:129] op_sel:[0,0] op_sel_hi:[0,1]
	s_nop 0
	v_cvt_pk_bf16_f32 v126, v126, v127
	s_nop 0
	ds_write_b16 v205, v126 offset:21440
	ds_write_b16_d16_hi v205, v126 offset:30656
	s_waitcnt lgkmcnt(15)
	v_fma_f32 v29, -v89, v28, v29
	v_pk_fma_f32 v[30:31], v[90:91], v[28:29], v[30:31] op_sel:[0,0,0] op_sel_hi:[1,0,1] neg_lo:[1,0,0] neg_hi:[1,0,0]
	ds_read_b128 v[88:91], v251 offset:8624
	s_waitcnt lgkmcnt(15)
	v_pk_fma_f32 v[32:33], v[92:93], v[28:29], v[32:33] op_sel:[0,0,0] op_sel_hi:[1,0,1] neg_lo:[1,0,0] neg_hi:[1,0,0]
	v_pk_fma_f32 v[34:35], v[94:95], v[28:29], v[34:35] op_sel:[0,0,0] op_sel_hi:[1,0,1] neg_lo:[1,0,0] neg_hi:[1,0,0]
	ds_read_b128 v[92:95], v251 offset:8640
	s_waitcnt lgkmcnt(15)
	v_pk_fma_f32 v[36:37], v[230:231], v[28:29], v[36:37] op_sel:[0,0,0] op_sel_hi:[1,0,1] neg_lo:[1,0,0] neg_hi:[1,0,0]
	v_pk_fma_f32 v[38:39], v[232:233], v[28:29], v[38:39] op_sel:[0,0,0] op_sel_hi:[1,0,1] neg_lo:[1,0,0] neg_hi:[1,0,0]
	ds_read_b128 v[230:233], v251 offset:8656
	s_waitcnt lgkmcnt(15)
	v_pk_fma_f32 v[40:41], v[234:235], v[28:29], v[40:41] op_sel:[0,0,0] op_sel_hi:[1,0,1] neg_lo:[1,0,0] neg_hi:[1,0,0]
	v_pk_fma_f32 v[42:43], v[236:237], v[28:29], v[42:43] op_sel:[0,0,0] op_sel_hi:[1,0,1] neg_lo:[1,0,0] neg_hi:[1,0,0]
	ds_read_b128 v[234:237], v251 offset:8672
	s_waitcnt lgkmcnt(14)
	v_pk_fma_f32 v[44:45], v[238:239], v[28:29], v[44:45] op_sel:[0,0,0] op_sel_hi:[1,0,1] neg_lo:[1,0,0] neg_hi:[1,0,0]
	v_pk_fma_f32 v[46:47], v[240:241], v[28:29], v[46:47] op_sel:[0,0,0] op_sel_hi:[1,0,1] neg_lo:[1,0,0] neg_hi:[1,0,0]
	ds_read_b128 v[238:241], v251 offset:8688
	s_waitcnt lgkmcnt(14)
	v_pk_fma_f32 v[48:49], v[242:243], v[28:29], v[48:49] op_sel:[0,0,0] op_sel_hi:[1,0,1] neg_lo:[1,0,0] neg_hi:[1,0,0]
	v_pk_fma_f32 v[50:51], v[244:245], v[28:29], v[50:51] op_sel:[0,0,0] op_sel_hi:[1,0,1] neg_lo:[1,0,0] neg_hi:[1,0,0]
	ds_read_b128 v[242:245], v251 offset:8816
	s_waitcnt lgkmcnt(14)
	v_pk_fma_f32 v[52:53], v[246:247], v[28:29], v[52:53] op_sel:[0,0,0] op_sel_hi:[1,0,1] neg_lo:[1,0,0] neg_hi:[1,0,0]
	v_pk_fma_f32 v[54:55], v[248:249], v[28:29], v[54:55] op_sel:[0,0,0] op_sel_hi:[1,0,1] neg_lo:[1,0,0] neg_hi:[1,0,0]
	ds_read_b128 v[246:249], v251 offset:8832
	s_waitcnt lgkmcnt(14)
	v_pk_fma_f32 v[56:57], v[64:65], v[28:29], v[56:57] op_sel:[0,0,0] op_sel_hi:[1,0,1] neg_lo:[1,0,0] neg_hi:[1,0,0]
	v_pk_fma_f32 v[58:59], v[66:67], v[28:29], v[58:59] op_sel:[0,0,0] op_sel_hi:[1,0,1] neg_lo:[1,0,0] neg_hi:[1,0,0]
	ds_read_b128 v[64:67], v251 offset:8848
	s_waitcnt lgkmcnt(14)
	v_pk_fma_f32 v[60:61], v[68:69], v[28:29], v[60:61] op_sel:[0,0,0] op_sel_hi:[1,0,1] neg_lo:[1,0,0] neg_hi:[1,0,0]
	v_pk_fma_f32 v[62:63], v[70:71], v[28:29], v[62:63] op_sel:[0,0,0] op_sel_hi:[1,0,1] neg_lo:[1,0,0] neg_hi:[1,0,0]
	ds_read_b128 v[68:71], v251 offset:8864
	v_pk_mul_f32 v[126:127], v[28:29], v[128:129] op_sel:[1,0] op_sel_hi:[1,1]
	s_nop 0
	v_cvt_pk_bf16_f32 v126, v126, v127
	s_nop 0
	ds_write_b16 v205, v126 offset:21584
	ds_write_b16_d16_hi v205, v126 offset:30800
	s_waitcnt lgkmcnt(15)
	v_pk_fma_f32 v[30:31], v[74:75], v[28:29], v[30:31] op_sel:[0,1,0] op_sel_hi:[1,1,1] neg_lo:[1,0,0] neg_hi:[1,0,0]
	ds_read_b128 v[72:75], v251 offset:8880
	s_waitcnt lgkmcnt(15)
	v_pk_fma_f32 v[32:33], v[76:77], v[28:29], v[32:33] op_sel:[0,1,0] op_sel_hi:[1,1,1] neg_lo:[1,0,0] neg_hi:[1,0,0]
	v_pk_fma_f32 v[34:35], v[78:79], v[28:29], v[34:35] op_sel:[0,1,0] op_sel_hi:[1,1,1] neg_lo:[1,0,0] neg_hi:[1,0,0]
	ds_read_b128 v[76:79], v251 offset:8896
	s_waitcnt lgkmcnt(15)
	v_pk_fma_f32 v[36:37], v[80:81], v[28:29], v[36:37] op_sel:[0,1,0] op_sel_hi:[1,1,1] neg_lo:[1,0,0] neg_hi:[1,0,0]
	v_pk_fma_f32 v[38:39], v[82:83], v[28:29], v[38:39] op_sel:[0,1,0] op_sel_hi:[1,1,1] neg_lo:[1,0,0] neg_hi:[1,0,0]
	ds_read_b128 v[80:83], v251 offset:8912
	s_waitcnt lgkmcnt(15)
	v_pk_fma_f32 v[40:41], v[84:85], v[28:29], v[40:41] op_sel:[0,1,0] op_sel_hi:[1,1,1] neg_lo:[1,0,0] neg_hi:[1,0,0]
	v_pk_fma_f32 v[42:43], v[86:87], v[28:29], v[42:43] op_sel:[0,1,0] op_sel_hi:[1,1,1] neg_lo:[1,0,0] neg_hi:[1,0,0]
	ds_read_b128 v[84:87], v251 offset:8928
	s_waitcnt lgkmcnt(14)
	v_pk_fma_f32 v[44:45], v[88:89], v[28:29], v[44:45] op_sel:[0,1,0] op_sel_hi:[1,1,1] neg_lo:[1,0,0] neg_hi:[1,0,0]
	v_pk_fma_f32 v[46:47], v[90:91], v[28:29], v[46:47] op_sel:[0,1,0] op_sel_hi:[1,1,1] neg_lo:[1,0,0] neg_hi:[1,0,0]
	ds_read_b128 v[88:91], v251 offset:8944
	s_waitcnt lgkmcnt(14)
; #define PG8_LAS __attribute__((address_space(3)))
; __device__ __forceinline__ bf16_t f2bf(float x) { return (bf16_t)(pk2(x, x) & 0xffffu); }
; __device__ __forceinline__ void solve64(float (&x)[64], const PG8_LAS float* sLt) {
;     f32x4 cur[16];
; #pragma unroll
;     for (int i4 = 0; i4 < 16; ++i4) cur[i4] = *(const PG8_LAS f32x4*)(sLt + 4 * i4);
;     asm volatile("" ::: "memory");
; #pragma unroll
;     for (int j = 0; j < 63; ++j) {
;         const float xj = x[j];
; #pragma unroll
;         for (int i4 = (j + 1) / 4; i4 < 16; ++i4) {
;             if (4 * i4 + 0 > j) x[4 * i4 + 0] -= cur[i4][0] * xj;
;             if (4 * i4 + 1 > j) x[4 * i4 + 1] -= cur[i4][1] * xj;
;             if (4 * i4 + 2 > j) x[4 * i4 + 2] -= cur[i4][2] * xj;
;             if (4 * i4 + 3 > j) x[4 * i4 + 3] -= cur[i4][3] * xj;
;             if (j + 1 < 63 && i4 >= (j + 2) / 4) cur[i4] = *(const PG8_LAS f32x4*)(sLt + (j + 1) * 64 + 4 * i4); }
;         asm volatile("" ::: "memory");
;     }
; }
; __device__ __forceinline__ void phase_prep(const Args& a, PG8_LAS unsigned char* lds) {
;     ...
;             const float bj = sB[lane], bej = bj * sE[lane];
; #pragma unroll
;             for (int i = 0; i < 64; ++i) { *(PG8_LAS bf16_t*)(Tu + (i * 72 + lane) * 2) = f2bf(x[i] * bj); *(PG8_LAS bf16_t*)(Tw + (i * 72 + lane) * 2) = f2bf(x[i] * bej); }
	v_pk_fma_f32 v[48:49], v[92:93], v[28:29], v[48:49] op_sel:[0,1,0] op_sel_hi:[1,1,1] neg_lo:[1,0,0] neg_hi:[1,0,0]
	v_pk_fma_f32 v[50:51], v[94:95], v[28:29], v[50:51] op_sel:[0,1,0] op_sel_hi:[1,1,1] neg_lo:[1,0,0] neg_hi:[1,0,0]
	ds_read_b128 v[92:95], v251 offset:9088
	s_waitcnt lgkmcnt(14)
	v_pk_fma_f32 v[52:53], v[230:231], v[28:29], v[52:53] op_sel:[0,1,0] op_sel_hi:[1,1,1] neg_lo:[1,0,0] neg_hi:[1,0,0]
	v_pk_fma_f32 v[54:55], v[232:233], v[28:29], v[54:55] op_sel:[0,1,0] op_sel_hi:[1,1,1] neg_lo:[1,0,0] neg_hi:[1,0,0]
	ds_read_b128 v[230:233], v251 offset:9104
	s_waitcnt lgkmcnt(14)
	v_pk_fma_f32 v[56:57], v[234:235], v[28:29], v[56:57] op_sel:[0,1,0] op_sel_hi:[1,1,1] neg_lo:[1,0,0] neg_hi:[1,0,0]
	v_pk_fma_f32 v[58:59], v[236:237], v[28:29], v[58:59] op_sel:[0,1,0] op_sel_hi:[1,1,1] neg_lo:[1,0,0] neg_hi:[1,0,0]
	ds_read_b128 v[234:237], v251 offset:9120
	s_waitcnt lgkmcnt(14)
	v_pk_fma_f32 v[60:61], v[238:239], v[28:29], v[60:61] op_sel:[0,1,0] op_sel_hi:[1,1,1] neg_lo:[1,0,0] neg_hi:[1,0,0]
	v_pk_fma_f32 v[62:63], v[240:241], v[28:29], v[62:63] op_sel:[0,1,0] op_sel_hi:[1,1,1] neg_lo:[1,0,0] neg_hi:[1,0,0]
	ds_read_b128 v[238:241], v251 offset:9136
	v_pk_mul_f32 v[126:127], v[30:31], v[128:129] op_sel:[0,0] op_sel_hi:[0,1]
	s_nop 0
	v_cvt_pk_bf16_f32 v126, v126, v127
	s_nop 0
	ds_write_b16 v205, v126 offset:21728
	ds_write_b16_d16_hi v205, v126 offset:30944
	s_waitcnt lgkmcnt(15)
	v_fma_f32 v31, -v245, v30, v31
	ds_read_b128 v[242:245], v251 offset:9152
	s_waitcnt lgkmcnt(15)
	v_pk_fma_f32 v[32:33], v[246:247], v[30:31], v[32:33] op_sel:[0,0,0] op_sel_hi:[1,0,1] neg_lo:[1,0,0] neg_hi:[1,0,0]
	v_pk_fma_f32 v[34:35], v[248:249], v[30:31], v[34:35] op_sel:[0,0,0] op_sel_hi:[1,0,1] neg_lo:[1,0,0] neg_hi:[1,0,0]
	ds_read_b128 v[246:249], v251 offset:9168
	s_waitcnt lgkmcnt(15)
	v_pk_fma_f32 v[36:37], v[64:65], v[30:31], v[36:37] op_sel:[0,0,0] op_sel_hi:[1,0,1] neg_lo:[1,0,0] neg_hi:[1,0,0]
	v_pk_fma_f32 v[38:39], v[66:67], v[30:31], v[38:39] op_sel:[0,0,0] op_sel_hi:[1,0,1] neg_lo:[1,0,0] neg_hi:[1,0,0]
	ds_read_b128 v[64:67], v251 offset:9184
	s_waitcnt lgkmcnt(15)
	v_pk_fma_f32 v[40:41], v[68:69], v[30:31], v[40:41] op_sel:[0,0,0] op_sel_hi:[1,0,1] neg_lo:[1,0,0] neg_hi:[1,0,0]
	v_pk_fma_f32 v[42:43], v[70:71], v[30:31], v[42:43] op_sel:[0,0,0] op_sel_hi:[1,0,1] neg_lo:[1,0,0] neg_hi:[1,0,0]
	ds_read_b128 v[68:71], v251 offset:9200
	s_waitcnt lgkmcnt(14)
	v_pk_fma_f32 v[44:45], v[72:73], v[30:31], v[44:45] op_sel:[0,0,0] op_sel_hi:[1,0,1] neg_lo:[1,0,0] neg_hi:[1,0,0]
	v_pk_fma_f32 v[46:47], v[74:75], v[30:31], v[46:47] op_sel:[0,0,0] op_sel_hi:[1,0,1] neg_lo:[1,0,0] neg_hi:[1,0,0]
	ds_read_b128 v[72:75], v251 offset:9344
	s_waitcnt lgkmcnt(14)
	v_pk_fma_f32 v[48:49], v[76:77], v[30:31], v[48:49] op_sel:[0,0,0] op_sel_hi:[1,0,1] neg_lo:[1,0,0] neg_hi:[1,0,0]
	v_pk_fma_f32 v[50:51], v[78:79], v[30:31], v[50:51] op_sel:[0,0,0] op_sel_hi:[1,0,1] neg_lo:[1,0,0] neg_hi:[1,0,0]
	ds_read_b128 v[76:79], v251 offset:9360
	s_waitcnt lgkmcnt(14)
	v_pk_fma_f32 v[52:53], v[80:81], v[30:31], v[52:53] op_sel:[0,0,0] op_sel_hi:[1,0,1] neg_lo:[1,0,0] neg_hi:[1,0,0]
	v_pk_fma_f32 v[54:55], v[82:83], v[30:31], v[54:55] op_sel:[0,0,0] op_sel_hi:[1,0,1] neg_lo:[1,0,0] neg_hi:[1,0,0]
	ds_read_b128 v[80:83], v251 offset:9376
	s_waitcnt lgkmcnt(14)
	v_pk_fma_f32 v[56:57], v[84:85], v[30:31], v[56:57] op_sel:[0,0,0] op_sel_hi:[1,0,1] neg_lo:[1,0,0] neg_hi:[1,0,0]
	v_pk_fma_f32 v[58:59], v[86:87], v[30:31], v[58:59] op_sel:[0,0,0] op_sel_hi:[1,0,1] neg_lo:[1,0,0] neg_hi:[1,0,0]
	ds_read_b128 v[84:87], v251 offset:9392
	s_waitcnt lgkmcnt(14)
	v_pk_fma_f32 v[60:61], v[88:89], v[30:31], v[60:61] op_sel:[0,0,0] op_sel_hi:[1,0,1] neg_lo:[1,0,0] neg_hi:[1,0,0]
	v_pk_fma_f32 v[62:63], v[90:91], v[30:31], v[62:63] op_sel:[0,0,0] op_sel_hi:[1,0,1] neg_lo:[1,0,0] neg_hi:[1,0,0]
	ds_read_b128 v[88:91], v251 offset:9408
	v_pk_mul_f32 v[126:127], v[30:31], v[128:129] op_sel:[1,0] op_sel_hi:[1,1]
	s_nop 0
	v_cvt_pk_bf16_f32 v126, v126, v127
	s_nop 0
	ds_write_b16 v205, v126 offset:21872
	ds_write_b16_d16_hi v205, v126 offset:31088
	s_waitcnt lgkmcnt(15)
	v_pk_fma_f32 v[32:33], v[92:93], v[30:31], v[32:33] op_sel:[0,1,0] op_sel_hi:[1,1,1] neg_lo:[1,0,0] neg_hi:[1,0,0]
	v_pk_fma_f32 v[34:35], v[94:95], v[30:31], v[34:35] op_sel:[0,1,0] op_sel_hi:[1,1,1] neg_lo:[1,0,0] neg_hi:[1,0,0]
	ds_read_b128 v[92:95], v251 offset:9424
	s_waitcnt lgkmcnt(15)
	v_pk_fma_f32 v[36:37], v[230:231], v[30:31], v[36:37] op_sel:[0,1,0] op_sel_hi:[1,1,1] neg_lo:[1,0,0] neg_hi:[1,0,0]
	v_pk_fma_f32 v[38:39], v[232:233], v[30:31], v[38:39] op_sel:[0,1,0] op_sel_hi:[1,1,1] neg_lo:[1,0,0] neg_hi:[1,0,0]
	ds_read_b128 v[230:233], v251 offset:9440
	s_waitcnt lgkmcnt(15)
	v_pk_fma_f32 v[40:41], v[234:235], v[30:31], v[40:41] op_sel:[0,1,0] op_sel_hi:[1,1,1] neg_lo:[1,0,0] neg_hi:[1,0,0]
	v_pk_fma_f32 v[42:43], v[236:237], v[30:31], v[42:43] op_sel:[0,1,0] op_sel_hi:[1,1,1] neg_lo:[1,0,0] neg_hi:[1,0,0]
	ds_read_b128 v[234:237], v251 offset:9456
	s_waitcnt lgkmcnt(15)
	v_pk_fma_f32 v[44:45], v[238:239], v[30:31], v[44:45] op_sel:[0,1,0] op_sel_hi:[1,1,1] neg_lo:[1,0,0] neg_hi:[1,0,0]
	v_pk_fma_f32 v[46:47], v[240:241], v[30:31], v[46:47] op_sel:[0,1,0] op_sel_hi:[1,1,1] neg_lo:[1,0,0] neg_hi:[1,0,0]
	ds_read_b128 v[238:241], v251 offset:9600
	s_waitcnt lgkmcnt(14)
	v_pk_fma_f32 v[48:49], v[242:243], v[30:31], v[48:49] op_sel:[0,1,0] op_sel_hi:[1,1,1] neg_lo:[1,0,0] neg_hi:[1,0,0]
	v_pk_fma_f32 v[50:51], v[244:245], v[30:31], v[50:51] op_sel:[0,1,0] op_sel_hi:[1,1,1] neg_lo:[1,0,0] neg_hi:[1,0,0]
	ds_read_b128 v[242:245], v251 offset:9616
	s_waitcnt lgkmcnt(14)
; #define PG8_LAS __attribute__((address_space(3)))
; __device__ __forceinline__ void solve64(float (&x)[64], const PG8_LAS float* sLt) {
;     f32x4 cur[16];
; #pragma unroll
;     for (int i4 = 0; i4 < 16; ++i4) cur[i4] = *(const PG8_LAS f32x4*)(sLt + 4 * i4);
;     asm volatile("" ::: "memory");
; #pragma unroll
;     for (int j = 0; j < 63; ++j) {
;         const float xj = x[j];
; #pragma unroll
;         for (int i4 = (j + 1) / 4; i4 < 16; ++i4) {
;             if (4 * i4 + 0 > j) x[4 * i4 + 0] -= cur[i4][0] * xj;
;             if (4 * i4 + 1 > j) x[4 * i4 + 1] -= cur[i4][1] * xj;
;             if (4 * i4 + 2 > j) x[4 * i4 + 2] -= cur[i4][2] * xj;
;             if (4 * i4 + 3 > j) x[4 * i4 + 3] -= cur[i4][3] * xj;
;             if (j + 1 < 63 && i4 >= (j + 2) / 4) cur[i4] = *(const PG8_LAS f32x4*)(sLt + (j + 1) * 64 + 4 * i4); }
;         asm volatile("" ::: "memory");
;     }
; }
; __device__ __forceinline__ void phase_prep(const Args& a, PG8_LAS unsigned char* lds) {
;     ...
; #pragma unroll
;             for (int cc = 0; cc < 2; ++cc) { const int ct = 2 * lw + cc;
;                 pv[cc][0] = *(const bf16x8*)(vTb + (size_t)(16 * ct + r) * 64 + 8 * q); pv[cc][1] = *(const bf16x8*)(vTb + (size_t)(16 * ct + r) * 64 + 32 + 8 * q);
;                 pk[cc][0] = *(const bf16x8*)(kTb + (size_t)(16 * ct + r) * 64 + 8 * q); pk[cc][1] = *(const bf16x8*)(kTb + (size_t)(16 * ct + r) * 64 + 32 + 8 * q); }
	v_pk_fma_f32 v[52:53], v[246:247], v[30:31], v[52:53] op_sel:[0,1,0] op_sel_hi:[1,1,1] neg_lo:[1,0,0] neg_hi:[1,0,0]
	v_pk_fma_f32 v[54:55], v[248:249], v[30:31], v[54:55] op_sel:[0,1,0] op_sel_hi:[1,1,1] neg_lo:[1,0,0] neg_hi:[1,0,0]
	ds_read_b128 v[246:249], v251 offset:9632
	s_waitcnt lgkmcnt(14)
	v_pk_fma_f32 v[56:57], v[64:65], v[30:31], v[56:57] op_sel:[0,1,0] op_sel_hi:[1,1,1] neg_lo:[1,0,0] neg_hi:[1,0,0]
	v_pk_fma_f32 v[58:59], v[66:67], v[30:31], v[58:59] op_sel:[0,1,0] op_sel_hi:[1,1,1] neg_lo:[1,0,0] neg_hi:[1,0,0]
	ds_read_b128 v[64:67], v251 offset:9648
	s_waitcnt lgkmcnt(14)
	v_pk_fma_f32 v[60:61], v[68:69], v[30:31], v[60:61] op_sel:[0,1,0] op_sel_hi:[1,1,1] neg_lo:[1,0,0] neg_hi:[1,0,0]
	v_pk_fma_f32 v[62:63], v[70:71], v[30:31], v[62:63] op_sel:[0,1,0] op_sel_hi:[1,1,1] neg_lo:[1,0,0] neg_hi:[1,0,0]
	ds_read_b128 v[68:71], v251 offset:9664
	v_mov_b32_e32 v115, v97
	v_lshl_add_u64 v[0:1], s[22:23], 0, v[114:115]
	v_lshl_add_u64 v[8:9], s[20:21], 0, v[114:115]
	v_lshl_add_u64 v[16:17], v[0:1], 0, v[96:97]
	v_lshl_add_u64 v[24:25], v[8:9], 0, v[96:97]
	global_load_dwordx4 v[0:3], v[16:17], off
	global_load_dwordx4 v[4:7], v[16:17], off offset:64
	global_load_dwordx4 v[8:11], v[24:25], off
	global_load_dwordx4 v[12:15], v[24:25], off offset:64
	global_load_dwordx4 v[20:23], v[16:17], off offset:2048
	global_load_dwordx4 v[28:31], v[16:17], off offset:2112
	s_nop 0
	global_load_dwordx4 v[16:19], v[24:25], off offset:2048
	s_nop 0
	global_load_dwordx4 v[24:27], v[24:25], off offset:2112
	v_pk_mul_f32 v[126:127], v[32:33], v[128:129] op_sel:[0,0] op_sel_hi:[0,1]
	s_nop 0
	v_cvt_pk_bf16_f32 v126, v126, v127
	s_nop 0
	ds_write_b16 v205, v126 offset:22016
	ds_write_b16_d16_hi v205, v126 offset:31232
	s_waitcnt lgkmcnt(15)
	v_fma_f32 v33, -v73, v32, v33
	v_pk_fma_f32 v[34:35], v[74:75], v[32:33], v[34:35] op_sel:[0,0,0] op_sel_hi:[1,0,1] neg_lo:[1,0,0] neg_hi:[1,0,0]
	ds_read_b128 v[72:75], v251 offset:9680
	s_waitcnt lgkmcnt(15)
	v_pk_fma_f32 v[36:37], v[76:77], v[32:33], v[36:37] op_sel:[0,0,0] op_sel_hi:[1,0,1] neg_lo:[1,0,0] neg_hi:[1,0,0]
	v_pk_fma_f32 v[38:39], v[78:79], v[32:33], v[38:39] op_sel:[0,0,0] op_sel_hi:[1,0,1] neg_lo:[1,0,0] neg_hi:[1,0,0]
	ds_read_b128 v[76:79], v251 offset:9696
	s_waitcnt lgkmcnt(15)
	v_pk_fma_f32 v[40:41], v[80:81], v[32:33], v[40:41] op_sel:[0,0,0] op_sel_hi:[1,0,1] neg_lo:[1,0,0] neg_hi:[1,0,0]
	v_pk_fma_f32 v[42:43], v[82:83], v[32:33], v[42:43] op_sel:[0,0,0] op_sel_hi:[1,0,1] neg_lo:[1,0,0] neg_hi:[1,0,0]
	ds_read_b128 v[80:83], v251 offset:9712
	s_waitcnt lgkmcnt(15)
	v_pk_fma_f32 v[44:45], v[84:85], v[32:33], v[44:45] op_sel:[0,0,0] op_sel_hi:[1,0,1] neg_lo:[1,0,0] neg_hi:[1,0,0]
	v_pk_fma_f32 v[46:47], v[86:87], v[32:33], v[46:47] op_sel:[0,0,0] op_sel_hi:[1,0,1] neg_lo:[1,0,0] neg_hi:[1,0,0]
	ds_read_b128 v[84:87], v251 offset:9856
	s_waitcnt lgkmcnt(15)
	v_pk_fma_f32 v[48:49], v[88:89], v[32:33], v[48:49] op_sel:[0,0,0] op_sel_hi:[1,0,1] neg_lo:[1,0,0] neg_hi:[1,0,0]
	v_pk_fma_f32 v[50:51], v[90:91], v[32:33], v[50:51] op_sel:[0,0,0] op_sel_hi:[1,0,1] neg_lo:[1,0,0] neg_hi:[1,0,0]
	ds_read_b128 v[88:91], v251 offset:9872
	s_waitcnt lgkmcnt(14)
	v_pk_fma_f32 v[52:53], v[92:93], v[32:33], v[52:53] op_sel:[0,0,0] op_sel_hi:[1,0,1] neg_lo:[1,0,0] neg_hi:[1,0,0]
	v_pk_fma_f32 v[54:55], v[94:95], v[32:33], v[54:55] op_sel:[0,0,0] op_sel_hi:[1,0,1] neg_lo:[1,0,0] neg_hi:[1,0,0]
	ds_read_b128 v[92:95], v251 offset:9888
	s_waitcnt lgkmcnt(14)
	v_pk_fma_f32 v[56:57], v[230:231], v[32:33], v[56:57] op_sel:[0,0,0] op_sel_hi:[1,0,1] neg_lo:[1,0,0] neg_hi:[1,0,0]
	v_pk_fma_f32 v[58:59], v[232:233], v[32:33], v[58:59] op_sel:[0,0,0] op_sel_hi:[1,0,1] neg_lo:[1,0,0] neg_hi:[1,0,0]
	ds_read_b128 v[230:233], v251 offset:9904
	s_waitcnt lgkmcnt(14)
	v_pk_fma_f32 v[60:61], v[234:235], v[32:33], v[60:61] op_sel:[0,0,0] op_sel_hi:[1,0,1] neg_lo:[1,0,0] neg_hi:[1,0,0]
	v_pk_fma_f32 v[62:63], v[236:237], v[32:33], v[62:63] op_sel:[0,0,0] op_sel_hi:[1,0,1] neg_lo:[1,0,0] neg_hi:[1,0,0]
	ds_read_b128 v[234:237], v251 offset:9920
	v_pk_mul_f32 v[126:127], v[32:33], v[128:129] op_sel:[1,0] op_sel_hi:[1,1]
	s_nop 0
	v_cvt_pk_bf16_f32 v126, v126, v127
	s_nop 0
	ds_write_b16 v205, v126 offset:22160
	ds_write_b16_d16_hi v205, v126 offset:31376
	s_waitcnt lgkmcnt(15)
	v_pk_fma_f32 v[34:35], v[240:241], v[32:33], v[34:35] op_sel:[0,1,0] op_sel_hi:[1,1,1] neg_lo:[1,0,0] neg_hi:[1,0,0]
	ds_read_b128 v[238:241], v251 offset:9936
	s_waitcnt lgkmcnt(15)
	v_pk_fma_f32 v[36:37], v[242:243], v[32:33], v[36:37] op_sel:[0,1,0] op_sel_hi:[1,1,1] neg_lo:[1,0,0] neg_hi:[1,0,0]
	v_pk_fma_f32 v[38:39], v[244:245], v[32:33], v[38:39] op_sel:[0,1,0] op_sel_hi:[1,1,1] neg_lo:[1,0,0] neg_hi:[1,0,0]
	ds_read_b128 v[242:245], v251 offset:9952
	s_waitcnt lgkmcnt(15)
	v_pk_fma_f32 v[40:41], v[246:247], v[32:33], v[40:41] op_sel:[0,1,0] op_sel_hi:[1,1,1] neg_lo:[1,0,0] neg_hi:[1,0,0]
	v_pk_fma_f32 v[42:43], v[248:249], v[32:33], v[42:43] op_sel:[0,1,0] op_sel_hi:[1,1,1] neg_lo:[1,0,0] neg_hi:[1,0,0]
	ds_read_b128 v[246:249], v251 offset:9968
	s_waitcnt lgkmcnt(15)
	v_pk_fma_f32 v[44:45], v[64:65], v[32:33], v[44:45] op_sel:[0,1,0] op_sel_hi:[1,1,1] neg_lo:[1,0,0] neg_hi:[1,0,0]
	v_pk_fma_f32 v[46:47], v[66:67], v[32:33], v[46:47] op_sel:[0,1,0] op_sel_hi:[1,1,1] neg_lo:[1,0,0] neg_hi:[1,0,0]
	ds_read_b128 v[64:67], v251 offset:10128
	s_waitcnt lgkmcnt(15)
	v_pk_fma_f32 v[48:49], v[68:69], v[32:33], v[48:49] op_sel:[0,1,0] op_sel_hi:[1,1,1] neg_lo:[1,0,0] neg_hi:[1,0,0]
	v_pk_fma_f32 v[50:51], v[70:71], v[32:33], v[50:51] op_sel:[0,1,0] op_sel_hi:[1,1,1] neg_lo:[1,0,0] neg_hi:[1,0,0]
	ds_read_b128 v[68:71], v251 offset:10144
	s_waitcnt lgkmcnt(14)
; #define PG8_LAS __attribute__((address_space(3)))
; __device__ __forceinline__ bf16_t f2bf(float x) { return (bf16_t)(pk2(x, x) & 0xffffu); }
; __device__ __forceinline__ void solve64(float (&x)[64], const PG8_LAS float* sLt) {
;     f32x4 cur[16];
; #pragma unroll
;     for (int i4 = 0; i4 < 16; ++i4) cur[i4] = *(const PG8_LAS f32x4*)(sLt + 4 * i4);
;     asm volatile("" ::: "memory");
; #pragma unroll
;     for (int j = 0; j < 63; ++j) {
;         const float xj = x[j];
; #pragma unroll
;         for (int i4 = (j + 1) / 4; i4 < 16; ++i4) {
;             if (4 * i4 + 0 > j) x[4 * i4 + 0] -= cur[i4][0] * xj;
;             if (4 * i4 + 1 > j) x[4 * i4 + 1] -= cur[i4][1] * xj;
;             if (4 * i4 + 2 > j) x[4 * i4 + 2] -= cur[i4][2] * xj;
;             if (4 * i4 + 3 > j) x[4 * i4 + 3] -= cur[i4][3] * xj;
;             if (j + 1 < 63 && i4 >= (j + 2) / 4) cur[i4] = *(const PG8_LAS f32x4*)(sLt + (j + 1) * 64 + 4 * i4); }
;         asm volatile("" ::: "memory");
;     }
; }
; __device__ __forceinline__ void phase_prep(const Args& a, PG8_LAS unsigned char* lds) {
;     ...
;             const float bj = sB[lane], bej = bj * sE[lane];
; #pragma unroll
;             for (int i = 0; i < 64; ++i) { *(PG8_LAS bf16_t*)(Tu + (i * 72 + lane) * 2) = f2bf(x[i] * bj); *(PG8_LAS bf16_t*)(Tw + (i * 72 + lane) * 2) = f2bf(x[i] * bej); }
	v_pk_fma_f32 v[52:53], v[72:73], v[32:33], v[52:53] op_sel:[0,1,0] op_sel_hi:[1,1,1] neg_lo:[1,0,0] neg_hi:[1,0,0]
	v_pk_fma_f32 v[54:55], v[74:75], v[32:33], v[54:55] op_sel:[0,1,0] op_sel_hi:[1,1,1] neg_lo:[1,0,0] neg_hi:[1,0,0]
	ds_read_b128 v[72:75], v251 offset:10160
	s_waitcnt lgkmcnt(14)
	v_pk_fma_f32 v[56:57], v[76:77], v[32:33], v[56:57] op_sel:[0,1,0] op_sel_hi:[1,1,1] neg_lo:[1,0,0] neg_hi:[1,0,0]
	v_pk_fma_f32 v[58:59], v[78:79], v[32:33], v[58:59] op_sel:[0,1,0] op_sel_hi:[1,1,1] neg_lo:[1,0,0] neg_hi:[1,0,0]
	ds_read_b128 v[76:79], v251 offset:10176
	s_waitcnt lgkmcnt(14)
	v_pk_fma_f32 v[60:61], v[80:81], v[32:33], v[60:61] op_sel:[0,1,0] op_sel_hi:[1,1,1] neg_lo:[1,0,0] neg_hi:[1,0,0]
	v_pk_fma_f32 v[62:63], v[82:83], v[32:33], v[62:63] op_sel:[0,1,0] op_sel_hi:[1,1,1] neg_lo:[1,0,0] neg_hi:[1,0,0]
	ds_read_b128 v[80:83], v251 offset:10192
	v_pk_mul_f32 v[126:127], v[34:35], v[128:129] op_sel:[0,0] op_sel_hi:[0,1]
	s_nop 0
	v_cvt_pk_bf16_f32 v126, v126, v127
	s_nop 0
	ds_write_b16 v205, v126 offset:22304
	ds_write_b16_d16_hi v205, v126 offset:31520
	s_waitcnt lgkmcnt(15)
	v_fma_f32 v35, -v87, v34, v35
	ds_read_b128 v[84:87], v251 offset:10208
	s_waitcnt lgkmcnt(15)
	v_pk_fma_f32 v[36:37], v[88:89], v[34:35], v[36:37] op_sel:[0,0,0] op_sel_hi:[1,0,1] neg_lo:[1,0,0] neg_hi:[1,0,0]
	v_pk_fma_f32 v[38:39], v[90:91], v[34:35], v[38:39] op_sel:[0,0,0] op_sel_hi:[1,0,1] neg_lo:[1,0,0] neg_hi:[1,0,0]
	ds_read_b128 v[88:91], v251 offset:10224
	s_waitcnt lgkmcnt(15)
	v_pk_fma_f32 v[40:41], v[92:93], v[34:35], v[40:41] op_sel:[0,0,0] op_sel_hi:[1,0,1] neg_lo:[1,0,0] neg_hi:[1,0,0]
	v_pk_fma_f32 v[42:43], v[94:95], v[34:35], v[42:43] op_sel:[0,0,0] op_sel_hi:[1,0,1] neg_lo:[1,0,0] neg_hi:[1,0,0]
	ds_read_b128 v[92:95], v251 offset:10384
	s_waitcnt lgkmcnt(15)
	v_pk_fma_f32 v[44:45], v[230:231], v[34:35], v[44:45] op_sel:[0,0,0] op_sel_hi:[1,0,1] neg_lo:[1,0,0] neg_hi:[1,0,0]
	v_pk_fma_f32 v[46:47], v[232:233], v[34:35], v[46:47] op_sel:[0,0,0] op_sel_hi:[1,0,1] neg_lo:[1,0,0] neg_hi:[1,0,0]
	ds_read_b128 v[230:233], v251 offset:10400
	s_waitcnt lgkmcnt(15)
	v_pk_fma_f32 v[48:49], v[234:235], v[34:35], v[48:49] op_sel:[0,0,0] op_sel_hi:[1,0,1] neg_lo:[1,0,0] neg_hi:[1,0,0]
	v_pk_fma_f32 v[50:51], v[236:237], v[34:35], v[50:51] op_sel:[0,0,0] op_sel_hi:[1,0,1] neg_lo:[1,0,0] neg_hi:[1,0,0]
	ds_read_b128 v[234:237], v251 offset:10416
	s_waitcnt lgkmcnt(14)
	v_pk_fma_f32 v[52:53], v[238:239], v[34:35], v[52:53] op_sel:[0,0,0] op_sel_hi:[1,0,1] neg_lo:[1,0,0] neg_hi:[1,0,0]
	v_pk_fma_f32 v[54:55], v[240:241], v[34:35], v[54:55] op_sel:[0,0,0] op_sel_hi:[1,0,1] neg_lo:[1,0,0] neg_hi:[1,0,0]
	ds_read_b128 v[238:241], v251 offset:10432
	s_waitcnt lgkmcnt(14)
	v_pk_fma_f32 v[56:57], v[242:243], v[34:35], v[56:57] op_sel:[0,0,0] op_sel_hi:[1,0,1] neg_lo:[1,0,0] neg_hi:[1,0,0]
	v_pk_fma_f32 v[58:59], v[244:245], v[34:35], v[58:59] op_sel:[0,0,0] op_sel_hi:[1,0,1] neg_lo:[1,0,0] neg_hi:[1,0,0]
	ds_read_b128 v[242:245], v251 offset:10448
	s_waitcnt lgkmcnt(14)
	v_pk_fma_f32 v[60:61], v[246:247], v[34:35], v[60:61] op_sel:[0,0,0] op_sel_hi:[1,0,1] neg_lo:[1,0,0] neg_hi:[1,0,0]
	v_pk_fma_f32 v[62:63], v[248:249], v[34:35], v[62:63] op_sel:[0,0,0] op_sel_hi:[1,0,1] neg_lo:[1,0,0] neg_hi:[1,0,0]
	ds_read_b128 v[246:249], v251 offset:10464
	v_pk_mul_f32 v[126:127], v[34:35], v[128:129] op_sel:[1,0] op_sel_hi:[1,1]
	s_nop 0
	v_cvt_pk_bf16_f32 v126, v126, v127
	s_nop 0
	ds_write_b16 v205, v126 offset:22448
	ds_write_b16_d16_hi v205, v126 offset:31664
	s_waitcnt lgkmcnt(15)
	v_pk_fma_f32 v[36:37], v[64:65], v[34:35], v[36:37] op_sel:[0,1,0] op_sel_hi:[1,1,1] neg_lo:[1,0,0] neg_hi:[1,0,0]
	v_pk_fma_f32 v[38:39], v[66:67], v[34:35], v[38:39] op_sel:[0,1,0] op_sel_hi:[1,1,1] neg_lo:[1,0,0] neg_hi:[1,0,0]
	ds_read_b128 v[64:67], v251 offset:10480
	s_waitcnt lgkmcnt(15)
	v_pk_fma_f32 v[40:41], v[68:69], v[34:35], v[40:41] op_sel:[0,1,0] op_sel_hi:[1,1,1] neg_lo:[1,0,0] neg_hi:[1,0,0]
	v_pk_fma_f32 v[42:43], v[70:71], v[34:35], v[42:43] op_sel:[0,1,0] op_sel_hi:[1,1,1] neg_lo:[1,0,0] neg_hi:[1,0,0]
	ds_read_b128 v[68:71], v251 offset:10640
	s_waitcnt lgkmcnt(15)
	v_pk_fma_f32 v[44:45], v[72:73], v[34:35], v[44:45] op_sel:[0,1,0] op_sel_hi:[1,1,1] neg_lo:[1,0,0] neg_hi:[1,0,0]
	v_pk_fma_f32 v[46:47], v[74:75], v[34:35], v[46:47] op_sel:[0,1,0] op_sel_hi:[1,1,1] neg_lo:[1,0,0] neg_hi:[1,0,0]
	ds_read_b128 v[72:75], v251 offset:10656
	s_waitcnt lgkmcnt(15)
	v_pk_fma_f32 v[48:49], v[76:77], v[34:35], v[48:49] op_sel:[0,1,0] op_sel_hi:[1,1,1] neg_lo:[1,0,0] neg_hi:[1,0,0]
	v_pk_fma_f32 v[50:51], v[78:79], v[34:35], v[50:51] op_sel:[0,1,0] op_sel_hi:[1,1,1] neg_lo:[1,0,0] neg_hi:[1,0,0]
	ds_read_b128 v[76:79], v251 offset:10672
	s_waitcnt lgkmcnt(15)
	v_pk_fma_f32 v[52:53], v[80:81], v[34:35], v[52:53] op_sel:[0,1,0] op_sel_hi:[1,1,1] neg_lo:[1,0,0] neg_hi:[1,0,0]
	v_pk_fma_f32 v[54:55], v[82:83], v[34:35], v[54:55] op_sel:[0,1,0] op_sel_hi:[1,1,1] neg_lo:[1,0,0] neg_hi:[1,0,0]
	ds_read_b128 v[80:83], v251 offset:10688
	s_waitcnt lgkmcnt(14)
	v_pk_fma_f32 v[56:57], v[84:85], v[34:35], v[56:57] op_sel:[0,1,0] op_sel_hi:[1,1,1] neg_lo:[1,0,0] neg_hi:[1,0,0]
	v_pk_fma_f32 v[58:59], v[86:87], v[34:35], v[58:59] op_sel:[0,1,0] op_sel_hi:[1,1,1] neg_lo:[1,0,0] neg_hi:[1,0,0]
	ds_read_b128 v[84:87], v251 offset:10704
	s_waitcnt lgkmcnt(14)
	v_pk_fma_f32 v[60:61], v[88:89], v[34:35], v[60:61] op_sel:[0,1,0] op_sel_hi:[1,1,1] neg_lo:[1,0,0] neg_hi:[1,0,0]
	v_pk_fma_f32 v[62:63], v[90:91], v[34:35], v[62:63] op_sel:[0,1,0] op_sel_hi:[1,1,1] neg_lo:[1,0,0] neg_hi:[1,0,0]
	ds_read_b128 v[88:91], v251 offset:10720
	v_pk_mul_f32 v[126:127], v[36:37], v[128:129] op_sel:[0,0] op_sel_hi:[0,1]
	s_nop 0
	v_cvt_pk_bf16_f32 v126, v126, v127
	s_nop 0
	ds_write_b16 v205, v126 offset:22592
	ds_write_b16_d16_hi v205, v126 offset:31808
	s_waitcnt lgkmcnt(15)
; #define PG8_LAS __attribute__((address_space(3)))
; __device__ __forceinline__ bf16_t f2bf(float x) { return (bf16_t)(pk2(x, x) & 0xffffu); }
; __device__ __forceinline__ void solve64(float (&x)[64], const PG8_LAS float* sLt) {
;     f32x4 cur[16];
; #pragma unroll
;     for (int i4 = 0; i4 < 16; ++i4) cur[i4] = *(const PG8_LAS f32x4*)(sLt + 4 * i4);
;     asm volatile("" ::: "memory");
; #pragma unroll
;     for (int j = 0; j < 63; ++j) {
;         const float xj = x[j];
; #pragma unroll
;         for (int i4 = (j + 1) / 4; i4 < 16; ++i4) {
;             if (4 * i4 + 0 > j) x[4 * i4 + 0] -= cur[i4][0] * xj;
;             if (4 * i4 + 1 > j) x[4 * i4 + 1] -= cur[i4][1] * xj;
;             if (4 * i4 + 2 > j) x[4 * i4 + 2] -= cur[i4][2] * xj;
;             if (4 * i4 + 3 > j) x[4 * i4 + 3] -= cur[i4][3] * xj;
;             if (j + 1 < 63 && i4 >= (j + 2) / 4) cur[i4] = *(const PG8_LAS f32x4*)(sLt + (j + 1) * 64 + 4 * i4); }
;         asm volatile("" ::: "memory");
;     }
; }
; __device__ __forceinline__ void phase_prep(const Args& a, PG8_LAS unsigned char* lds) {
;     ...
;             const float bj = sB[lane], bej = bj * sE[lane];
; #pragma unroll
;             for (int i = 0; i < 64; ++i) { *(PG8_LAS bf16_t*)(Tu + (i * 72 + lane) * 2) = f2bf(x[i] * bj); *(PG8_LAS bf16_t*)(Tw + (i * 72 + lane) * 2) = f2bf(x[i] * bej); }
	v_fma_f32 v37, -v93, v36, v37
	v_pk_fma_f32 v[38:39], v[94:95], v[36:37], v[38:39] op_sel:[0,0,0] op_sel_hi:[1,0,1] neg_lo:[1,0,0] neg_hi:[1,0,0]
	ds_read_b128 v[92:95], v251 offset:10736
	s_waitcnt lgkmcnt(15)
	v_pk_fma_f32 v[40:41], v[230:231], v[36:37], v[40:41] op_sel:[0,0,0] op_sel_hi:[1,0,1] neg_lo:[1,0,0] neg_hi:[1,0,0]
	v_pk_fma_f32 v[42:43], v[232:233], v[36:37], v[42:43] op_sel:[0,0,0] op_sel_hi:[1,0,1] neg_lo:[1,0,0] neg_hi:[1,0,0]
	ds_read_b128 v[230:233], v251 offset:10896
	s_waitcnt lgkmcnt(15)
	v_pk_fma_f32 v[44:45], v[234:235], v[36:37], v[44:45] op_sel:[0,0,0] op_sel_hi:[1,0,1] neg_lo:[1,0,0] neg_hi:[1,0,0]
	v_pk_fma_f32 v[46:47], v[236:237], v[36:37], v[46:47] op_sel:[0,0,0] op_sel_hi:[1,0,1] neg_lo:[1,0,0] neg_hi:[1,0,0]
	ds_read_b128 v[234:237], v251 offset:10912
	s_waitcnt lgkmcnt(15)
	v_pk_fma_f32 v[48:49], v[238:239], v[36:37], v[48:49] op_sel:[0,0,0] op_sel_hi:[1,0,1] neg_lo:[1,0,0] neg_hi:[1,0,0]
	v_pk_fma_f32 v[50:51], v[240:241], v[36:37], v[50:51] op_sel:[0,0,0] op_sel_hi:[1,0,1] neg_lo:[1,0,0] neg_hi:[1,0,0]
	ds_read_b128 v[238:241], v251 offset:10928
	s_waitcnt lgkmcnt(15)
	v_pk_fma_f32 v[52:53], v[242:243], v[36:37], v[52:53] op_sel:[0,0,0] op_sel_hi:[1,0,1] neg_lo:[1,0,0] neg_hi:[1,0,0]
	v_pk_fma_f32 v[54:55], v[244:245], v[36:37], v[54:55] op_sel:[0,0,0] op_sel_hi:[1,0,1] neg_lo:[1,0,0] neg_hi:[1,0,0]
	ds_read_b128 v[242:245], v251 offset:10944
	s_waitcnt lgkmcnt(15)
	v_pk_fma_f32 v[56:57], v[246:247], v[36:37], v[56:57] op_sel:[0,0,0] op_sel_hi:[1,0,1] neg_lo:[1,0,0] neg_hi:[1,0,0]
	v_pk_fma_f32 v[58:59], v[248:249], v[36:37], v[58:59] op_sel:[0,0,0] op_sel_hi:[1,0,1] neg_lo:[1,0,0] neg_hi:[1,0,0]
	ds_read_b128 v[246:249], v251 offset:10960
	s_waitcnt lgkmcnt(14)
	v_pk_fma_f32 v[60:61], v[64:65], v[36:37], v[60:61] op_sel:[0,0,0] op_sel_hi:[1,0,1] neg_lo:[1,0,0] neg_hi:[1,0,0]
	v_pk_fma_f32 v[62:63], v[66:67], v[36:37], v[62:63] op_sel:[0,0,0] op_sel_hi:[1,0,1] neg_lo:[1,0,0] neg_hi:[1,0,0]
	ds_read_b128 v[64:67], v251 offset:10976
	v_pk_mul_f32 v[126:127], v[36:37], v[128:129] op_sel:[1,0] op_sel_hi:[1,1]
	s_nop 0
	v_cvt_pk_bf16_f32 v126, v126, v127
	s_nop 0
	ds_write_b16 v205, v126 offset:22736
	ds_write_b16_d16_hi v205, v126 offset:31952
	s_waitcnt lgkmcnt(15)
	v_pk_fma_f32 v[38:39], v[70:71], v[36:37], v[38:39] op_sel:[0,1,0] op_sel_hi:[1,1,1] neg_lo:[1,0,0] neg_hi:[1,0,0]
	ds_read_b128 v[68:71], v251 offset:10992
	s_waitcnt lgkmcnt(15)
	v_pk_fma_f32 v[40:41], v[72:73], v[36:37], v[40:41] op_sel:[0,1,0] op_sel_hi:[1,1,1] neg_lo:[1,0,0] neg_hi:[1,0,0]
	v_pk_fma_f32 v[42:43], v[74:75], v[36:37], v[42:43] op_sel:[0,1,0] op_sel_hi:[1,1,1] neg_lo:[1,0,0] neg_hi:[1,0,0]
	ds_read_b128 v[72:75], v251 offset:11168
	s_waitcnt lgkmcnt(15)
	v_pk_fma_f32 v[44:45], v[76:77], v[36:37], v[44:45] op_sel:[0,1,0] op_sel_hi:[1,1,1] neg_lo:[1,0,0] neg_hi:[1,0,0]
	v_pk_fma_f32 v[46:47], v[78:79], v[36:37], v[46:47] op_sel:[0,1,0] op_sel_hi:[1,1,1] neg_lo:[1,0,0] neg_hi:[1,0,0]
	ds_read_b128 v[76:79], v251 offset:11184
	s_waitcnt lgkmcnt(15)
	v_pk_fma_f32 v[48:49], v[80:81], v[36:37], v[48:49] op_sel:[0,1,0] op_sel_hi:[1,1,1] neg_lo:[1,0,0] neg_hi:[1,0,0]
	v_pk_fma_f32 v[50:51], v[82:83], v[36:37], v[50:51] op_sel:[0,1,0] op_sel_hi:[1,1,1] neg_lo:[1,0,0] neg_hi:[1,0,0]
	ds_read_b128 v[80:83], v251 offset:11200
	s_waitcnt lgkmcnt(15)
	v_pk_fma_f32 v[52:53], v[84:85], v[36:37], v[52:53] op_sel:[0,1,0] op_sel_hi:[1,1,1] neg_lo:[1,0,0] neg_hi:[1,0,0]
	v_pk_fma_f32 v[54:55], v[86:87], v[36:37], v[54:55] op_sel:[0,1,0] op_sel_hi:[1,1,1] neg_lo:[1,0,0] neg_hi:[1,0,0]
	ds_read_b128 v[84:87], v251 offset:11216
	s_waitcnt lgkmcnt(15)
	v_pk_fma_f32 v[56:57], v[88:89], v[36:37], v[56:57] op_sel:[0,1,0] op_sel_hi:[1,1,1] neg_lo:[1,0,0] neg_hi:[1,0,0]
	v_pk_fma_f32 v[58:59], v[90:91], v[36:37], v[58:59] op_sel:[0,1,0] op_sel_hi:[1,1,1] neg_lo:[1,0,0] neg_hi:[1,0,0]
	ds_read_b128 v[88:91], v251 offset:11232
	s_waitcnt lgkmcnt(14)
	v_pk_fma_f32 v[60:61], v[92:93], v[36:37], v[60:61] op_sel:[0,1,0] op_sel_hi:[1,1,1] neg_lo:[1,0,0] neg_hi:[1,0,0]
	v_pk_fma_f32 v[62:63], v[94:95], v[36:37], v[62:63] op_sel:[0,1,0] op_sel_hi:[1,1,1] neg_lo:[1,0,0] neg_hi:[1,0,0]
	ds_read_b128 v[92:95], v251 offset:11248
	v_pk_mul_f32 v[126:127], v[38:39], v[128:129] op_sel:[0,0] op_sel_hi:[0,1]
	s_nop 0
	v_cvt_pk_bf16_f32 v126, v126, v127
	s_nop 0
	ds_write_b16 v205, v126 offset:22880
	ds_write_b16_d16_hi v205, v126 offset:32096
	s_waitcnt lgkmcnt(15)
	v_fma_f32 v39, -v233, v38, v39
	ds_read_b128 v[230:233], v251 offset:11424
	s_waitcnt lgkmcnt(15)
	v_pk_fma_f32 v[40:41], v[234:235], v[38:39], v[40:41] op_sel:[0,0,0] op_sel_hi:[1,0,1] neg_lo:[1,0,0] neg_hi:[1,0,0]
	v_pk_fma_f32 v[42:43], v[236:237], v[38:39], v[42:43] op_sel:[0,0,0] op_sel_hi:[1,0,1] neg_lo:[1,0,0] neg_hi:[1,0,0]
	ds_read_b128 v[234:237], v251 offset:11440
	s_waitcnt lgkmcnt(15)
	v_pk_fma_f32 v[44:45], v[238:239], v[38:39], v[44:45] op_sel:[0,0,0] op_sel_hi:[1,0,1] neg_lo:[1,0,0] neg_hi:[1,0,0]
	v_pk_fma_f32 v[46:47], v[240:241], v[38:39], v[46:47] op_sel:[0,0,0] op_sel_hi:[1,0,1] neg_lo:[1,0,0] neg_hi:[1,0,0]
	ds_read_b128 v[238:241], v251 offset:11456
	s_waitcnt lgkmcnt(15)
	v_pk_fma_f32 v[48:49], v[242:243], v[38:39], v[48:49] op_sel:[0,0,0] op_sel_hi:[1,0,1] neg_lo:[1,0,0] neg_hi:[1,0,0]
	v_pk_fma_f32 v[50:51], v[244:245], v[38:39], v[50:51] op_sel:[0,0,0] op_sel_hi:[1,0,1] neg_lo:[1,0,0] neg_hi:[1,0,0]
	ds_read_b128 v[242:245], v251 offset:11472
	s_waitcnt lgkmcnt(15)
	v_pk_fma_f32 v[52:53], v[246:247], v[38:39], v[52:53] op_sel:[0,0,0] op_sel_hi:[1,0,1] neg_lo:[1,0,0] neg_hi:[1,0,0]
	v_pk_fma_f32 v[54:55], v[248:249], v[38:39], v[54:55] op_sel:[0,0,0] op_sel_hi:[1,0,1] neg_lo:[1,0,0] neg_hi:[1,0,0]
	ds_read_b128 v[246:249], v251 offset:11488
	s_waitcnt lgkmcnt(15)
; #define PG8_LAS __attribute__((address_space(3)))
; __device__ __forceinline__ bf16_t f2bf(float x) { return (bf16_t)(pk2(x, x) & 0xffffu); }
; __device__ __forceinline__ void solve64(float (&x)[64], const PG8_LAS float* sLt) {
;     f32x4 cur[16];
; #pragma unroll
;     for (int i4 = 0; i4 < 16; ++i4) cur[i4] = *(const PG8_LAS f32x4*)(sLt + 4 * i4);
;     asm volatile("" ::: "memory");
; #pragma unroll
;     for (int j = 0; j < 63; ++j) {
;         const float xj = x[j];
; #pragma unroll
;         for (int i4 = (j + 1) / 4; i4 < 16; ++i4) {
;             if (4 * i4 + 0 > j) x[4 * i4 + 0] -= cur[i4][0] * xj;
;             if (4 * i4 + 1 > j) x[4 * i4 + 1] -= cur[i4][1] * xj;
;             if (4 * i4 + 2 > j) x[4 * i4 + 2] -= cur[i4][2] * xj;
;             if (4 * i4 + 3 > j) x[4 * i4 + 3] -= cur[i4][3] * xj;
;             if (j + 1 < 63 && i4 >= (j + 2) / 4) cur[i4] = *(const PG8_LAS f32x4*)(sLt + (j + 1) * 64 + 4 * i4); }
;         asm volatile("" ::: "memory");
;     }
; }
; __device__ __forceinline__ void phase_prep(const Args& a, PG8_LAS unsigned char* lds) {
;     ...
;             const float bj = sB[lane], bej = bj * sE[lane];
; #pragma unroll
;             for (int i = 0; i < 64; ++i) { *(PG8_LAS bf16_t*)(Tu + (i * 72 + lane) * 2) = f2bf(x[i] * bj); *(PG8_LAS bf16_t*)(Tw + (i * 72 + lane) * 2) = f2bf(x[i] * bej); }
	v_pk_fma_f32 v[56:57], v[64:65], v[38:39], v[56:57] op_sel:[0,0,0] op_sel_hi:[1,0,1] neg_lo:[1,0,0] neg_hi:[1,0,0]
	v_pk_fma_f32 v[58:59], v[66:67], v[38:39], v[58:59] op_sel:[0,0,0] op_sel_hi:[1,0,1] neg_lo:[1,0,0] neg_hi:[1,0,0]
	ds_read_b128 v[64:67], v251 offset:11504
	s_waitcnt lgkmcnt(14)
	v_pk_fma_f32 v[60:61], v[68:69], v[38:39], v[60:61] op_sel:[0,0,0] op_sel_hi:[1,0,1] neg_lo:[1,0,0] neg_hi:[1,0,0]
	v_pk_fma_f32 v[62:63], v[70:71], v[38:39], v[62:63] op_sel:[0,0,0] op_sel_hi:[1,0,1] neg_lo:[1,0,0] neg_hi:[1,0,0]
	ds_read_b128 v[68:71], v251 offset:11680
	v_pk_mul_f32 v[126:127], v[38:39], v[128:129] op_sel:[1,0] op_sel_hi:[1,1]
	s_nop 0
	v_cvt_pk_bf16_f32 v126, v126, v127
	s_nop 0
	ds_write_b16 v205, v126 offset:23024
	ds_write_b16_d16_hi v205, v126 offset:32240
	s_waitcnt lgkmcnt(15)
	v_pk_fma_f32 v[40:41], v[72:73], v[38:39], v[40:41] op_sel:[0,1,0] op_sel_hi:[1,1,1] neg_lo:[1,0,0] neg_hi:[1,0,0]
	v_pk_fma_f32 v[42:43], v[74:75], v[38:39], v[42:43] op_sel:[0,1,0] op_sel_hi:[1,1,1] neg_lo:[1,0,0] neg_hi:[1,0,0]
	ds_read_b128 v[72:75], v251 offset:11696
	s_waitcnt lgkmcnt(15)
	v_pk_fma_f32 v[44:45], v[76:77], v[38:39], v[44:45] op_sel:[0,1,0] op_sel_hi:[1,1,1] neg_lo:[1,0,0] neg_hi:[1,0,0]
	v_pk_fma_f32 v[46:47], v[78:79], v[38:39], v[46:47] op_sel:[0,1,0] op_sel_hi:[1,1,1] neg_lo:[1,0,0] neg_hi:[1,0,0]
	ds_read_b128 v[76:79], v251 offset:11712
	s_waitcnt lgkmcnt(15)
	v_pk_fma_f32 v[48:49], v[80:81], v[38:39], v[48:49] op_sel:[0,1,0] op_sel_hi:[1,1,1] neg_lo:[1,0,0] neg_hi:[1,0,0]
	v_pk_fma_f32 v[50:51], v[82:83], v[38:39], v[50:51] op_sel:[0,1,0] op_sel_hi:[1,1,1] neg_lo:[1,0,0] neg_hi:[1,0,0]
	ds_read_b128 v[80:83], v251 offset:11728
	s_waitcnt lgkmcnt(15)
	v_pk_fma_f32 v[52:53], v[84:85], v[38:39], v[52:53] op_sel:[0,1,0] op_sel_hi:[1,1,1] neg_lo:[1,0,0] neg_hi:[1,0,0]
	v_pk_fma_f32 v[54:55], v[86:87], v[38:39], v[54:55] op_sel:[0,1,0] op_sel_hi:[1,1,1] neg_lo:[1,0,0] neg_hi:[1,0,0]
	ds_read_b128 v[84:87], v251 offset:11744
	s_waitcnt lgkmcnt(15)
	v_pk_fma_f32 v[56:57], v[88:89], v[38:39], v[56:57] op_sel:[0,1,0] op_sel_hi:[1,1,1] neg_lo:[1,0,0] neg_hi:[1,0,0]
	v_pk_fma_f32 v[58:59], v[90:91], v[38:39], v[58:59] op_sel:[0,1,0] op_sel_hi:[1,1,1] neg_lo:[1,0,0] neg_hi:[1,0,0]
	ds_read_b128 v[88:91], v251 offset:11760
	s_waitcnt lgkmcnt(15)
	v_pk_fma_f32 v[60:61], v[92:93], v[38:39], v[60:61] op_sel:[0,1,0] op_sel_hi:[1,1,1] neg_lo:[1,0,0] neg_hi:[1,0,0]
	v_pk_fma_f32 v[62:63], v[94:95], v[38:39], v[62:63] op_sel:[0,1,0] op_sel_hi:[1,1,1] neg_lo:[1,0,0] neg_hi:[1,0,0]
	ds_read_b128 v[92:95], v251 offset:11936
	v_pk_mul_f32 v[126:127], v[40:41], v[128:129] op_sel:[0,0] op_sel_hi:[0,1]
	s_nop 0
	v_cvt_pk_bf16_f32 v126, v126, v127
	s_nop 0
	ds_write_b16 v205, v126 offset:23168
	ds_write_b16_d16_hi v205, v126 offset:32384
	s_waitcnt lgkmcnt(15)
	v_fma_f32 v41, -v231, v40, v41
	v_pk_fma_f32 v[42:43], v[232:233], v[40:41], v[42:43] op_sel:[0,0,0] op_sel_hi:[1,0,1] neg_lo:[1,0,0] neg_hi:[1,0,0]
	ds_read_b128 v[230:233], v251 offset:11952
	s_waitcnt lgkmcnt(15)
	v_pk_fma_f32 v[44:45], v[234:235], v[40:41], v[44:45] op_sel:[0,0,0] op_sel_hi:[1,0,1] neg_lo:[1,0,0] neg_hi:[1,0,0]
	v_pk_fma_f32 v[46:47], v[236:237], v[40:41], v[46:47] op_sel:[0,0,0] op_sel_hi:[1,0,1] neg_lo:[1,0,0] neg_hi:[1,0,0]
	ds_read_b128 v[234:237], v251 offset:11968
	s_waitcnt lgkmcnt(15)
	v_pk_fma_f32 v[48:49], v[238:239], v[40:41], v[48:49] op_sel:[0,0,0] op_sel_hi:[1,0,1] neg_lo:[1,0,0] neg_hi:[1,0,0]
	v_pk_fma_f32 v[50:51], v[240:241], v[40:41], v[50:51] op_sel:[0,0,0] op_sel_hi:[1,0,1] neg_lo:[1,0,0] neg_hi:[1,0,0]
	ds_read_b128 v[238:241], v251 offset:11984
	s_waitcnt lgkmcnt(15)
	v_pk_fma_f32 v[52:53], v[242:243], v[40:41], v[52:53] op_sel:[0,0,0] op_sel_hi:[1,0,1] neg_lo:[1,0,0] neg_hi:[1,0,0]
	v_pk_fma_f32 v[54:55], v[244:245], v[40:41], v[54:55] op_sel:[0,0,0] op_sel_hi:[1,0,1] neg_lo:[1,0,0] neg_hi:[1,0,0]
	ds_read_b128 v[242:245], v251 offset:12000
	s_waitcnt lgkmcnt(15)
	v_pk_fma_f32 v[56:57], v[246:247], v[40:41], v[56:57] op_sel:[0,0,0] op_sel_hi:[1,0,1] neg_lo:[1,0,0] neg_hi:[1,0,0]
	v_pk_fma_f32 v[58:59], v[248:249], v[40:41], v[58:59] op_sel:[0,0,0] op_sel_hi:[1,0,1] neg_lo:[1,0,0] neg_hi:[1,0,0]
	ds_read_b128 v[246:249], v251 offset:12016
	s_waitcnt lgkmcnt(15)
	v_pk_fma_f32 v[60:61], v[64:65], v[40:41], v[60:61] op_sel:[0,0,0] op_sel_hi:[1,0,1] neg_lo:[1,0,0] neg_hi:[1,0,0]
	v_pk_fma_f32 v[62:63], v[66:67], v[40:41], v[62:63] op_sel:[0,0,0] op_sel_hi:[1,0,1] neg_lo:[1,0,0] neg_hi:[1,0,0]
	ds_read_b128 v[64:67], v251 offset:12208
	v_pk_mul_f32 v[126:127], v[40:41], v[128:129] op_sel:[1,0] op_sel_hi:[1,1]
	s_nop 0
	v_cvt_pk_bf16_f32 v126, v126, v127
	s_nop 0
	ds_write_b16 v205, v126 offset:23312
	ds_write_b16_d16_hi v205, v126 offset:32528
	s_waitcnt lgkmcnt(15)
	v_pk_fma_f32 v[42:43], v[70:71], v[40:41], v[42:43] op_sel:[0,1,0] op_sel_hi:[1,1,1] neg_lo:[1,0,0] neg_hi:[1,0,0]
	ds_read_b128 v[68:71], v251 offset:12224
	s_waitcnt lgkmcnt(15)
	v_pk_fma_f32 v[44:45], v[72:73], v[40:41], v[44:45] op_sel:[0,1,0] op_sel_hi:[1,1,1] neg_lo:[1,0,0] neg_hi:[1,0,0]
	v_pk_fma_f32 v[46:47], v[74:75], v[40:41], v[46:47] op_sel:[0,1,0] op_sel_hi:[1,1,1] neg_lo:[1,0,0] neg_hi:[1,0,0]
	ds_read_b128 v[72:75], v251 offset:12240
	s_waitcnt lgkmcnt(15)
	v_pk_fma_f32 v[48:49], v[76:77], v[40:41], v[48:49] op_sel:[0,1,0] op_sel_hi:[1,1,1] neg_lo:[1,0,0] neg_hi:[1,0,0]
	v_pk_fma_f32 v[50:51], v[78:79], v[40:41], v[50:51] op_sel:[0,1,0] op_sel_hi:[1,1,1] neg_lo:[1,0,0] neg_hi:[1,0,0]
	ds_read_b128 v[76:79], v251 offset:12256
	s_waitcnt lgkmcnt(15)
; #define PG8_LAS __attribute__((address_space(3)))
; __device__ __forceinline__ bf16_t f2bf(float x) { return (bf16_t)(pk2(x, x) & 0xffffu); }
; __device__ __forceinline__ void solve64(float (&x)[64], const PG8_LAS float* sLt) {
;     f32x4 cur[16];
; #pragma unroll
;     for (int i4 = 0; i4 < 16; ++i4) cur[i4] = *(const PG8_LAS f32x4*)(sLt + 4 * i4);
;     asm volatile("" ::: "memory");
; #pragma unroll
;     for (int j = 0; j < 63; ++j) {
;         const float xj = x[j];
; #pragma unroll
;         for (int i4 = (j + 1) / 4; i4 < 16; ++i4) {
;             if (4 * i4 + 0 > j) x[4 * i4 + 0] -= cur[i4][0] * xj;
;             if (4 * i4 + 1 > j) x[4 * i4 + 1] -= cur[i4][1] * xj;
;             if (4 * i4 + 2 > j) x[4 * i4 + 2] -= cur[i4][2] * xj;
;             if (4 * i4 + 3 > j) x[4 * i4 + 3] -= cur[i4][3] * xj;
;             if (j + 1 < 63 && i4 >= (j + 2) / 4) cur[i4] = *(const PG8_LAS f32x4*)(sLt + (j + 1) * 64 + 4 * i4); }
;         asm volatile("" ::: "memory");
;     }
; }
; __device__ __forceinline__ void phase_prep(const Args& a, PG8_LAS unsigned char* lds) {
;     ...
;             const float bj = sB[lane], bej = bj * sE[lane];
; #pragma unroll
;             for (int i = 0; i < 64; ++i) { *(PG8_LAS bf16_t*)(Tu + (i * 72 + lane) * 2) = f2bf(x[i] * bj); *(PG8_LAS bf16_t*)(Tw + (i * 72 + lane) * 2) = f2bf(x[i] * bej); }
	v_pk_fma_f32 v[52:53], v[80:81], v[40:41], v[52:53] op_sel:[0,1,0] op_sel_hi:[1,1,1] neg_lo:[1,0,0] neg_hi:[1,0,0]
	v_pk_fma_f32 v[54:55], v[82:83], v[40:41], v[54:55] op_sel:[0,1,0] op_sel_hi:[1,1,1] neg_lo:[1,0,0] neg_hi:[1,0,0]
	ds_read_b128 v[80:83], v251 offset:12272
	s_waitcnt lgkmcnt(15)
	v_pk_fma_f32 v[56:57], v[84:85], v[40:41], v[56:57] op_sel:[0,1,0] op_sel_hi:[1,1,1] neg_lo:[1,0,0] neg_hi:[1,0,0]
	v_pk_fma_f32 v[58:59], v[86:87], v[40:41], v[58:59] op_sel:[0,1,0] op_sel_hi:[1,1,1] neg_lo:[1,0,0] neg_hi:[1,0,0]
	ds_read_b128 v[84:87], v251 offset:12464
	s_waitcnt lgkmcnt(15)
	v_pk_fma_f32 v[60:61], v[88:89], v[40:41], v[60:61] op_sel:[0,1,0] op_sel_hi:[1,1,1] neg_lo:[1,0,0] neg_hi:[1,0,0]
	v_pk_fma_f32 v[62:63], v[90:91], v[40:41], v[62:63] op_sel:[0,1,0] op_sel_hi:[1,1,1] neg_lo:[1,0,0] neg_hi:[1,0,0]
	ds_read_b128 v[88:91], v251 offset:12480
	v_pk_mul_f32 v[126:127], v[42:43], v[128:129] op_sel:[0,0] op_sel_hi:[0,1]
	s_nop 0
	v_cvt_pk_bf16_f32 v126, v126, v127
	s_nop 0
	ds_write_b16 v205, v126 offset:23456
	ds_write_b16_d16_hi v205, v126 offset:32672
	s_waitcnt lgkmcnt(15)
	v_fma_f32 v43, -v95, v42, v43
	ds_read_b128 v[92:95], v251 offset:12496
	s_waitcnt lgkmcnt(15)
	v_pk_fma_f32 v[44:45], v[230:231], v[42:43], v[44:45] op_sel:[0,0,0] op_sel_hi:[1,0,1] neg_lo:[1,0,0] neg_hi:[1,0,0]
	v_pk_fma_f32 v[46:47], v[232:233], v[42:43], v[46:47] op_sel:[0,0,0] op_sel_hi:[1,0,1] neg_lo:[1,0,0] neg_hi:[1,0,0]
	ds_read_b128 v[230:233], v251 offset:12512
	s_waitcnt lgkmcnt(15)
	v_pk_fma_f32 v[48:49], v[234:235], v[42:43], v[48:49] op_sel:[0,0,0] op_sel_hi:[1,0,1] neg_lo:[1,0,0] neg_hi:[1,0,0]
	v_pk_fma_f32 v[50:51], v[236:237], v[42:43], v[50:51] op_sel:[0,0,0] op_sel_hi:[1,0,1] neg_lo:[1,0,0] neg_hi:[1,0,0]
	ds_read_b128 v[234:237], v251 offset:12528
	s_waitcnt lgkmcnt(15)
	v_pk_fma_f32 v[52:53], v[238:239], v[42:43], v[52:53] op_sel:[0,0,0] op_sel_hi:[1,0,1] neg_lo:[1,0,0] neg_hi:[1,0,0]
	v_pk_fma_f32 v[54:55], v[240:241], v[42:43], v[54:55] op_sel:[0,0,0] op_sel_hi:[1,0,1] neg_lo:[1,0,0] neg_hi:[1,0,0]
	ds_read_b128 v[238:241], v251 offset:12720
	s_waitcnt lgkmcnt(15)
	v_pk_fma_f32 v[56:57], v[242:243], v[42:43], v[56:57] op_sel:[0,0,0] op_sel_hi:[1,0,1] neg_lo:[1,0,0] neg_hi:[1,0,0]
	v_pk_fma_f32 v[58:59], v[244:245], v[42:43], v[58:59] op_sel:[0,0,0] op_sel_hi:[1,0,1] neg_lo:[1,0,0] neg_hi:[1,0,0]
	ds_read_b128 v[242:245], v251 offset:12736
	s_waitcnt lgkmcnt(15)
	v_pk_fma_f32 v[60:61], v[246:247], v[42:43], v[60:61] op_sel:[0,0,0] op_sel_hi:[1,0,1] neg_lo:[1,0,0] neg_hi:[1,0,0]
	v_pk_fma_f32 v[62:63], v[248:249], v[42:43], v[62:63] op_sel:[0,0,0] op_sel_hi:[1,0,1] neg_lo:[1,0,0] neg_hi:[1,0,0]
	ds_read_b128 v[246:249], v251 offset:12752
	v_pk_mul_f32 v[126:127], v[42:43], v[128:129] op_sel:[1,0] op_sel_hi:[1,1]
	s_nop 0
	v_cvt_pk_bf16_f32 v126, v126, v127
	s_nop 0
	ds_write_b16 v205, v126 offset:23600
	ds_write_b16_d16_hi v205, v126 offset:32816
	s_waitcnt lgkmcnt(15)
	v_pk_fma_f32 v[44:45], v[64:65], v[42:43], v[44:45] op_sel:[0,1,0] op_sel_hi:[1,1,1] neg_lo:[1,0,0] neg_hi:[1,0,0]
	v_pk_fma_f32 v[46:47], v[66:67], v[42:43], v[46:47] op_sel:[0,1,0] op_sel_hi:[1,1,1] neg_lo:[1,0,0] neg_hi:[1,0,0]
	ds_read_b128 v[64:67], v251 offset:12768
	s_waitcnt lgkmcnt(15)
	v_pk_fma_f32 v[48:49], v[68:69], v[42:43], v[48:49] op_sel:[0,1,0] op_sel_hi:[1,1,1] neg_lo:[1,0,0] neg_hi:[1,0,0]
	v_pk_fma_f32 v[50:51], v[70:71], v[42:43], v[50:51] op_sel:[0,1,0] op_sel_hi:[1,1,1] neg_lo:[1,0,0] neg_hi:[1,0,0]
	ds_read_b128 v[68:71], v251 offset:12784
	s_waitcnt lgkmcnt(15)
	v_pk_fma_f32 v[52:53], v[72:73], v[42:43], v[52:53] op_sel:[0,1,0] op_sel_hi:[1,1,1] neg_lo:[1,0,0] neg_hi:[1,0,0]
	v_pk_fma_f32 v[54:55], v[74:75], v[42:43], v[54:55] op_sel:[0,1,0] op_sel_hi:[1,1,1] neg_lo:[1,0,0] neg_hi:[1,0,0]
	ds_read_b128 v[72:75], v251 offset:12976
	s_waitcnt lgkmcnt(15)
	v_pk_fma_f32 v[56:57], v[76:77], v[42:43], v[56:57] op_sel:[0,1,0] op_sel_hi:[1,1,1] neg_lo:[1,0,0] neg_hi:[1,0,0]
	v_pk_fma_f32 v[58:59], v[78:79], v[42:43], v[58:59] op_sel:[0,1,0] op_sel_hi:[1,1,1] neg_lo:[1,0,0] neg_hi:[1,0,0]
	ds_read_b128 v[76:79], v251 offset:12992
	s_waitcnt lgkmcnt(15)
	v_pk_fma_f32 v[60:61], v[80:81], v[42:43], v[60:61] op_sel:[0,1,0] op_sel_hi:[1,1,1] neg_lo:[1,0,0] neg_hi:[1,0,0]
	v_pk_fma_f32 v[62:63], v[82:83], v[42:43], v[62:63] op_sel:[0,1,0] op_sel_hi:[1,1,1] neg_lo:[1,0,0] neg_hi:[1,0,0]
	ds_read_b128 v[80:83], v251 offset:13008
	v_pk_mul_f32 v[126:127], v[44:45], v[128:129] op_sel:[0,0] op_sel_hi:[0,1]
	s_nop 0
	v_cvt_pk_bf16_f32 v126, v126, v127
	s_nop 0
	ds_write_b16 v205, v126 offset:23744
	ds_write_b16_d16_hi v205, v126 offset:32960
	s_waitcnt lgkmcnt(15)
	v_fma_f32 v45, -v85, v44, v45
	v_pk_fma_f32 v[46:47], v[86:87], v[44:45], v[46:47] op_sel:[0,0,0] op_sel_hi:[1,0,1] neg_lo:[1,0,0] neg_hi:[1,0,0]
	ds_read_b128 v[84:87], v251 offset:13024
	s_waitcnt lgkmcnt(15)
	v_pk_fma_f32 v[48:49], v[88:89], v[44:45], v[48:49] op_sel:[0,0,0] op_sel_hi:[1,0,1] neg_lo:[1,0,0] neg_hi:[1,0,0]
	v_pk_fma_f32 v[50:51], v[90:91], v[44:45], v[50:51] op_sel:[0,0,0] op_sel_hi:[1,0,1] neg_lo:[1,0,0] neg_hi:[1,0,0]
	ds_read_b128 v[88:91], v251 offset:13040
	s_waitcnt lgkmcnt(15)
	v_pk_fma_f32 v[52:53], v[92:93], v[44:45], v[52:53] op_sel:[0,0,0] op_sel_hi:[1,0,1] neg_lo:[1,0,0] neg_hi:[1,0,0]
	v_pk_fma_f32 v[54:55], v[94:95], v[44:45], v[54:55] op_sel:[0,0,0] op_sel_hi:[1,0,1] neg_lo:[1,0,0] neg_hi:[1,0,0]
	ds_read_b128 v[92:95], v251 offset:13248
	s_waitcnt lgkmcnt(15)
	v_pk_fma_f32 v[56:57], v[230:231], v[44:45], v[56:57] op_sel:[0,0,0] op_sel_hi:[1,0,1] neg_lo:[1,0,0] neg_hi:[1,0,0]
	v_pk_fma_f32 v[58:59], v[232:233], v[44:45], v[58:59] op_sel:[0,0,0] op_sel_hi:[1,0,1] neg_lo:[1,0,0] neg_hi:[1,0,0]
	ds_read_b128 v[230:233], v251 offset:13264
	s_waitcnt lgkmcnt(15)
; #define PG8_LAS __attribute__((address_space(3)))
; __device__ __forceinline__ bf16_t f2bf(float x) { return (bf16_t)(pk2(x, x) & 0xffffu); }
; __device__ __forceinline__ void solve64(float (&x)[64], const PG8_LAS float* sLt) {
;     f32x4 cur[16];
; #pragma unroll
;     for (int i4 = 0; i4 < 16; ++i4) cur[i4] = *(const PG8_LAS f32x4*)(sLt + 4 * i4);
;     asm volatile("" ::: "memory");
; #pragma unroll
;     for (int j = 0; j < 63; ++j) {
;         const float xj = x[j];
; #pragma unroll
;         for (int i4 = (j + 1) / 4; i4 < 16; ++i4) {
;             if (4 * i4 + 0 > j) x[4 * i4 + 0] -= cur[i4][0] * xj;
;             if (4 * i4 + 1 > j) x[4 * i4 + 1] -= cur[i4][1] * xj;
;             if (4 * i4 + 2 > j) x[4 * i4 + 2] -= cur[i4][2] * xj;
;             if (4 * i4 + 3 > j) x[4 * i4 + 3] -= cur[i4][3] * xj;
;             if (j + 1 < 63 && i4 >= (j + 2) / 4) cur[i4] = *(const PG8_LAS f32x4*)(sLt + (j + 1) * 64 + 4 * i4); }
;         asm volatile("" ::: "memory");
;     }
; }
; __device__ __forceinline__ void phase_prep(const Args& a, PG8_LAS unsigned char* lds) {
;     ...
;             const float bj = sB[lane], bej = bj * sE[lane];
; #pragma unroll
;             for (int i = 0; i < 64; ++i) { *(PG8_LAS bf16_t*)(Tu + (i * 72 + lane) * 2) = f2bf(x[i] * bj); *(PG8_LAS bf16_t*)(Tw + (i * 72 + lane) * 2) = f2bf(x[i] * bej); }
	v_pk_fma_f32 v[60:61], v[234:235], v[44:45], v[60:61] op_sel:[0,0,0] op_sel_hi:[1,0,1] neg_lo:[1,0,0] neg_hi:[1,0,0]
	v_pk_fma_f32 v[62:63], v[236:237], v[44:45], v[62:63] op_sel:[0,0,0] op_sel_hi:[1,0,1] neg_lo:[1,0,0] neg_hi:[1,0,0]
	ds_read_b128 v[234:237], v251 offset:13280
	v_pk_mul_f32 v[126:127], v[44:45], v[128:129] op_sel:[1,0] op_sel_hi:[1,1]
	s_nop 0
	v_cvt_pk_bf16_f32 v126, v126, v127
	s_nop 0
	ds_write_b16 v205, v126 offset:23888
	ds_write_b16_d16_hi v205, v126 offset:33104
	s_waitcnt lgkmcnt(15)
	v_pk_fma_f32 v[46:47], v[240:241], v[44:45], v[46:47] op_sel:[0,1,0] op_sel_hi:[1,1,1] neg_lo:[1,0,0] neg_hi:[1,0,0]
	ds_read_b128 v[238:241], v251 offset:13296
	s_waitcnt lgkmcnt(15)
	v_pk_fma_f32 v[48:49], v[242:243], v[44:45], v[48:49] op_sel:[0,1,0] op_sel_hi:[1,1,1] neg_lo:[1,0,0] neg_hi:[1,0,0]
	v_pk_fma_f32 v[50:51], v[244:245], v[44:45], v[50:51] op_sel:[0,1,0] op_sel_hi:[1,1,1] neg_lo:[1,0,0] neg_hi:[1,0,0]
	ds_read_b128 v[242:245], v251 offset:13504
	s_waitcnt lgkmcnt(15)
	v_pk_fma_f32 v[52:53], v[246:247], v[44:45], v[52:53] op_sel:[0,1,0] op_sel_hi:[1,1,1] neg_lo:[1,0,0] neg_hi:[1,0,0]
	v_pk_fma_f32 v[54:55], v[248:249], v[44:45], v[54:55] op_sel:[0,1,0] op_sel_hi:[1,1,1] neg_lo:[1,0,0] neg_hi:[1,0,0]
	ds_read_b128 v[246:249], v251 offset:13520
	s_waitcnt lgkmcnt(15)
	v_pk_fma_f32 v[56:57], v[64:65], v[44:45], v[56:57] op_sel:[0,1,0] op_sel_hi:[1,1,1] neg_lo:[1,0,0] neg_hi:[1,0,0]
	v_pk_fma_f32 v[58:59], v[66:67], v[44:45], v[58:59] op_sel:[0,1,0] op_sel_hi:[1,1,1] neg_lo:[1,0,0] neg_hi:[1,0,0]
	ds_read_b128 v[64:67], v251 offset:13536
	s_waitcnt lgkmcnt(15)
	v_pk_fma_f32 v[60:61], v[68:69], v[44:45], v[60:61] op_sel:[0,1,0] op_sel_hi:[1,1,1] neg_lo:[1,0,0] neg_hi:[1,0,0]
	v_pk_fma_f32 v[62:63], v[70:71], v[44:45], v[62:63] op_sel:[0,1,0] op_sel_hi:[1,1,1] neg_lo:[1,0,0] neg_hi:[1,0,0]
	ds_read_b128 v[68:71], v251 offset:13552
	v_pk_mul_f32 v[126:127], v[46:47], v[128:129] op_sel:[0,0] op_sel_hi:[0,1]
	s_nop 0
	v_cvt_pk_bf16_f32 v126, v126, v127
	s_nop 0
	ds_write_b16 v205, v126 offset:24032
	ds_write_b16_d16_hi v205, v126 offset:33248
	s_waitcnt lgkmcnt(15)
	v_fma_f32 v47, -v75, v46, v47
	ds_read_b128 v[72:75], v251 offset:13760
	s_waitcnt lgkmcnt(15)
	v_pk_fma_f32 v[48:49], v[76:77], v[46:47], v[48:49] op_sel:[0,0,0] op_sel_hi:[1,0,1] neg_lo:[1,0,0] neg_hi:[1,0,0]
	v_pk_fma_f32 v[50:51], v[78:79], v[46:47], v[50:51] op_sel:[0,0,0] op_sel_hi:[1,0,1] neg_lo:[1,0,0] neg_hi:[1,0,0]
	ds_read_b128 v[76:79], v251 offset:13776
	s_waitcnt lgkmcnt(15)
	v_pk_fma_f32 v[52:53], v[80:81], v[46:47], v[52:53] op_sel:[0,0,0] op_sel_hi:[1,0,1] neg_lo:[1,0,0] neg_hi:[1,0,0]
	v_pk_fma_f32 v[54:55], v[82:83], v[46:47], v[54:55] op_sel:[0,0,0] op_sel_hi:[1,0,1] neg_lo:[1,0,0] neg_hi:[1,0,0]
	ds_read_b128 v[80:83], v251 offset:13792
	s_waitcnt lgkmcnt(15)
	v_pk_fma_f32 v[56:57], v[84:85], v[46:47], v[56:57] op_sel:[0,0,0] op_sel_hi:[1,0,1] neg_lo:[1,0,0] neg_hi:[1,0,0]
	v_pk_fma_f32 v[58:59], v[86:87], v[46:47], v[58:59] op_sel:[0,0,0] op_sel_hi:[1,0,1] neg_lo:[1,0,0] neg_hi:[1,0,0]
	ds_read_b128 v[84:87], v251 offset:13808
	s_waitcnt lgkmcnt(15)
	v_pk_fma_f32 v[60:61], v[88:89], v[46:47], v[60:61] op_sel:[0,0,0] op_sel_hi:[1,0,1] neg_lo:[1,0,0] neg_hi:[1,0,0]
	v_pk_fma_f32 v[62:63], v[90:91], v[46:47], v[62:63] op_sel:[0,0,0] op_sel_hi:[1,0,1] neg_lo:[1,0,0] neg_hi:[1,0,0]
	ds_read_b128 v[88:91], v251 offset:14016
	v_pk_mul_f32 v[126:127], v[46:47], v[128:129] op_sel:[1,0] op_sel_hi:[1,1]
	s_nop 0
	v_cvt_pk_bf16_f32 v126, v126, v127
	s_nop 0
	ds_write_b16 v205, v126 offset:24176
	ds_write_b16_d16_hi v205, v126 offset:33392
	s_waitcnt lgkmcnt(15)
	v_pk_fma_f32 v[48:49], v[92:93], v[46:47], v[48:49] op_sel:[0,1,0] op_sel_hi:[1,1,1] neg_lo:[1,0,0] neg_hi:[1,0,0]
	v_pk_fma_f32 v[50:51], v[94:95], v[46:47], v[50:51] op_sel:[0,1,0] op_sel_hi:[1,1,1] neg_lo:[1,0,0] neg_hi:[1,0,0]
	ds_read_b128 v[92:95], v251 offset:14032
	s_waitcnt lgkmcnt(15)
	v_pk_fma_f32 v[52:53], v[230:231], v[46:47], v[52:53] op_sel:[0,1,0] op_sel_hi:[1,1,1] neg_lo:[1,0,0] neg_hi:[1,0,0]
	v_pk_fma_f32 v[54:55], v[232:233], v[46:47], v[54:55] op_sel:[0,1,0] op_sel_hi:[1,1,1] neg_lo:[1,0,0] neg_hi:[1,0,0]
	ds_read_b128 v[230:233], v251 offset:14048
	s_waitcnt lgkmcnt(15)
	v_pk_fma_f32 v[56:57], v[234:235], v[46:47], v[56:57] op_sel:[0,1,0] op_sel_hi:[1,1,1] neg_lo:[1,0,0] neg_hi:[1,0,0]
	v_pk_fma_f32 v[58:59], v[236:237], v[46:47], v[58:59] op_sel:[0,1,0] op_sel_hi:[1,1,1] neg_lo:[1,0,0] neg_hi:[1,0,0]
	ds_read_b128 v[234:237], v251 offset:14064
	s_waitcnt lgkmcnt(15)
	v_pk_fma_f32 v[60:61], v[238:239], v[46:47], v[60:61] op_sel:[0,1,0] op_sel_hi:[1,1,1] neg_lo:[1,0,0] neg_hi:[1,0,0]
	v_pk_fma_f32 v[62:63], v[240:241], v[46:47], v[62:63] op_sel:[0,1,0] op_sel_hi:[1,1,1] neg_lo:[1,0,0] neg_hi:[1,0,0]
	ds_read_b128 v[238:241], v251 offset:14288
	v_pk_mul_f32 v[126:127], v[48:49], v[128:129] op_sel:[0,0] op_sel_hi:[0,1]
	s_nop 0
	v_cvt_pk_bf16_f32 v126, v126, v127
	s_nop 0
	ds_write_b16 v205, v126 offset:24320
	ds_write_b16_d16_hi v205, v126 offset:33536
	s_waitcnt lgkmcnt(15)
	v_fma_f32 v49, -v243, v48, v49
	v_pk_fma_f32 v[50:51], v[244:245], v[48:49], v[50:51] op_sel:[0,0,0] op_sel_hi:[1,0,1] neg_lo:[1,0,0] neg_hi:[1,0,0]
	ds_read_b128 v[242:245], v251 offset:14304
	s_waitcnt lgkmcnt(15)
	v_pk_fma_f32 v[52:53], v[246:247], v[48:49], v[52:53] op_sel:[0,0,0] op_sel_hi:[1,0,1] neg_lo:[1,0,0] neg_hi:[1,0,0]
	v_pk_fma_f32 v[54:55], v[248:249], v[48:49], v[54:55] op_sel:[0,0,0] op_sel_hi:[1,0,1] neg_lo:[1,0,0] neg_hi:[1,0,0]
	ds_read_b128 v[246:249], v251 offset:14320
	s_waitcnt lgkmcnt(15)
; #define PG8_LAS __attribute__((address_space(3)))
; __device__ __forceinline__ bf16_t f2bf(float x) { return (bf16_t)(pk2(x, x) & 0xffffu); }
; __device__ __forceinline__ void solve64(float (&x)[64], const PG8_LAS float* sLt) {
;     f32x4 cur[16];
; #pragma unroll
;     for (int i4 = 0; i4 < 16; ++i4) cur[i4] = *(const PG8_LAS f32x4*)(sLt + 4 * i4);
;     asm volatile("" ::: "memory");
; #pragma unroll
;     for (int j = 0; j < 63; ++j) {
;         const float xj = x[j];
; #pragma unroll
;         for (int i4 = (j + 1) / 4; i4 < 16; ++i4) {
;             if (4 * i4 + 0 > j) x[4 * i4 + 0] -= cur[i4][0] * xj;
;             if (4 * i4 + 1 > j) x[4 * i4 + 1] -= cur[i4][1] * xj;
;             if (4 * i4 + 2 > j) x[4 * i4 + 2] -= cur[i4][2] * xj;
;             if (4 * i4 + 3 > j) x[4 * i4 + 3] -= cur[i4][3] * xj;
;             if (j + 1 < 63 && i4 >= (j + 2) / 4) cur[i4] = *(const PG8_LAS f32x4*)(sLt + (j + 1) * 64 + 4 * i4); }
;         asm volatile("" ::: "memory");
;     }
; }
; __device__ __forceinline__ void phase_prep(const Args& a, PG8_LAS unsigned char* lds) {
;     ...
;             const float bj = sB[lane], bej = bj * sE[lane];
; #pragma unroll
;             for (int i = 0; i < 64; ++i) { *(PG8_LAS bf16_t*)(Tu + (i * 72 + lane) * 2) = f2bf(x[i] * bj); *(PG8_LAS bf16_t*)(Tw + (i * 72 + lane) * 2) = f2bf(x[i] * bej); }
	v_pk_fma_f32 v[56:57], v[64:65], v[48:49], v[56:57] op_sel:[0,0,0] op_sel_hi:[1,0,1] neg_lo:[1,0,0] neg_hi:[1,0,0]
	v_pk_fma_f32 v[58:59], v[66:67], v[48:49], v[58:59] op_sel:[0,0,0] op_sel_hi:[1,0,1] neg_lo:[1,0,0] neg_hi:[1,0,0]
	ds_read_b128 v[64:67], v251 offset:14544
	s_waitcnt lgkmcnt(15)
	v_pk_fma_f32 v[60:61], v[68:69], v[48:49], v[60:61] op_sel:[0,0,0] op_sel_hi:[1,0,1] neg_lo:[1,0,0] neg_hi:[1,0,0]
	v_pk_fma_f32 v[62:63], v[70:71], v[48:49], v[62:63] op_sel:[0,0,0] op_sel_hi:[1,0,1] neg_lo:[1,0,0] neg_hi:[1,0,0]
	ds_read_b128 v[68:71], v251 offset:14560
	v_pk_mul_f32 v[126:127], v[48:49], v[128:129] op_sel:[1,0] op_sel_hi:[1,1]
	s_nop 0
	v_cvt_pk_bf16_f32 v126, v126, v127
	s_nop 0
	ds_write_b16 v205, v126 offset:24464
	ds_write_b16_d16_hi v205, v126 offset:33680
	s_waitcnt lgkmcnt(15)
	v_pk_fma_f32 v[50:51], v[74:75], v[48:49], v[50:51] op_sel:[0,1,0] op_sel_hi:[1,1,1] neg_lo:[1,0,0] neg_hi:[1,0,0]
	ds_read_b128 v[72:75], v251 offset:14576
	s_waitcnt lgkmcnt(15)
	v_pk_fma_f32 v[52:53], v[76:77], v[48:49], v[52:53] op_sel:[0,1,0] op_sel_hi:[1,1,1] neg_lo:[1,0,0] neg_hi:[1,0,0]
	v_pk_fma_f32 v[54:55], v[78:79], v[48:49], v[54:55] op_sel:[0,1,0] op_sel_hi:[1,1,1] neg_lo:[1,0,0] neg_hi:[1,0,0]
	ds_read_b128 v[76:79], v251 offset:14800
	s_waitcnt lgkmcnt(15)
	v_pk_fma_f32 v[56:57], v[80:81], v[48:49], v[56:57] op_sel:[0,1,0] op_sel_hi:[1,1,1] neg_lo:[1,0,0] neg_hi:[1,0,0]
	v_pk_fma_f32 v[58:59], v[82:83], v[48:49], v[58:59] op_sel:[0,1,0] op_sel_hi:[1,1,1] neg_lo:[1,0,0] neg_hi:[1,0,0]
	ds_read_b128 v[80:83], v251 offset:14816
	s_waitcnt lgkmcnt(15)
	v_pk_fma_f32 v[60:61], v[84:85], v[48:49], v[60:61] op_sel:[0,1,0] op_sel_hi:[1,1,1] neg_lo:[1,0,0] neg_hi:[1,0,0]
	v_pk_fma_f32 v[62:63], v[86:87], v[48:49], v[62:63] op_sel:[0,1,0] op_sel_hi:[1,1,1] neg_lo:[1,0,0] neg_hi:[1,0,0]
	ds_read_b128 v[84:87], v251 offset:14832
	v_pk_mul_f32 v[126:127], v[50:51], v[128:129] op_sel:[0,0] op_sel_hi:[0,1]
	s_nop 0
	v_cvt_pk_bf16_f32 v126, v126, v127
	s_nop 0
	ds_write_b16 v205, v126 offset:24608
	ds_write_b16_d16_hi v205, v126 offset:33824
	s_waitcnt lgkmcnt(15)
	v_fma_f32 v51, -v91, v50, v51
	ds_read_b128 v[88:91], v251 offset:15056
	s_waitcnt lgkmcnt(15)
	v_pk_fma_f32 v[52:53], v[92:93], v[50:51], v[52:53] op_sel:[0,0,0] op_sel_hi:[1,0,1] neg_lo:[1,0,0] neg_hi:[1,0,0]
	v_pk_fma_f32 v[54:55], v[94:95], v[50:51], v[54:55] op_sel:[0,0,0] op_sel_hi:[1,0,1] neg_lo:[1,0,0] neg_hi:[1,0,0]
	ds_read_b128 v[92:95], v251 offset:15072
	s_waitcnt lgkmcnt(15)
	v_pk_fma_f32 v[56:57], v[230:231], v[50:51], v[56:57] op_sel:[0,0,0] op_sel_hi:[1,0,1] neg_lo:[1,0,0] neg_hi:[1,0,0]
	v_pk_fma_f32 v[58:59], v[232:233], v[50:51], v[58:59] op_sel:[0,0,0] op_sel_hi:[1,0,1] neg_lo:[1,0,0] neg_hi:[1,0,0]
	ds_read_b128 v[230:233], v251 offset:15088
	s_waitcnt lgkmcnt(15)
	v_pk_fma_f32 v[60:61], v[234:235], v[50:51], v[60:61] op_sel:[0,0,0] op_sel_hi:[1,0,1] neg_lo:[1,0,0] neg_hi:[1,0,0]
	v_pk_fma_f32 v[62:63], v[236:237], v[50:51], v[62:63] op_sel:[0,0,0] op_sel_hi:[1,0,1] neg_lo:[1,0,0] neg_hi:[1,0,0]
	ds_read_b128 v[234:237], v251 offset:15328
	v_pk_mul_f32 v[126:127], v[50:51], v[128:129] op_sel:[1,0] op_sel_hi:[1,1]
	s_nop 0
	v_cvt_pk_bf16_f32 v126, v126, v127
	s_nop 0
	ds_write_b16 v205, v126 offset:24752
	ds_write_b16_d16_hi v205, v126 offset:33968
	s_waitcnt lgkmcnt(15)
	v_pk_fma_f32 v[52:53], v[238:239], v[50:51], v[52:53] op_sel:[0,1,0] op_sel_hi:[1,1,1] neg_lo:[1,0,0] neg_hi:[1,0,0]
	v_pk_fma_f32 v[54:55], v[240:241], v[50:51], v[54:55] op_sel:[0,1,0] op_sel_hi:[1,1,1] neg_lo:[1,0,0] neg_hi:[1,0,0]
	ds_read_b128 v[238:241], v251 offset:15344
	s_waitcnt lgkmcnt(15)
	v_pk_fma_f32 v[56:57], v[242:243], v[50:51], v[56:57] op_sel:[0,1,0] op_sel_hi:[1,1,1] neg_lo:[1,0,0] neg_hi:[1,0,0]
	v_pk_fma_f32 v[58:59], v[244:245], v[50:51], v[58:59] op_sel:[0,1,0] op_sel_hi:[1,1,1] neg_lo:[1,0,0] neg_hi:[1,0,0]
	ds_read_b128 v[242:245], v251 offset:15584
	s_waitcnt lgkmcnt(15)
	v_pk_fma_f32 v[60:61], v[246:247], v[50:51], v[60:61] op_sel:[0,1,0] op_sel_hi:[1,1,1] neg_lo:[1,0,0] neg_hi:[1,0,0]
	v_pk_fma_f32 v[62:63], v[248:249], v[50:51], v[62:63] op_sel:[0,1,0] op_sel_hi:[1,1,1] neg_lo:[1,0,0] neg_hi:[1,0,0]
	ds_read_b128 v[246:249], v251 offset:15600
	v_pk_mul_f32 v[126:127], v[52:53], v[128:129] op_sel:[0,0] op_sel_hi:[0,1]
	s_nop 0
	v_cvt_pk_bf16_f32 v126, v126, v127
	s_nop 0
	ds_write_b16 v205, v126 offset:24896
	ds_write_b16_d16_hi v205, v126 offset:34112
	s_waitcnt lgkmcnt(15)
	v_fma_f32 v53, -v65, v52, v53
	v_pk_fma_f32 v[54:55], v[66:67], v[52:53], v[54:55] op_sel:[0,0,0] op_sel_hi:[1,0,1] neg_lo:[1,0,0] neg_hi:[1,0,0]
	ds_read_b128 v[64:67], v251 offset:15840
	s_waitcnt lgkmcnt(15)
	v_pk_fma_f32 v[56:57], v[68:69], v[52:53], v[56:57] op_sel:[0,0,0] op_sel_hi:[1,0,1] neg_lo:[1,0,0] neg_hi:[1,0,0]
	v_pk_fma_f32 v[58:59], v[70:71], v[52:53], v[58:59] op_sel:[0,0,0] op_sel_hi:[1,0,1] neg_lo:[1,0,0] neg_hi:[1,0,0]
	ds_read_b128 v[68:71], v251 offset:15856
	s_waitcnt lgkmcnt(15)
	v_pk_fma_f32 v[60:61], v[72:73], v[52:53], v[60:61] op_sel:[0,0,0] op_sel_hi:[1,0,1] neg_lo:[1,0,0] neg_hi:[1,0,0]
	v_pk_fma_f32 v[62:63], v[74:75], v[52:53], v[62:63] op_sel:[0,0,0] op_sel_hi:[1,0,1] neg_lo:[1,0,0] neg_hi:[1,0,0]
	ds_read_b128 v[72:75], v251 offset:16096
	v_pk_mul_f32 v[126:127], v[52:53], v[128:129] op_sel:[1,0] op_sel_hi:[1,1]
	s_nop 0
	v_cvt_pk_bf16_f32 v126, v126, v127
	s_nop 0
	ds_write_b16 v205, v126 offset:25040
	ds_write_b16_d16_hi v205, v126 offset:34256
	s_waitcnt lgkmcnt(15)
	v_pk_fma_f32 v[54:55], v[78:79], v[52:53], v[54:55] op_sel:[0,1,0] op_sel_hi:[1,1,1] neg_lo:[1,0,0] neg_hi:[1,0,0]
	ds_read_b128 v[76:79], v251 offset:16112
	s_waitcnt lgkmcnt(15)
; #define PG8_LAS __attribute__((address_space(3)))
; __device__ __forceinline__ bf16_t f2bf(float x) { return (bf16_t)(pk2(x, x) & 0xffffu); }
; __device__ __forceinline__ void solve64(float (&x)[64], const PG8_LAS float* sLt) {
;     ...
; #pragma unroll
;     for (int j = 0; j < 63; ++j) {
;         const float xj = x[j];
; #pragma unroll
;         for (int i4 = (j + 1) / 4; i4 < 16; ++i4) {
;             if (4 * i4 + 0 > j) x[4 * i4 + 0] -= cur[i4][0] * xj;
;             if (4 * i4 + 1 > j) x[4 * i4 + 1] -= cur[i4][1] * xj;
;             if (4 * i4 + 2 > j) x[4 * i4 + 2] -= cur[i4][2] * xj;
;             if (4 * i4 + 3 > j) x[4 * i4 + 3] -= cur[i4][3] * xj;
;             if (j + 1 < 63 && i4 >= (j + 2) / 4) cur[i4] = *(const PG8_LAS f32x4*)(sLt + (j + 1) * 64 + 4 * i4); }
;         asm volatile("" ::: "memory");
;     }
; }
; __device__ __forceinline__ void phase_prep(const Args& a, PG8_LAS unsigned char* lds) {
;     ...
;             const float bj = sB[lane], bej = bj * sE[lane];
; #pragma unroll
;             for (int i = 0; i < 64; ++i) { *(PG8_LAS bf16_t*)(Tu + (i * 72 + lane) * 2) = f2bf(x[i] * bj); *(PG8_LAS bf16_t*)(Tw + (i * 72 + lane) * 2) = f2bf(x[i] * bej); }
	v_pk_fma_f32 v[56:57], v[80:81], v[52:53], v[56:57] op_sel:[0,1,0] op_sel_hi:[1,1,1] neg_lo:[1,0,0] neg_hi:[1,0,0]
	v_pk_fma_f32 v[58:59], v[82:83], v[52:53], v[58:59] op_sel:[0,1,0] op_sel_hi:[1,1,1] neg_lo:[1,0,0] neg_hi:[1,0,0]
	ds_read_b128 v[80:83], v251 offset:16368
	s_waitcnt lgkmcnt(15)
	v_pk_fma_f32 v[60:61], v[84:85], v[52:53], v[60:61] op_sel:[0,1,0] op_sel_hi:[1,1,1] neg_lo:[1,0,0] neg_hi:[1,0,0]
	v_pk_fma_f32 v[62:63], v[86:87], v[52:53], v[62:63] op_sel:[0,1,0] op_sel_hi:[1,1,1] neg_lo:[1,0,0] neg_hi:[1,0,0]
	ds_read_b128 v[84:87], v251 offset:16624
	v_pk_mul_f32 v[126:127], v[54:55], v[128:129] op_sel:[0,0] op_sel_hi:[0,1]
	s_nop 0
	v_cvt_pk_bf16_f32 v126, v126, v127
	s_nop 0
	ds_write_b16 v205, v126 offset:25184
	ds_write_b16_d16_hi v205, v126 offset:34400
	s_waitcnt lgkmcnt(15)
	v_fma_f32 v55, -v91, v54, v55
	ds_read_b128 v[88:91], v251 offset:16880
	s_waitcnt lgkmcnt(15)
	v_pk_fma_f32 v[56:57], v[92:93], v[54:55], v[56:57] op_sel:[0,0,0] op_sel_hi:[1,0,1] neg_lo:[1,0,0] neg_hi:[1,0,0]
	v_pk_fma_f32 v[58:59], v[94:95], v[54:55], v[58:59] op_sel:[0,0,0] op_sel_hi:[1,0,1] neg_lo:[1,0,0] neg_hi:[1,0,0]
	ds_read_b128 v[92:95], v251 offset:17136
	s_waitcnt lgkmcnt(15)
	v_pk_fma_f32 v[60:61], v[230:231], v[54:55], v[60:61] op_sel:[0,0,0] op_sel_hi:[1,0,1] neg_lo:[1,0,0] neg_hi:[1,0,0]
	v_pk_fma_f32 v[62:63], v[232:233], v[54:55], v[62:63] op_sel:[0,0,0] op_sel_hi:[1,0,1] neg_lo:[1,0,0] neg_hi:[1,0,0]
	v_pk_mul_f32 v[126:127], v[54:55], v[128:129] op_sel:[1,0] op_sel_hi:[1,1]
	s_nop 0
	v_cvt_pk_bf16_f32 v126, v126, v127
	s_nop 0
	ds_write_b16 v205, v126 offset:25328
	ds_write_b16_d16_hi v205, v126 offset:34544
	s_waitcnt lgkmcnt(15)
	v_pk_fma_f32 v[56:57], v[234:235], v[54:55], v[56:57] op_sel:[0,1,0] op_sel_hi:[1,1,1] neg_lo:[1,0,0] neg_hi:[1,0,0]
	v_pk_fma_f32 v[58:59], v[236:237], v[54:55], v[58:59] op_sel:[0,1,0] op_sel_hi:[1,1,1] neg_lo:[1,0,0] neg_hi:[1,0,0]
	s_waitcnt lgkmcnt(15)
	v_pk_fma_f32 v[60:61], v[238:239], v[54:55], v[60:61] op_sel:[0,1,0] op_sel_hi:[1,1,1] neg_lo:[1,0,0] neg_hi:[1,0,0]
	v_pk_fma_f32 v[62:63], v[240:241], v[54:55], v[62:63] op_sel:[0,1,0] op_sel_hi:[1,1,1] neg_lo:[1,0,0] neg_hi:[1,0,0]
	v_pk_mul_f32 v[126:127], v[56:57], v[128:129] op_sel:[0,0] op_sel_hi:[0,1]
	s_nop 0
	v_cvt_pk_bf16_f32 v126, v126, v127
	s_nop 0
	ds_write_b16 v205, v126 offset:25472
	ds_write_b16_d16_hi v205, v126 offset:34688
	s_waitcnt lgkmcnt(15)
	v_fma_f32 v57, -v243, v56, v57
	v_pk_fma_f32 v[58:59], v[244:245], v[56:57], v[58:59] op_sel:[0,0,0] op_sel_hi:[1,0,1] neg_lo:[1,0,0] neg_hi:[1,0,0]
	s_waitcnt lgkmcnt(15)
	v_pk_fma_f32 v[60:61], v[246:247], v[56:57], v[60:61] op_sel:[0,0,0] op_sel_hi:[1,0,1] neg_lo:[1,0,0] neg_hi:[1,0,0]
	v_pk_fma_f32 v[62:63], v[248:249], v[56:57], v[62:63] op_sel:[0,0,0] op_sel_hi:[1,0,1] neg_lo:[1,0,0] neg_hi:[1,0,0]
	v_pk_mul_f32 v[126:127], v[56:57], v[128:129] op_sel:[1,0] op_sel_hi:[1,1]
	s_nop 0
	v_cvt_pk_bf16_f32 v126, v126, v127
	s_nop 0
	ds_write_b16 v205, v126 offset:25616
	ds_write_b16_d16_hi v205, v126 offset:34832
	s_waitcnt lgkmcnt(15)
	v_pk_fma_f32 v[58:59], v[66:67], v[56:57], v[58:59] op_sel:[0,1,0] op_sel_hi:[1,1,1] neg_lo:[1,0,0] neg_hi:[1,0,0]
	s_waitcnt lgkmcnt(15)
	v_pk_fma_f32 v[60:61], v[68:69], v[56:57], v[60:61] op_sel:[0,1,0] op_sel_hi:[1,1,1] neg_lo:[1,0,0] neg_hi:[1,0,0]
	v_pk_fma_f32 v[62:63], v[70:71], v[56:57], v[62:63] op_sel:[0,1,0] op_sel_hi:[1,1,1] neg_lo:[1,0,0] neg_hi:[1,0,0]
	v_pk_mul_f32 v[126:127], v[58:59], v[128:129] op_sel:[0,0] op_sel_hi:[0,1]
	s_nop 0
	v_cvt_pk_bf16_f32 v126, v126, v127
	s_nop 0
	ds_write_b16 v205, v126 offset:25760
	ds_write_b16_d16_hi v205, v126 offset:34976
	s_waitcnt lgkmcnt(15)
	v_fma_f32 v59, -v75, v58, v59
	s_waitcnt lgkmcnt(14)
	v_pk_fma_f32 v[60:61], v[76:77], v[58:59], v[60:61] op_sel:[0,0,0] op_sel_hi:[1,0,1] neg_lo:[1,0,0] neg_hi:[1,0,0]
	v_pk_fma_f32 v[62:63], v[78:79], v[58:59], v[62:63] op_sel:[0,0,0] op_sel_hi:[1,0,1] neg_lo:[1,0,0] neg_hi:[1,0,0]
	v_pk_mul_f32 v[126:127], v[58:59], v[128:129] op_sel:[1,0] op_sel_hi:[1,1]
	s_nop 0
	v_cvt_pk_bf16_f32 v126, v126, v127
	s_nop 0
	ds_write_b16 v205, v126 offset:25904
	ds_write_b16_d16_hi v205, v126 offset:35120
	s_waitcnt lgkmcnt(15)
	v_pk_fma_f32 v[60:61], v[80:81], v[58:59], v[60:61] op_sel:[0,1,0] op_sel_hi:[1,1,1] neg_lo:[1,0,0] neg_hi:[1,0,0]
	v_pk_fma_f32 v[62:63], v[82:83], v[58:59], v[62:63] op_sel:[0,1,0] op_sel_hi:[1,1,1] neg_lo:[1,0,0] neg_hi:[1,0,0]
	v_pk_mul_f32 v[126:127], v[60:61], v[128:129] op_sel:[0,0] op_sel_hi:[0,1]
	s_nop 0
	v_cvt_pk_bf16_f32 v126, v126, v127
	s_nop 0
	ds_write_b16 v205, v126 offset:26048
	ds_write_b16_d16_hi v205, v126 offset:35264
	s_waitcnt lgkmcnt(15)
	v_fma_f32 v61, -v85, v60, v61
	v_pk_fma_f32 v[62:63], v[86:87], v[60:61], v[62:63] op_sel:[0,0,0] op_sel_hi:[1,0,1] neg_lo:[1,0,0] neg_hi:[1,0,0]
	v_pk_mul_f32 v[126:127], v[60:61], v[128:129] op_sel:[1,0] op_sel_hi:[1,1]
	s_nop 0
	v_cvt_pk_bf16_f32 v126, v126, v127
	s_nop 0
	ds_write_b16 v205, v126 offset:26192
	ds_write_b16_d16_hi v205, v126 offset:35408
	s_waitcnt lgkmcnt(15)
	v_pk_fma_f32 v[62:63], v[90:91], v[60:61], v[62:63] op_sel:[0,1,0] op_sel_hi:[1,1,1] neg_lo:[1,0,0] neg_hi:[1,0,0]
	v_pk_mul_f32 v[126:127], v[62:63], v[128:129] op_sel:[0,0] op_sel_hi:[0,1]
	s_nop 0
	v_cvt_pk_bf16_f32 v126, v126, v127
	s_nop 0
	ds_write_b16 v205, v126 offset:26336
	ds_write_b16_d16_hi v205, v126 offset:35552
	s_waitcnt lgkmcnt(15)
	v_fma_f32 v63, -v95, v62, v63
	v_pk_mul_f32 v[126:127], v[62:63], v[128:129] op_sel:[1,0] op_sel_hi:[1,1]
	s_nop 0
	v_cvt_pk_bf16_f32 v126, v126, v127
	s_nop 0
	ds_write_b16 v205, v126 offset:26480
	ds_write_b16_d16_hi v205, v126 offset:35696
	s_setprio 0
	s_branch .LBB0_252
